# GEMM K-loops: per-K-tile LDS fragment base address adds hoisted into spare VGPRs (10 of 11 loops); on top of v37
# baseline (speedup 1.0000x reference)
; #define PG8_STAGE(bufoff, gbase, voff) do { _Pragma("unroll") for (int _i = 0; _i < 2; ++_i) \
;         asm volatile("s_mov_b32 m0, %0\n\ts_nop 0\n\tglobal_load_lds_dwordx4 %1, %2" :: "s"(ldsb + (unsigned)((bufoff) + _i * 8192)), "v"((voff)[_i]), "s"(gbase) : "m0", "memory"); } while (0)
; #define PG8_WAIT_V(n) asm volatile("s_waitcnt vmcnt(" #n ")" ::: "memory")
; #define PG8_BAR __builtin_amdgcn_s_barrier()
; template <class Epi, class Sched, bool ALIGN_EPI = false, bool SP2 = false>
; __device__ __forceinline__ void gemm_phase(PG8_LAS unsigned char* lds, const Gemm g, const Sched& S, const Epi& E, const int wv) {
;     ...
;     for (int i = 0; i < 2; ++i) { int R, C; stage_rc(tid * 16 + i * 8192, R, C); const int Rb = Epi::PERM ? ((R & ~31) + perm32(R & 31)) : R;
;         voffA[i] = (unsigned)(R * K + C) * 2u; voffB[i] = (unsigned)(Rb * Kb + C) * 2u; }
;     const size_t kstep = (size_t)(BK * 2);
;     const size_t hstepA = (size_t)HALF * K * 2, hstepB = (size_t)HALF * Kb * 2;
;     const size_t tstepA = 2 * hstepA, tstepB = 2 * hstepB;
;     const unsigned ldsw = (unsigned)wid * 1024u;
;     const unsigned ldsb = (unsigned)(size_t)lds + ldsw;
;     const int aoff = lds_byte(wr * 64 + fr, fq * 8), boff = lds_byte(wc * 32 + fr, fq * 8);
;     ...
;     if constexpr (SP2) {
;         PG8_STAGE(PG8_SB(0, 0), cB, voffB); PG8_STAGE(PG8_SB(0, 1), cB + hstepB, voffB); PG8_STAGE(PG8_SA(0, 0), cA, voffA); PG8_STAGE(PG8_SA(0, 1), cA + hstepA, voffA);
;         if (wr == 1) PG8_BAR;
;         PG8_WAIT_V(2); PG8_BAR;
;         PG8_STAGE(PG8_SB(1, 0), cB + kstep, voffB); PG8_STAGE(PG8_SA(1, 0), cA + kstep, voffA); PG8_STAGE(PG8_SB(1, 1), cB + hstepB + kstep, voffB);
;         PG8_WAIT_V(6); PG8_BAR;
.LBB0_259:
	s_bfe_u32 s40, s6, 0x80010
	s_add_u32 s6, s10, 0xd26f000
	s_addc_u32 s7, s11, 0
	v_readlane_b32 s14, v254, 54
	s_add_u32 s8, s10, 0x43e000
	v_readlane_b32 s15, v254, 55
	s_addc_u32 s9, s11, 0
	s_lshl_b64 s[14:15], s[14:15], 2
	s_add_u32 s2, s10, s14
	s_addc_u32 s10, s11, s15
	v_bfe_u32 v1, v0, 4, 2
	s_add_u32 s37, s2, 0xd4000
	v_and_b32_e32 v155, 15, v0
	v_lshlrev_b32_e32 v2, 3, v1
	v_lshlrev_b32_e32 v1, 4, v1
	v_lshlrev_b32_e32 v3, 2, v0
	s_addc_u32 s42, s10, 0
	v_lshl_or_b32 v1, v155, 6, v1
	s_lshl_b32 s2, s13, 13
	v_and_b32_e32 v3, 32, v3
	v_bitop3_b32 v4, v1, s2, v3 bitop3:0xde
	s_lshl_b32 s2, s12, 5
	s_and_b32 s44, s2, 0x60
	s_lshl_b32 s43, s13, 6
	s_lshl_b32 s2, s44, 7
	s_add_i32 s45, s28, 0x18000
	s_add_u32 s10, s18, 0x80
	s_waitcnt vmcnt(2)
	s_barrier
	s_addc_u32 s11, s19, 0
	s_mov_b32 m0, s45
	s_nop 0
	global_load_lds_dwordx4 v149, s[10:11]
	s_add_i32 s46, s28, 0x1a000
	s_add_i32 s47, s28, 0x8000
	s_mov_b32 m0, s46
	s_nop 0
	global_load_lds_dwordx4 v153, s[10:11]
	s_add_u32 s10, s20, 0x80
	s_addc_u32 s11, s21, 0
	s_mov_b32 m0, s47
	s_nop 0
	global_load_lds_dwordx4 v147, s[10:11]
	s_add_i32 s48, s28, 0xa000
	s_add_i32 s49, s28, 0x1c000
	s_mov_b32 m0, s48
	s_nop 0
	global_load_lds_dwordx4 v151, s[10:11]
	s_add_u32 s10, s18, 0x80080
	s_addc_u32 s11, s19, 0
	s_mov_b32 m0, s49
	s_nop 0
	global_load_lds_dwordx4 v149, s[10:11]
	s_add_i32 s50, s28, 0x1e000
	s_mov_b32 m0, s50
	s_nop 0
	global_load_lds_dwordx4 v153, s[10:11]
	v_bitop3_b32 v1, v1, s2, v3 bitop3:0xde
	s_waitcnt vmcnt(6)
	s_add_i32 s51, s28, 0xc000
	v_and_b32_e32 v3, 3, v0
	v_bfe_u32 v157, v0, 2, 4
	v_and_b32_e32 v0, 60, v0
	s_cmp_lt_u32 s12, 4
	v_lshl_or_b32 v159, v3, 6, v0
	v_lshlrev_b32_e32 v0, 3, v3
	v_add_u32_e32 v160, 0, v1
	v_add_u32_e32 v253, 0x18000, v160
	v_add_u32_e32 v252, 0x1c000, v160
	s_cselect_b64 s[10:11], -1, 0
	s_add_i32 s52, s28, 0xe000
	s_ashr_i32 s53, s70, 31
	s_mov_b32 s54, 0
	v_add_u32_e32 v161, 0x10000, v160
	v_add_u32_e32 v162, 0x14000, v160
	v_add_u32_e32 v163, 0, v4
	v_lshlrev_b32_e32 v192, 1, v0
	v_lshlrev_b32_e32 v164, 2, v2
	s_barrier
	s_branch .LBB0_262

; #define PG8_STAGE(bufoff, gbase, voff) do { _Pragma("unroll") for (int _i = 0; _i < 2; ++_i) \
;         asm volatile("s_mov_b32 m0, %0\n\ts_nop 0\n\tglobal_load_lds_dwordx4 %1, %2" :: "s"(ldsb + (unsigned)((bufoff) + _i * 8192)), "v"((voff)[_i]), "s"(gbase) : "m0", "memory"); } while (0)
; #define PG8_LDA(dst, b, h) do { _Pragma("unroll") for (int m = 0; m < 4; ++m) _Pragma("unroll") for (int k = 0; k < 2; ++k) dst[m][k] = *(const PG8_LAS bf16x8*)(lds + PG8_SA(b, h) + aoff + m * 2048 + k * 1024); } while (0)
; #define PG8_LDB(dst, b, h) do { _Pragma("unroll") for (int n = 0; n < 2; ++n) _Pragma("unroll") for (int k = 0; k < 2; ++k) dst[n][k] = *(const PG8_LAS bf16x8*)(lds + PG8_SB(b, h) + boff + n * 2048 + k * 1024); } while (0)
; #define PG8_WAIT_V(n) asm volatile("s_waitcnt vmcnt(" #n ")" ::: "memory")
; #define PG8_BAR __builtin_amdgcn_s_barrier()
; template <class Epi, class Sched, bool ALIGN_EPI = false, bool SP2 = false>
; __device__ __forceinline__ void gemm_phase(PG8_LAS unsigned char* lds, const Gemm g, const Sched& S, const Epi& E, const int wv) {
;     ...
;         nxt = cur; bool has_next; PG8_NEXT(ui + 1, nxt, has_next);
;         const char* nA = has_next ? (const char*)g.A + (size_t)nxt.pm * tstepA + (size_t)nxt.ko * 2 : cA; const char* nB = has_next ? (const char*)g.Bt + (size_t)nxt.pn * tstepB + (size_t)nxt.ko * 2 : cB;
;         const int nt = __builtin_amdgcn_readfirstlane(cur.nk);
;         for (int t = 0; t < nt; t += 2) {
;             const bool last = (t == nt - 2);
;             const char* a1 = cA + (size_t)(t + 1) * kstep;
;             const char* a2 = last ? nA : cA + (size_t)(t + 2) * kstep; const char* b2 = last ? nB : cB + (size_t)(t + 2) * kstep;
;             const char* a3 = a2 + kstep; const char* b3 = b2 + kstep;
;             if (last && has_next) S.a_ready(nxt);
;             if constexpr (SP2) {
;             PG8_LDB(B0, 0, 0); PG8_LDB(B1, 0, 1); PG8_SCHED; PG8_LDA(At, 0, 0); PG8_STAGE(PG8_SA(1, 1), a1 + hstepA, voffA);
;             PG8_WAIT_V(8); PG8_WAIT_L(0); PG8_BAR; PG8_MMA(0, 0, At, B0); PG8_MMA(0, 1, At, B1); PG8_BAR; PG8_SCHED;
;             PG8_LDA(At, 0, 1); PG8_STAGE(PG8_SB(0, 0), b2, voffB); PG8_STAGE(PG8_SB(0, 1), b2 + hstepB, voffB); PG8_STAGE(PG8_SA(0, 0), a2, voffA);
;             PG8_WAIT_V(8); PG8_WAIT_L(0); PG8_BAR; PG8_MMA(1, 0, At, B0); PG8_MMA(1, 1, At, B1); PG8_BAR; PG8_SCHED;
.LBB0_268:
	ds_read_b128 v[80:83], v161
	ds_read_b128 v[84:87], v161 offset:1024
	ds_read_b128 v[88:91], v161 offset:2048
	ds_read_b128 v[92:95], v161 offset:3072
	ds_read_b128 v[166:169], v162
	ds_read_b128 v[170:173], v162 offset:1024
	ds_read_b128 v[174:177], v162 offset:2048
	ds_read_b128 v[178:181], v162 offset:3072
	s_add_i32 s84, s18, 2
	s_cmp_eq_u32 s71, s18
	s_cselect_b32 s22, s12, s72
	s_cselect_b32 s23, s13, s77
	s_cselect_b32 s20, s65, s79
	s_cselect_b32 s21, s62, s83
	s_add_u32 s18, s22, 0x80
	s_addc_u32 s19, s23, 0
	ds_read_b128 v[182:185], v163
	ds_read_b128 v[186:189], v163 offset:1024
	ds_read_b128 v[194:197], v163 offset:2048
	ds_read_b128 v[198:201], v163 offset:3072
	ds_read_b128 v[202:205], v163 offset:4096
	ds_read_b128 v[206:209], v163 offset:5120
	ds_read_b128 v[210:213], v163 offset:6144
	ds_read_b128 v[214:217], v163 offset:7168
	s_add_u32 s86, s72, 0x83f80
	s_addc_u32 s87, s77, 0
	s_mov_b32 m0, s51
	s_nop 0
	global_load_lds_dwordx4 v147, s[86:87]
	s_nop 0
	s_mov_b32 m0, s52
	s_nop 0
	global_load_lds_dwordx4 v151, s[86:87]
	s_waitcnt vmcnt(8) lgkmcnt(0)
	s_setprio 1
	s_barrier
	v_mfma_f32_16x16x32_bf16 v[140:143], v[80:83], v[182:185], v[140:143]
	v_mfma_f32_16x16x32_bf16 v[136:139], v[88:91], v[182:185], v[136:139]
	v_mfma_f32_16x16x32_bf16 v[124:127], v[80:83], v[194:197], v[124:127]
	v_mfma_f32_16x16x32_bf16 v[120:123], v[88:91], v[194:197], v[120:123]
	v_mfma_f32_16x16x32_bf16 v[108:111], v[80:83], v[202:205], v[108:111]
	v_mfma_f32_16x16x32_bf16 v[104:107], v[88:91], v[202:205], v[104:107]
	v_mfma_f32_16x16x32_bf16 v[76:79], v[80:83], v[210:213], v[76:79]
	v_mfma_f32_16x16x32_bf16 v[72:75], v[88:91], v[210:213], v[72:75]
	v_mfma_f32_16x16x32_bf16 v[140:143], v[84:87], v[186:189], v[140:143]
	v_mfma_f32_16x16x32_bf16 v[136:139], v[92:95], v[186:189], v[136:139]
	v_mfma_f32_16x16x32_bf16 v[124:127], v[84:87], v[198:201], v[124:127]
	v_mfma_f32_16x16x32_bf16 v[120:123], v[92:95], v[198:201], v[120:123]
	v_mfma_f32_16x16x32_bf16 v[108:111], v[84:87], v[206:209], v[108:111]
	v_mfma_f32_16x16x32_bf16 v[104:107], v[92:95], v[206:209], v[104:107]
	v_mfma_f32_16x16x32_bf16 v[76:79], v[84:87], v[214:217], v[76:79]
	v_mfma_f32_16x16x32_bf16 v[72:75], v[92:95], v[214:217], v[72:75]
	v_mfma_f32_16x16x32_bf16 v[132:135], v[166:169], v[182:185], v[132:135]
	v_mfma_f32_16x16x32_bf16 v[128:131], v[174:177], v[182:185], v[128:131]
	v_mfma_f32_16x16x32_bf16 v[116:119], v[166:169], v[194:197], v[116:119]
	v_mfma_f32_16x16x32_bf16 v[112:115], v[174:177], v[194:197], v[112:115]
	v_mfma_f32_16x16x32_bf16 v[100:103], v[166:169], v[202:205], v[100:103]
	v_mfma_f32_16x16x32_bf16 v[96:99], v[174:177], v[202:205], v[96:99]
	v_mfma_f32_16x16x32_bf16 v[68:71], v[166:169], v[210:213], v[68:71]
	v_mfma_f32_16x16x32_bf16 v[64:67], v[174:177], v[210:213], v[64:67]
	v_mfma_f32_16x16x32_bf16 v[132:135], v[170:173], v[186:189], v[132:135]
	v_mfma_f32_16x16x32_bf16 v[128:131], v[178:181], v[186:189], v[128:131]
	v_mfma_f32_16x16x32_bf16 v[116:119], v[170:173], v[198:201], v[116:119]
	v_mfma_f32_16x16x32_bf16 v[112:115], v[178:181], v[198:201], v[112:115]
	v_mfma_f32_16x16x32_bf16 v[100:103], v[170:173], v[206:209], v[100:103]
	v_mfma_f32_16x16x32_bf16 v[96:99], v[178:181], v[206:209], v[96:99]
	v_mfma_f32_16x16x32_bf16 v[68:71], v[170:173], v[214:217], v[68:71]
	v_mfma_f32_16x16x32_bf16 v[64:67], v[178:181], v[214:217], v[64:67]
	s_setprio 0
	s_barrier
	ds_read_b128 v[182:185], v163 offset:16384
	ds_read_b128 v[186:189], v163 offset:17408
	ds_read_b128 v[194:197], v163 offset:18432
	ds_read_b128 v[198:201], v163 offset:19456
	ds_read_b128 v[202:205], v163 offset:20480
	ds_read_b128 v[206:209], v163 offset:21504
	ds_read_b128 v[210:213], v163 offset:22528
	ds_read_b128 v[214:217], v163 offset:23552
	s_mov_b32 m0, s29
	s_nop 0
	global_load_lds_dwordx4 v149, s[20:21]
	s_add_u32 s86, s20, 0x80000
	s_mov_b32 m0, s30
	s_nop 0
	global_load_lds_dwordx4 v153, s[20:21]
	s_addc_u32 s87, s21, 0
	s_mov_b32 m0, s31
	s_nop 0
	global_load_lds_dwordx4 v149, s[86:87]
	s_nop 0
	s_mov_b32 m0, s33
	s_nop 0
	global_load_lds_dwordx4 v153, s[86:87]
	s_nop 0
	s_mov_b32 m0, s28
	s_nop 0
	global_load_lds_dwordx4 v147, s[22:23]
	s_nop 0
	s_mov_b32 m0, s34
	s_nop 0
	global_load_lds_dwordx4 v151, s[22:23]
	s_waitcnt vmcnt(8) lgkmcnt(0)
	s_setprio 1
	s_barrier
	v_mfma_f32_16x16x32_bf16 v[60:63], v[80:83], v[182:185], v[60:63]
	v_mfma_f32_16x16x32_bf16 v[56:59], v[88:91], v[182:185], v[56:59]
	v_mfma_f32_16x16x32_bf16 v[44:47], v[80:83], v[194:197], v[44:47]
	v_mfma_f32_16x16x32_bf16 v[40:43], v[88:91], v[194:197], v[40:43]
	v_mfma_f32_16x16x32_bf16 v[28:31], v[80:83], v[202:205], v[28:31]
	v_mfma_f32_16x16x32_bf16 v[24:27], v[88:91], v[202:205], v[24:27]
	v_mfma_f32_16x16x32_bf16 v[12:15], v[80:83], v[210:213], v[12:15]
	v_mfma_f32_16x16x32_bf16 v[8:11], v[88:91], v[210:213], v[8:11]
	v_mfma_f32_16x16x32_bf16 v[60:63], v[84:87], v[186:189], v[60:63]
	v_mfma_f32_16x16x32_bf16 v[56:59], v[92:95], v[186:189], v[56:59]
	v_mfma_f32_16x16x32_bf16 v[44:47], v[84:87], v[198:201], v[44:47]
	v_mfma_f32_16x16x32_bf16 v[40:43], v[92:95], v[198:201], v[40:43]
	v_mfma_f32_16x16x32_bf16 v[28:31], v[84:87], v[206:209], v[28:31]
	v_mfma_f32_16x16x32_bf16 v[24:27], v[92:95], v[206:209], v[24:27]
	v_mfma_f32_16x16x32_bf16 v[12:15], v[84:87], v[214:217], v[12:15]
	v_mfma_f32_16x16x32_bf16 v[8:11], v[92:95], v[214:217], v[8:11]
	v_mfma_f32_16x16x32_bf16 v[52:55], v[166:169], v[182:185], v[52:55]
	v_mfma_f32_16x16x32_bf16 v[48:51], v[174:177], v[182:185], v[48:51]
	v_mfma_f32_16x16x32_bf16 v[36:39], v[166:169], v[194:197], v[36:39]
	v_mfma_f32_16x16x32_bf16 v[32:35], v[174:177], v[194:197], v[32:35]
	v_mfma_f32_16x16x32_bf16 v[20:23], v[166:169], v[202:205], v[20:23]
	v_mfma_f32_16x16x32_bf16 v[16:19], v[174:177], v[202:205], v[16:19]
	v_mfma_f32_16x16x32_bf16 v[4:7], v[166:169], v[210:213], v[4:7]
	v_mfma_f32_16x16x32_bf16 v[0:3], v[174:177], v[210:213], v[0:3]
	v_mfma_f32_16x16x32_bf16 v[52:55], v[170:173], v[186:189], v[52:55]
	v_mfma_f32_16x16x32_bf16 v[48:51], v[178:181], v[186:189], v[48:51]
	v_mfma_f32_16x16x32_bf16 v[36:39], v[170:173], v[198:201], v[36:39]
	v_mfma_f32_16x16x32_bf16 v[32:35], v[178:181], v[198:201], v[32:35]
	v_mfma_f32_16x16x32_bf16 v[20:23], v[170:173], v[206:209], v[20:23]
	v_mfma_f32_16x16x32_bf16 v[16:19], v[178:181], v[206:209], v[16:19]
	v_mfma_f32_16x16x32_bf16 v[4:7], v[170:173], v[214:217], v[4:7]
	v_mfma_f32_16x16x32_bf16 v[0:3], v[178:181], v[214:217], v[0:3]
	s_setprio 0
	s_barrier
; #define PG8_STAGE(bufoff, gbase, voff) do { _Pragma("unroll") for (int _i = 0; _i < 2; ++_i) \
;         asm volatile("s_mov_b32 m0, %0\n\ts_nop 0\n\tglobal_load_lds_dwordx4 %1, %2" :: "s"(ldsb + (unsigned)((bufoff) + _i * 8192)), "v"((voff)[_i]), "s"(gbase) : "m0", "memory"); } while (0)
; #define PG8_LDA(dst, b, h) do { _Pragma("unroll") for (int m = 0; m < 4; ++m) _Pragma("unroll") for (int k = 0; k < 2; ++k) dst[m][k] = *(const PG8_LAS bf16x8*)(lds + PG8_SA(b, h) + aoff + m * 2048 + k * 1024); } while (0)
; #define PG8_LDB(dst, b, h) do { _Pragma("unroll") for (int n = 0; n < 2; ++n) _Pragma("unroll") for (int k = 0; k < 2; ++k) dst[n][k] = *(const PG8_LAS bf16x8*)(lds + PG8_SB(b, h) + boff + n * 2048 + k * 1024); } while (0)
; #define PG8_MMA(ai, bj, At, Bt) do { __builtin_amdgcn_s_setprio(1); _Pragma("unroll") for (int m = 0; m < 4; ++m) _Pragma("unroll") for (int n = 0; n < 2; ++n) _Pragma("unroll") for (int k = 0; k < 2; ++k) \
;         acc[ai][bj][m][n] = __builtin_amdgcn_mfma_f32_16x16x32_bf16(Bt[n][k], At[m][k], acc[ai][bj][m][n], 0, 0, 0); __builtin_amdgcn_s_setprio(0); } while (0)
; #define PG8_WAIT_V(n) asm volatile("s_waitcnt vmcnt(" #n ")" ::: "memory")
; #define PG8_WAIT_L(n) asm volatile("s_waitcnt lgkmcnt(" #n ")" ::: "memory")
; #define PG8_BAR __builtin_amdgcn_s_barrier()
; template <class Epi, class Sched, bool ALIGN_EPI = false, bool SP2 = false>
; __device__ __forceinline__ void gemm_phase(PG8_LAS unsigned char* lds, const Gemm g, const Sched& S, const Epi& E, const int wv) {
;     ...
;         for (int t = 0; t < nt; t += 2) {
;             const bool last = (t == nt - 2);
;             const char* a1 = cA + (size_t)(t + 1) * kstep;
;             const char* a2 = last ? nA : cA + (size_t)(t + 2) * kstep; const char* b2 = last ? nB : cB + (size_t)(t + 2) * kstep;
;             const char* a3 = a2 + kstep; const char* b3 = b2 + kstep;
;     ...
;             PG8_LDB(B0, 1, 0); PG8_LDB(B1, 1, 1); PG8_SCHED; PG8_LDA(At, 1, 0); PG8_STAGE(PG8_SA(0, 1), a2 + hstepA, voffA);
;             PG8_WAIT_V(8); PG8_WAIT_L(0); PG8_BAR; PG8_MMA(0, 0, At, B0); PG8_MMA(0, 1, At, B1); PG8_BAR; PG8_SCHED;
;             PG8_LDA(At, 1, 1); PG8_STAGE(PG8_SB(1, 0), b3, voffB); PG8_STAGE(PG8_SB(1, 1), b3 + hstepB, voffB); PG8_STAGE(PG8_SA(1, 0), a3, voffA);
;             PG8_WAIT_V(8); PG8_WAIT_L(0); PG8_BAR; PG8_MMA(1, 0, At, B0); PG8_MMA(1, 1, At, B1); PG8_BAR; PG8_SCHED;
	ds_read_b128 v[80:83], v253
	ds_read_b128 v[84:87], v253 offset:1024
	ds_read_b128 v[88:91], v253 offset:2048
	ds_read_b128 v[92:95], v253 offset:3072
	ds_read_b128 v[166:169], v252
	ds_read_b128 v[170:173], v252 offset:1024
	ds_read_b128 v[174:177], v252 offset:2048
	ds_read_b128 v[178:181], v252 offset:3072
	ds_read_b128 v[182:185], v163 offset:32768
	ds_read_b128 v[186:189], v163 offset:33792
	ds_read_b128 v[194:197], v163 offset:34816
	ds_read_b128 v[198:201], v163 offset:35840
	ds_read_b128 v[202:205], v163 offset:36864
	ds_read_b128 v[206:209], v163 offset:37888
	ds_read_b128 v[210:213], v163 offset:38912
	ds_read_b128 v[214:217], v163 offset:39936
	s_add_u32 s22, s22, 0x84000
	s_addc_u32 s23, s23, 0
	s_mov_b32 m0, s35
	s_nop 0
	global_load_lds_dwordx4 v147, s[22:23]
	s_nop 0
	s_mov_b32 m0, s36
	s_nop 0
	global_load_lds_dwordx4 v151, s[22:23]
	s_waitcnt vmcnt(8) lgkmcnt(0)
	s_setprio 1
	s_barrier
	v_mfma_f32_16x16x32_bf16 v[140:143], v[80:83], v[182:185], v[140:143]
	v_mfma_f32_16x16x32_bf16 v[136:139], v[88:91], v[182:185], v[136:139]
	v_mfma_f32_16x16x32_bf16 v[124:127], v[80:83], v[194:197], v[124:127]
	v_mfma_f32_16x16x32_bf16 v[120:123], v[88:91], v[194:197], v[120:123]
	v_mfma_f32_16x16x32_bf16 v[108:111], v[80:83], v[202:205], v[108:111]
	v_mfma_f32_16x16x32_bf16 v[104:107], v[88:91], v[202:205], v[104:107]
	v_mfma_f32_16x16x32_bf16 v[76:79], v[80:83], v[210:213], v[76:79]
	v_mfma_f32_16x16x32_bf16 v[72:75], v[88:91], v[210:213], v[72:75]
	v_mfma_f32_16x16x32_bf16 v[140:143], v[84:87], v[186:189], v[140:143]
	v_mfma_f32_16x16x32_bf16 v[136:139], v[92:95], v[186:189], v[136:139]
	v_mfma_f32_16x16x32_bf16 v[124:127], v[84:87], v[198:201], v[124:127]
	v_mfma_f32_16x16x32_bf16 v[120:123], v[92:95], v[198:201], v[120:123]
	v_mfma_f32_16x16x32_bf16 v[108:111], v[84:87], v[206:209], v[108:111]
	v_mfma_f32_16x16x32_bf16 v[104:107], v[92:95], v[206:209], v[104:107]
	v_mfma_f32_16x16x32_bf16 v[76:79], v[84:87], v[214:217], v[76:79]
	v_mfma_f32_16x16x32_bf16 v[72:75], v[92:95], v[214:217], v[72:75]
	v_mfma_f32_16x16x32_bf16 v[132:135], v[166:169], v[182:185], v[132:135]
	v_mfma_f32_16x16x32_bf16 v[128:131], v[174:177], v[182:185], v[128:131]
	v_mfma_f32_16x16x32_bf16 v[116:119], v[166:169], v[194:197], v[116:119]
	v_mfma_f32_16x16x32_bf16 v[112:115], v[174:177], v[194:197], v[112:115]
	v_mfma_f32_16x16x32_bf16 v[100:103], v[166:169], v[202:205], v[100:103]
	v_mfma_f32_16x16x32_bf16 v[96:99], v[174:177], v[202:205], v[96:99]
	v_mfma_f32_16x16x32_bf16 v[68:71], v[166:169], v[210:213], v[68:71]
	v_mfma_f32_16x16x32_bf16 v[64:67], v[174:177], v[210:213], v[64:67]
	v_mfma_f32_16x16x32_bf16 v[132:135], v[170:173], v[186:189], v[132:135]
	v_mfma_f32_16x16x32_bf16 v[128:131], v[178:181], v[186:189], v[128:131]
	v_mfma_f32_16x16x32_bf16 v[116:119], v[170:173], v[198:201], v[116:119]
	v_mfma_f32_16x16x32_bf16 v[112:115], v[178:181], v[198:201], v[112:115]
	v_mfma_f32_16x16x32_bf16 v[100:103], v[170:173], v[206:209], v[100:103]
	v_mfma_f32_16x16x32_bf16 v[96:99], v[178:181], v[206:209], v[96:99]
	v_mfma_f32_16x16x32_bf16 v[68:71], v[170:173], v[214:217], v[68:71]
	v_mfma_f32_16x16x32_bf16 v[64:67], v[178:181], v[214:217], v[64:67]
	s_setprio 0
	s_barrier
	ds_read_b128 v[182:185], v163 offset:49152
	ds_read_b128 v[186:189], v163 offset:50176
	ds_read_b128 v[194:197], v163 offset:51200
	ds_read_b128 v[198:201], v163 offset:52224
	ds_read_b128 v[202:205], v163 offset:53248
	ds_read_b128 v[206:209], v163 offset:54272
	ds_read_b128 v[210:213], v163 offset:55296
	ds_read_b128 v[214:217], v163 offset:56320
	s_add_u32 s22, s20, 0x80
	s_addc_u32 s23, s21, 0
	s_mov_b32 m0, s45
	s_nop 0
	global_load_lds_dwordx4 v149, s[22:23]
	s_add_u32 s20, s20, 0x80080
	s_mov_b32 m0, s46
	s_nop 0
	global_load_lds_dwordx4 v153, s[22:23]
	s_addc_u32 s21, s21, 0
	s_mov_b32 m0, s49
	s_nop 0
	global_load_lds_dwordx4 v149, s[20:21]
	s_nop 0
	s_mov_b32 m0, s50
	s_nop 0
	global_load_lds_dwordx4 v153, s[20:21]
	s_nop 0
	s_mov_b32 m0, s47
	s_nop 0
	global_load_lds_dwordx4 v147, s[18:19]
	s_nop 0
	s_mov_b32 m0, s48
	s_nop 0
	global_load_lds_dwordx4 v151, s[18:19]
	s_waitcnt vmcnt(8) lgkmcnt(0)
	s_setprio 1
	s_barrier
	v_mfma_f32_16x16x32_bf16 v[60:63], v[80:83], v[182:185], v[60:63]
	v_mfma_f32_16x16x32_bf16 v[56:59], v[88:91], v[182:185], v[56:59]
	v_mfma_f32_16x16x32_bf16 v[44:47], v[80:83], v[194:197], v[44:47]
	v_mfma_f32_16x16x32_bf16 v[40:43], v[88:91], v[194:197], v[40:43]
	v_mfma_f32_16x16x32_bf16 v[28:31], v[80:83], v[202:205], v[28:31]
	v_mfma_f32_16x16x32_bf16 v[24:27], v[88:91], v[202:205], v[24:27]
	v_mfma_f32_16x16x32_bf16 v[12:15], v[80:83], v[210:213], v[12:15]
	v_mfma_f32_16x16x32_bf16 v[8:11], v[88:91], v[210:213], v[8:11]
	v_mfma_f32_16x16x32_bf16 v[60:63], v[84:87], v[186:189], v[60:63]
	v_mfma_f32_16x16x32_bf16 v[56:59], v[92:95], v[186:189], v[56:59]
	v_mfma_f32_16x16x32_bf16 v[44:47], v[84:87], v[198:201], v[44:47]
	v_mfma_f32_16x16x32_bf16 v[40:43], v[92:95], v[198:201], v[40:43]
	v_mfma_f32_16x16x32_bf16 v[28:31], v[84:87], v[206:209], v[28:31]
	v_mfma_f32_16x16x32_bf16 v[24:27], v[92:95], v[206:209], v[24:27]
	v_mfma_f32_16x16x32_bf16 v[12:15], v[84:87], v[214:217], v[12:15]
	v_mfma_f32_16x16x32_bf16 v[8:11], v[92:95], v[214:217], v[8:11]
	v_mfma_f32_16x16x32_bf16 v[52:55], v[166:169], v[182:185], v[52:55]
	v_mfma_f32_16x16x32_bf16 v[48:51], v[174:177], v[182:185], v[48:51]
	v_mfma_f32_16x16x32_bf16 v[36:39], v[166:169], v[194:197], v[36:39]
	v_mfma_f32_16x16x32_bf16 v[32:35], v[174:177], v[194:197], v[32:35]
	v_mfma_f32_16x16x32_bf16 v[20:23], v[166:169], v[202:205], v[20:23]
	v_mfma_f32_16x16x32_bf16 v[16:19], v[174:177], v[202:205], v[16:19]
	v_mfma_f32_16x16x32_bf16 v[4:7], v[166:169], v[210:213], v[4:7]
	v_mfma_f32_16x16x32_bf16 v[0:3], v[174:177], v[210:213], v[0:3]
	v_mfma_f32_16x16x32_bf16 v[52:55], v[170:173], v[186:189], v[52:55]
	v_mfma_f32_16x16x32_bf16 v[48:51], v[178:181], v[186:189], v[48:51]
	v_mfma_f32_16x16x32_bf16 v[36:39], v[170:173], v[198:201], v[36:39]
	v_mfma_f32_16x16x32_bf16 v[32:35], v[178:181], v[198:201], v[32:35]
	v_mfma_f32_16x16x32_bf16 v[20:23], v[170:173], v[206:209], v[20:23]
	v_mfma_f32_16x16x32_bf16 v[16:19], v[178:181], v[206:209], v[16:19]
	v_mfma_f32_16x16x32_bf16 v[4:7], v[170:173], v[214:217], v[4:7]
	v_mfma_f32_16x16x32_bf16 v[0:3], v[178:181], v[214:217], v[0:3]
	s_setprio 0
	s_barrier
	s_add_u32 s72, s72, 0x100
	s_addc_u32 s77, s77, 0
	s_add_u32 s79, s79, 0x100
	s_addc_u32 s83, s83, 0
	s_cmp_ge_i32 s84, s40
	s_mov_b32 s18, s84
	s_cbranch_scc0 .LBB0_268
	s_mov_b32 s79, 0xc00000
	s_and_b64 vcc, exec, s[10:11]
	s_cbranch_vccz .LBB0_271

; #define PG8_STAGE(bufoff, gbase, voff) do { _Pragma("unroll") for (int _i = 0; _i < 2; ++_i) \
;         asm volatile("s_mov_b32 m0, %0\n\ts_nop 0\n\tglobal_load_lds_dwordx4 %1, %2" :: "s"(ldsb + (unsigned)((bufoff) + _i * 8192)), "v"((voff)[_i]), "s"(gbase) : "m0", "memory"); } while (0)
; #define PG8_WAIT_V(n) asm volatile("s_waitcnt vmcnt(" #n ")" ::: "memory")
; #define PG8_BAR __builtin_amdgcn_s_barrier()
; template <class Epi, class Sched, bool ALIGN_EPI = false, bool SP2 = false>
; __device__ __forceinline__ void gemm_phase(PG8_LAS unsigned char* lds, const Gemm g, const Sched& S, const Epi& E, const int wv) {
;     ...
;     for (int i = 0; i < 2; ++i) { int R, C; stage_rc(tid * 16 + i * 8192, R, C); const int Rb = Epi::PERM ? ((R & ~31) + perm32(R & 31)) : R;
;         voffA[i] = (unsigned)(R * K + C) * 2u; voffB[i] = (unsigned)(Rb * Kb + C) * 2u; }
;     const size_t kstep = (size_t)(BK * 2);
;     const size_t hstepA = (size_t)HALF * K * 2, hstepB = (size_t)HALF * Kb * 2;
;     const size_t tstepA = 2 * hstepA, tstepB = 2 * hstepB;
;     const unsigned ldsw = (unsigned)wid * 1024u;
;     const unsigned ldsb = (unsigned)(size_t)lds + ldsw;
;     const int aoff = lds_byte(wr * 64 + fr, fq * 8), boff = lds_byte(wc * 32 + fr, fq * 8);
;     ...
;     if constexpr (SP2) {
;         PG8_STAGE(PG8_SB(0, 0), cB, voffB); PG8_STAGE(PG8_SB(0, 1), cB + hstepB, voffB); PG8_STAGE(PG8_SA(0, 0), cA, voffA); PG8_STAGE(PG8_SA(0, 1), cA + hstepA, voffA);
;         if (wr == 1) PG8_BAR;
;         PG8_WAIT_V(2); PG8_BAR;
;         PG8_STAGE(PG8_SB(1, 0), cB + kstep, voffB); PG8_STAGE(PG8_SA(1, 0), cA + kstep, voffA); PG8_STAGE(PG8_SB(1, 1), cB + hstepB + kstep, voffB);
;         PG8_WAIT_V(6); PG8_BAR;
.LBB0_324:
	v_readlane_b32 s8, v254, 56
	v_readlane_b32 s2, v254, 32
	v_readlane_b32 s9, v254, 57
	s_bfe_u32 s40, s2, 0x80010
	s_bfe_u32 s21, s2, 0x40018
	s_lshl_b64 s[10:11], s[8:9], 2
	s_add_u32 s2, s6, s10
	s_addc_u32 s8, s7, s11
	s_add_u32 s10, s6, 0x44f000
	s_addc_u32 s11, s7, 0
	s_add_u32 s54, s2, 0x24000
	s_addc_u32 s55, s8, 0
	s_add_u32 s12, s6, 0x8c4f000
	v_readlane_b32 s9, v254, 43
	s_addc_u32 s13, s7, 0
	s_mulk_i32 s9, 0x6000
	s_waitcnt lgkmcnt(0)
	s_add_u32 s4, s4, s9
	s_addc_u32 s5, s5, 0
	s_add_u32 s14, s4, 0x2000
	s_addc_u32 s15, s5, 0
	s_add_u32 s57, s2, 0x28000
	s_addc_u32 s72, s8, 0
	v_bfe_u32 v1, v0, 4, 2
	s_add_u32 s16, s6, 0x3b98f000
	v_and_b32_e32 v212, 15, v0
	v_lshlrev_b32_e32 v2, 4, v1
	v_lshlrev_b32_e32 v3, 2, v0
	s_addc_u32 s17, s7, 0
	s_and_b32 s2, s20, 3
	v_lshl_or_b32 v2, v212, 6, v2
	s_lshl_b32 s4, s22, 13
	v_and_b32_e32 v3, 32, v3
	s_lshl_b32 s84, s22, 6
	v_bitop3_b32 v4, v2, s4, v3 bitop3:0xde
	s_lshl_b32 s8, s2, 5
	s_lshl_b32 s4, s2, 12
	s_add_i32 s86, s46, 0x18000
	v_bitop3_b32 v3, v2, s4, v3 bitop3:0xde
	s_add_u32 s4, s28, 0x80
	s_waitcnt vmcnt(2)
	s_barrier
	s_addc_u32 s5, s29, 0
	s_mov_b32 m0, s86
	s_nop 0
	global_load_lds_dwordx4 v209, s[4:5]
	s_add_i32 s87, s46, 0x1a000
	s_add_i32 s83, s46, 0x8000
	s_mov_b32 m0, s87
	s_nop 0
	global_load_lds_dwordx4 v211, s[4:5]
	s_add_u32 s4, s30, 0x80
	s_addc_u32 s5, s31, 0
	s_mov_b32 m0, s83
	s_nop 0
	global_load_lds_dwordx4 v208, s[4:5]
	s_add_i32 s60, s46, 0xa000
	s_add_i32 s89, s46, 0x1c000
	s_mov_b32 m0, s60
	s_nop 0
	global_load_lds_dwordx4 v210, s[4:5]
	s_add_u32 s4, s18, 0x80
	s_addc_u32 s5, s19, 0
	s_add_i32 s92, s46, 0x1e000
	s_add_i32 s93, s46, 0xc000
	s_mov_b32 m0, s89
	s_nop 0
	global_load_lds_dwordx4 v209, s[4:5]
	s_cmp_lt_u32 s20, 4
	s_mov_b32 m0, s92
	s_nop 0
	global_load_lds_dwordx4 v211, s[4:5]
	s_cselect_b64 s[18:19], -1, 0
	s_ashr_i32 s4, s84, 31
	s_add_i32 s58, s46, 0xe000
	s_lshl_b32 s2, s2, 2
	s_add_u32 s2, s6, s2
	v_lshrrev_b32_e32 v5, 2, v0
	s_addc_u32 s6, s7, 0
	s_waitcnt vmcnt(6)
	v_and_b32_e32 v2, 3, v0
	v_and_b32_e32 v6, 60, v0
	v_and_or_b32 v156, v5, 15, s84
	v_and_b32_e32 v5, 63, v0
	v_bfe_u32 v215, v0, 2, 4
	v_lshlrev_b32_e32 v0, 4, v212
	s_add_u32 s88, s2, 0x21e000
	s_mov_b32 s2, s24
	v_lshl_or_b32 v214, v2, 6, v6
	v_lshlrev_b32_e32 v2, 3, v2
	v_lshl_or_b32 v216, v1, 2, v0
	v_lshlrev_b32_e32 v0, 2, v5
	v_writelane_b32 v254, s2, 30
	v_lshl_or_b32 v213, v1, 3, s8
	v_mov_b32_e32 v157, s4
	v_or_b32_e32 v217, s8, v2
	v_xor_b32_e32 v218, 64, v0
	v_xor_b32_e32 v219, 0x80, v0
	s_mov_b32 s71, 0
	v_cmp_eq_u32_e64 s[4:5], 0, v1
	s_addc_u32 s97, s6, 0
	s_ashr_i32 s90, s70, 31
	v_add_u32_e32 v220, 0, v3
	v_add_u32_e32 v253, 0x10000, v220
	v_add_u32_e32 v252, 0x14000, v220
	v_add_u32_e32 v251, 0x18000, v220
	v_add_u32_e32 v250, 0x1c000, v220
	v_add_u32_e32 v221, 0, v4
	s_lshl_b32 s20, s8, 1
	v_lshlrev_b32_e32 v158, 1, v2
	v_writelane_b32 v254, s3, 31
	s_mov_b32 s22, s24
	s_barrier
	s_branch .LBB0_327

; #define PG8_STAGE(bufoff, gbase, voff) do { _Pragma("unroll") for (int _i = 0; _i < 2; ++_i) \
;         asm volatile("s_mov_b32 m0, %0\n\ts_nop 0\n\tglobal_load_lds_dwordx4 %1, %2" :: "s"(ldsb + (unsigned)((bufoff) + _i * 8192)), "v"((voff)[_i]), "s"(gbase) : "m0", "memory"); } while (0)
; #define PG8_LDA(dst, b, h) do { _Pragma("unroll") for (int m = 0; m < 4; ++m) _Pragma("unroll") for (int k = 0; k < 2; ++k) dst[m][k] = *(const PG8_LAS bf16x8*)(lds + PG8_SA(b, h) + aoff + m * 2048 + k * 1024); } while (0)
; #define PG8_LDB(dst, b, h) do { _Pragma("unroll") for (int n = 0; n < 2; ++n) _Pragma("unroll") for (int k = 0; k < 2; ++k) dst[n][k] = *(const PG8_LAS bf16x8*)(lds + PG8_SB(b, h) + boff + n * 2048 + k * 1024); } while (0)
; #define PG8_MMA(ai, bj, At, Bt) do { __builtin_amdgcn_s_setprio(1); _Pragma("unroll") for (int m = 0; m < 4; ++m) _Pragma("unroll") for (int n = 0; n < 2; ++n) _Pragma("unroll") for (int k = 0; k < 2; ++k) \
;         acc[ai][bj][m][n] = __builtin_amdgcn_mfma_f32_16x16x32_bf16(Bt[n][k], At[m][k], acc[ai][bj][m][n], 0, 0, 0); __builtin_amdgcn_s_setprio(0); } while (0)
; #define PG8_WAIT_V(n) asm volatile("s_waitcnt vmcnt(" #n ")" ::: "memory")
; template <class Epi, class Sched, bool ALIGN_EPI = false, bool SP2 = false>
; __device__ __forceinline__ void gemm_phase(PG8_LAS unsigned char* lds, const Gemm g, const Sched& S, const Epi& E, const int wv) {
;     ...
;         for (int t = 0; t < nt; t += 2) {
;             const bool last = (t == nt - 2);
;             const char* a1 = cA + (size_t)(t + 1) * kstep;
;             const char* a2 = last ? nA : cA + (size_t)(t + 2) * kstep; const char* b2 = last ? nB : cB + (size_t)(t + 2) * kstep;
;             const char* a3 = a2 + kstep; const char* b3 = b2 + kstep;
;             if (last && has_next) S.a_ready(nxt);
;             if constexpr (SP2) {
;             PG8_LDB(B0, 0, 0); PG8_LDB(B1, 0, 1); PG8_SCHED; PG8_LDA(At, 0, 0); PG8_STAGE(PG8_SA(1, 1), a1 + hstepA, voffA);
;             PG8_WAIT_V(8); PG8_WAIT_L(0); PG8_BAR; PG8_MMA(0, 0, At, B0); PG8_MMA(0, 1, At, B1); PG8_BAR; PG8_SCHED;
;             PG8_LDA(At, 0, 1); PG8_STAGE(PG8_SB(0, 0), b2, voffB); PG8_STAGE(PG8_SB(0, 1), b2 + hstepB, voffB); PG8_STAGE(PG8_SA(0, 0), a2, voffA);
;             PG8_WAIT_V(8); PG8_WAIT_L(0); PG8_BAR; PG8_MMA(1, 0, At, B0); PG8_MMA(1, 1, At, B1); PG8_BAR; PG8_SCHED;
.LBB0_343:
	ds_read_b128 v[128:131], v253
	ds_read_b128 v[132:135], v253 offset:1024
	ds_read_b128 v[136:139], v253 offset:2048
	ds_read_b128 v[140:143], v253 offset:3072
	ds_read_b128 v[144:147], v252
	ds_read_b128 v[148:151], v252 offset:1024
	ds_read_b128 v[152:155], v252 offset:2048
	ds_read_b128 v[160:163], v252 offset:3072
	s_add_i32 s62, s30, 2
	s_cmp_eq_u32 s23, s30
	s_cselect_b32 s36, s24, s85
	s_cselect_b32 s37, s25, vcc_lo
	s_cselect_b32 s34, s26, vcc_hi
	s_cselect_b32 s35, s27, s79
	s_add_u32 s30, s36, 0x80
	s_addc_u32 s31, s37, 0
	ds_read_b128 v[164:167], v221
	ds_read_b128 v[168:171], v221 offset:1024
	ds_read_b128 v[172:175], v221 offset:2048
	ds_read_b128 v[176:179], v221 offset:3072
	ds_read_b128 v[180:183], v221 offset:4096
	ds_read_b128 v[184:187], v221 offset:5120
	ds_read_b128 v[188:191], v221 offset:6144
	ds_read_b128 v[194:197], v221 offset:7168
	s_mov_b32 m0, s93
	s_nop 0
	global_load_lds_dwordx4 v208, s[28:29]
	s_nop 0
	s_mov_b32 m0, s58
	s_nop 0
	global_load_lds_dwordx4 v210, s[28:29]
	s_waitcnt vmcnt(8) lgkmcnt(0)
	s_setprio 1
	s_barrier
	v_mfma_f32_16x16x32_bf16 v[124:127], v[128:131], v[164:167], v[124:127]
	v_mfma_f32_16x16x32_bf16 v[120:123], v[136:139], v[164:167], v[120:123]
	v_mfma_f32_16x16x32_bf16 v[108:111], v[128:131], v[172:175], v[108:111]
	v_mfma_f32_16x16x32_bf16 v[104:107], v[136:139], v[172:175], v[104:107]
	v_mfma_f32_16x16x32_bf16 v[92:95], v[128:131], v[180:183], v[92:95]
	v_mfma_f32_16x16x32_bf16 v[88:91], v[136:139], v[180:183], v[88:91]
	v_mfma_f32_16x16x32_bf16 v[76:79], v[128:131], v[188:191], v[76:79]
	v_mfma_f32_16x16x32_bf16 v[72:75], v[136:139], v[188:191], v[72:75]
	v_mfma_f32_16x16x32_bf16 v[124:127], v[132:135], v[168:171], v[124:127]
	v_mfma_f32_16x16x32_bf16 v[120:123], v[140:143], v[168:171], v[120:123]
	v_mfma_f32_16x16x32_bf16 v[108:111], v[132:135], v[176:179], v[108:111]
	v_mfma_f32_16x16x32_bf16 v[104:107], v[140:143], v[176:179], v[104:107]
	v_mfma_f32_16x16x32_bf16 v[92:95], v[132:135], v[184:187], v[92:95]
	v_mfma_f32_16x16x32_bf16 v[88:91], v[140:143], v[184:187], v[88:91]
	v_mfma_f32_16x16x32_bf16 v[76:79], v[132:135], v[194:197], v[76:79]
	v_mfma_f32_16x16x32_bf16 v[72:75], v[140:143], v[194:197], v[72:75]
	v_mfma_f32_16x16x32_bf16 v[116:119], v[144:147], v[164:167], v[116:119]
	v_mfma_f32_16x16x32_bf16 v[112:115], v[152:155], v[164:167], v[112:115]
	v_mfma_f32_16x16x32_bf16 v[100:103], v[144:147], v[172:175], v[100:103]
	v_mfma_f32_16x16x32_bf16 v[96:99], v[152:155], v[172:175], v[96:99]
	v_mfma_f32_16x16x32_bf16 v[84:87], v[144:147], v[180:183], v[84:87]
	v_mfma_f32_16x16x32_bf16 v[80:83], v[152:155], v[180:183], v[80:83]
	v_mfma_f32_16x16x32_bf16 v[68:71], v[144:147], v[188:191], v[68:71]
	v_mfma_f32_16x16x32_bf16 v[64:67], v[152:155], v[188:191], v[64:67]
	v_mfma_f32_16x16x32_bf16 v[116:119], v[148:151], v[168:171], v[116:119]
	v_mfma_f32_16x16x32_bf16 v[112:115], v[160:163], v[168:171], v[112:115]
	v_mfma_f32_16x16x32_bf16 v[100:103], v[148:151], v[176:179], v[100:103]
	v_mfma_f32_16x16x32_bf16 v[96:99], v[160:163], v[176:179], v[96:99]
	v_mfma_f32_16x16x32_bf16 v[84:87], v[148:151], v[184:187], v[84:87]
	v_mfma_f32_16x16x32_bf16 v[80:83], v[160:163], v[184:187], v[80:83]
	v_mfma_f32_16x16x32_bf16 v[68:71], v[148:151], v[194:197], v[68:71]
	v_mfma_f32_16x16x32_bf16 v[64:67], v[160:163], v[194:197], v[64:67]
	s_setprio 0
	s_barrier
	ds_read_b128 v[164:167], v221 offset:16384
	ds_read_b128 v[168:171], v221 offset:17408
	ds_read_b128 v[172:175], v221 offset:18432
	ds_read_b128 v[176:179], v221 offset:19456
	ds_read_b128 v[180:183], v221 offset:20480
	ds_read_b128 v[184:187], v221 offset:21504
	ds_read_b128 v[188:191], v221 offset:22528
	ds_read_b128 v[194:197], v221 offset:23552
	s_mov_b32 m0, s47
	s_nop 0
	global_load_lds_dwordx4 v209, s[34:35]
	s_add_u32 s8, s34, 0x160000
	s_mov_b32 m0, s48
	s_nop 0
	global_load_lds_dwordx4 v211, s[34:35]
	s_addc_u32 s9, s35, 0
	s_mov_b32 m0, s49
	s_nop 0
	global_load_lds_dwordx4 v209, s[8:9]
	s_nop 0
	s_mov_b32 m0, s50
	s_nop 0
	global_load_lds_dwordx4 v211, s[8:9]
	s_nop 0
	s_mov_b32 m0, s46
	s_nop 0
	global_load_lds_dwordx4 v208, s[36:37]
	s_nop 0
	s_mov_b32 m0, s51
	s_nop 0
	global_load_lds_dwordx4 v210, s[36:37]
	s_waitcnt vmcnt(8) lgkmcnt(0)
	s_setprio 1
	s_barrier
	v_mfma_f32_16x16x32_bf16 v[60:63], v[128:131], v[164:167], v[60:63]
	v_mfma_f32_16x16x32_bf16 v[56:59], v[136:139], v[164:167], v[56:59]
	v_mfma_f32_16x16x32_bf16 v[44:47], v[128:131], v[172:175], v[44:47]
	v_mfma_f32_16x16x32_bf16 v[40:43], v[136:139], v[172:175], v[40:43]
	v_mfma_f32_16x16x32_bf16 v[28:31], v[128:131], v[180:183], v[28:31]
	v_mfma_f32_16x16x32_bf16 v[24:27], v[136:139], v[180:183], v[24:27]
	v_mfma_f32_16x16x32_bf16 v[12:15], v[128:131], v[188:191], v[12:15]
	v_mfma_f32_16x16x32_bf16 v[8:11], v[136:139], v[188:191], v[8:11]
	v_mfma_f32_16x16x32_bf16 v[60:63], v[132:135], v[168:171], v[60:63]
	v_mfma_f32_16x16x32_bf16 v[56:59], v[140:143], v[168:171], v[56:59]
	v_mfma_f32_16x16x32_bf16 v[44:47], v[132:135], v[176:179], v[44:47]
	v_mfma_f32_16x16x32_bf16 v[40:43], v[140:143], v[176:179], v[40:43]
	v_mfma_f32_16x16x32_bf16 v[28:31], v[132:135], v[184:187], v[28:31]
	v_mfma_f32_16x16x32_bf16 v[24:27], v[140:143], v[184:187], v[24:27]
	v_mfma_f32_16x16x32_bf16 v[12:15], v[132:135], v[194:197], v[12:15]
	v_mfma_f32_16x16x32_bf16 v[8:11], v[140:143], v[194:197], v[8:11]
	v_mfma_f32_16x16x32_bf16 v[52:55], v[144:147], v[164:167], v[52:55]
	v_mfma_f32_16x16x32_bf16 v[48:51], v[152:155], v[164:167], v[48:51]
	v_mfma_f32_16x16x32_bf16 v[36:39], v[144:147], v[172:175], v[36:39]
	v_mfma_f32_16x16x32_bf16 v[32:35], v[152:155], v[172:175], v[32:35]
	v_mfma_f32_16x16x32_bf16 v[20:23], v[144:147], v[180:183], v[20:23]
	v_mfma_f32_16x16x32_bf16 v[16:19], v[152:155], v[180:183], v[16:19]
	v_mfma_f32_16x16x32_bf16 v[4:7], v[144:147], v[188:191], v[4:7]
	v_mfma_f32_16x16x32_bf16 v[0:3], v[152:155], v[188:191], v[0:3]
	v_mfma_f32_16x16x32_bf16 v[52:55], v[148:151], v[168:171], v[52:55]
	v_mfma_f32_16x16x32_bf16 v[48:51], v[160:163], v[168:171], v[48:51]
	v_mfma_f32_16x16x32_bf16 v[36:39], v[148:151], v[176:179], v[36:39]
	v_mfma_f32_16x16x32_bf16 v[32:35], v[160:163], v[176:179], v[32:35]
	v_mfma_f32_16x16x32_bf16 v[20:23], v[148:151], v[184:187], v[20:23]
	v_mfma_f32_16x16x32_bf16 v[16:19], v[160:163], v[184:187], v[16:19]
	v_mfma_f32_16x16x32_bf16 v[4:7], v[148:151], v[194:197], v[4:7]
	v_mfma_f32_16x16x32_bf16 v[0:3], v[160:163], v[194:197], v[0:3]
	s_setprio 0
	s_barrier
; #define PG8_STAGE(bufoff, gbase, voff) do { _Pragma("unroll") for (int _i = 0; _i < 2; ++_i) \
;         asm volatile("s_mov_b32 m0, %0\n\ts_nop 0\n\tglobal_load_lds_dwordx4 %1, %2" :: "s"(ldsb + (unsigned)((bufoff) + _i * 8192)), "v"((voff)[_i]), "s"(gbase) : "m0", "memory"); } while (0)
; #define PG8_LDA(dst, b, h) do { _Pragma("unroll") for (int m = 0; m < 4; ++m) _Pragma("unroll") for (int k = 0; k < 2; ++k) dst[m][k] = *(const PG8_LAS bf16x8*)(lds + PG8_SA(b, h) + aoff + m * 2048 + k * 1024); } while (0)
; #define PG8_LDB(dst, b, h) do { _Pragma("unroll") for (int n = 0; n < 2; ++n) _Pragma("unroll") for (int k = 0; k < 2; ++k) dst[n][k] = *(const PG8_LAS bf16x8*)(lds + PG8_SB(b, h) + boff + n * 2048 + k * 1024); } while (0)
; #define PG8_MMA(ai, bj, At, Bt) do { __builtin_amdgcn_s_setprio(1); _Pragma("unroll") for (int m = 0; m < 4; ++m) _Pragma("unroll") for (int n = 0; n < 2; ++n) _Pragma("unroll") for (int k = 0; k < 2; ++k) \
;         acc[ai][bj][m][n] = __builtin_amdgcn_mfma_f32_16x16x32_bf16(Bt[n][k], At[m][k], acc[ai][bj][m][n], 0, 0, 0); __builtin_amdgcn_s_setprio(0); } while (0)
; #define PG8_WAIT_V(n) asm volatile("s_waitcnt vmcnt(" #n ")" ::: "memory")
; #define PG8_WAIT_L(n) asm volatile("s_waitcnt lgkmcnt(" #n ")" ::: "memory")
; #define PG8_BAR __builtin_amdgcn_s_barrier()
; template <class Epi, class Sched, bool ALIGN_EPI = false, bool SP2 = false>
; __device__ __forceinline__ void gemm_phase(PG8_LAS unsigned char* lds, const Gemm g, const Sched& S, const Epi& E, const int wv) {
;     ...
;         for (int t = 0; t < nt; t += 2) {
;             const bool last = (t == nt - 2);
;             const char* a1 = cA + (size_t)(t + 1) * kstep;
;             const char* a2 = last ? nA : cA + (size_t)(t + 2) * kstep; const char* b2 = last ? nB : cB + (size_t)(t + 2) * kstep;
;             const char* a3 = a2 + kstep; const char* b3 = b2 + kstep;
;     ...
;             PG8_LDB(B0, 1, 0); PG8_LDB(B1, 1, 1); PG8_SCHED; PG8_LDA(At, 1, 0); PG8_STAGE(PG8_SA(0, 1), a2 + hstepA, voffA);
;             PG8_WAIT_V(8); PG8_WAIT_L(0); PG8_BAR; PG8_MMA(0, 0, At, B0); PG8_MMA(0, 1, At, B1); PG8_BAR; PG8_SCHED;
;             PG8_LDA(At, 1, 1); PG8_STAGE(PG8_SB(1, 0), b3, voffB); PG8_STAGE(PG8_SB(1, 1), b3 + hstepB, voffB); PG8_STAGE(PG8_SA(1, 0), a3, voffA);
;             PG8_WAIT_V(8); PG8_WAIT_L(0); PG8_BAR; PG8_MMA(1, 0, At, B0); PG8_MMA(1, 1, At, B1); PG8_BAR; PG8_SCHED;
	ds_read_b128 v[128:131], v251
	ds_read_b128 v[132:135], v251 offset:1024
	ds_read_b128 v[136:139], v251 offset:2048
	ds_read_b128 v[140:143], v251 offset:3072
	ds_read_b128 v[144:147], v250
	ds_read_b128 v[148:151], v250 offset:1024
	ds_read_b128 v[152:155], v250 offset:2048
	ds_read_b128 v[160:163], v250 offset:3072
	ds_read_b128 v[164:167], v221 offset:32768
	ds_read_b128 v[168:171], v221 offset:33792
	ds_read_b128 v[172:175], v221 offset:34816
	ds_read_b128 v[176:179], v221 offset:35840
	ds_read_b128 v[180:183], v221 offset:36864
	ds_read_b128 v[184:187], v221 offset:37888
	ds_read_b128 v[188:191], v221 offset:38912
	ds_read_b128 v[194:197], v221 offset:39936
	s_add_u32 s8, s36, 0x160000
	s_addc_u32 s9, s37, 0
	s_mov_b32 m0, s52
	s_nop 0
	global_load_lds_dwordx4 v208, s[8:9]
	s_nop 0
	s_mov_b32 m0, s53
	s_nop 0
	global_load_lds_dwordx4 v210, s[8:9]
	s_waitcnt vmcnt(8) lgkmcnt(0)
	s_setprio 1
	s_barrier
	v_mfma_f32_16x16x32_bf16 v[124:127], v[128:131], v[164:167], v[124:127]
	v_mfma_f32_16x16x32_bf16 v[120:123], v[136:139], v[164:167], v[120:123]
	v_mfma_f32_16x16x32_bf16 v[108:111], v[128:131], v[172:175], v[108:111]
	v_mfma_f32_16x16x32_bf16 v[104:107], v[136:139], v[172:175], v[104:107]
	v_mfma_f32_16x16x32_bf16 v[92:95], v[128:131], v[180:183], v[92:95]
	v_mfma_f32_16x16x32_bf16 v[88:91], v[136:139], v[180:183], v[88:91]
	v_mfma_f32_16x16x32_bf16 v[76:79], v[128:131], v[188:191], v[76:79]
	v_mfma_f32_16x16x32_bf16 v[72:75], v[136:139], v[188:191], v[72:75]
	v_mfma_f32_16x16x32_bf16 v[124:127], v[132:135], v[168:171], v[124:127]
	v_mfma_f32_16x16x32_bf16 v[120:123], v[140:143], v[168:171], v[120:123]
	v_mfma_f32_16x16x32_bf16 v[108:111], v[132:135], v[176:179], v[108:111]
	v_mfma_f32_16x16x32_bf16 v[104:107], v[140:143], v[176:179], v[104:107]
	v_mfma_f32_16x16x32_bf16 v[92:95], v[132:135], v[184:187], v[92:95]
	v_mfma_f32_16x16x32_bf16 v[88:91], v[140:143], v[184:187], v[88:91]
	v_mfma_f32_16x16x32_bf16 v[76:79], v[132:135], v[194:197], v[76:79]
	v_mfma_f32_16x16x32_bf16 v[72:75], v[140:143], v[194:197], v[72:75]
	v_mfma_f32_16x16x32_bf16 v[116:119], v[144:147], v[164:167], v[116:119]
	v_mfma_f32_16x16x32_bf16 v[112:115], v[152:155], v[164:167], v[112:115]
	v_mfma_f32_16x16x32_bf16 v[100:103], v[144:147], v[172:175], v[100:103]
	v_mfma_f32_16x16x32_bf16 v[96:99], v[152:155], v[172:175], v[96:99]
	v_mfma_f32_16x16x32_bf16 v[84:87], v[144:147], v[180:183], v[84:87]
	v_mfma_f32_16x16x32_bf16 v[80:83], v[152:155], v[180:183], v[80:83]
	v_mfma_f32_16x16x32_bf16 v[68:71], v[144:147], v[188:191], v[68:71]
	v_mfma_f32_16x16x32_bf16 v[64:67], v[152:155], v[188:191], v[64:67]
	v_mfma_f32_16x16x32_bf16 v[116:119], v[148:151], v[168:171], v[116:119]
	v_mfma_f32_16x16x32_bf16 v[112:115], v[160:163], v[168:171], v[112:115]
	v_mfma_f32_16x16x32_bf16 v[100:103], v[148:151], v[176:179], v[100:103]
	v_mfma_f32_16x16x32_bf16 v[96:99], v[160:163], v[176:179], v[96:99]
	v_mfma_f32_16x16x32_bf16 v[84:87], v[148:151], v[184:187], v[84:87]
	v_mfma_f32_16x16x32_bf16 v[80:83], v[160:163], v[184:187], v[80:83]
	v_mfma_f32_16x16x32_bf16 v[68:71], v[148:151], v[194:197], v[68:71]
	v_mfma_f32_16x16x32_bf16 v[64:67], v[160:163], v[194:197], v[64:67]
	s_setprio 0
	s_barrier
	ds_read_b128 v[164:167], v221 offset:49152
	ds_read_b128 v[168:171], v221 offset:50176
	ds_read_b128 v[172:175], v221 offset:51200
	ds_read_b128 v[176:179], v221 offset:52224
	ds_read_b128 v[180:183], v221 offset:53248
	ds_read_b128 v[184:187], v221 offset:54272
	ds_read_b128 v[188:191], v221 offset:55296
	ds_read_b128 v[194:197], v221 offset:56320
	s_add_u32 s8, s34, 0x80
	s_addc_u32 s9, s35, 0
	s_mov_b32 m0, s86
	s_nop 0
	global_load_lds_dwordx4 v209, s[8:9]
	s_nop 0
	s_mov_b32 m0, s87
	s_nop 0
	global_load_lds_dwordx4 v211, s[8:9]
	s_add_u32 s8, s34, 0x160080
	s_addc_u32 s9, s35, 0
	s_mov_b32 m0, s89
	s_nop 0
	global_load_lds_dwordx4 v209, s[8:9]
	s_nop 0
	s_mov_b32 m0, s92
	s_nop 0
	global_load_lds_dwordx4 v211, s[8:9]
	s_nop 0
	s_mov_b32 m0, s83
	s_nop 0
	global_load_lds_dwordx4 v208, s[30:31]
	s_nop 0
	s_mov_b32 m0, s60
	s_nop 0
	global_load_lds_dwordx4 v210, s[30:31]
	s_waitcnt vmcnt(8) lgkmcnt(0)
	s_setprio 1
	s_barrier
	v_mfma_f32_16x16x32_bf16 v[60:63], v[128:131], v[164:167], v[60:63]
	v_mfma_f32_16x16x32_bf16 v[56:59], v[136:139], v[164:167], v[56:59]
	v_mfma_f32_16x16x32_bf16 v[44:47], v[128:131], v[172:175], v[44:47]
	v_mfma_f32_16x16x32_bf16 v[40:43], v[136:139], v[172:175], v[40:43]
	v_mfma_f32_16x16x32_bf16 v[28:31], v[128:131], v[180:183], v[28:31]
	v_mfma_f32_16x16x32_bf16 v[24:27], v[136:139], v[180:183], v[24:27]
	v_mfma_f32_16x16x32_bf16 v[12:15], v[128:131], v[188:191], v[12:15]
	v_mfma_f32_16x16x32_bf16 v[8:11], v[136:139], v[188:191], v[8:11]
	v_mfma_f32_16x16x32_bf16 v[60:63], v[132:135], v[168:171], v[60:63]
	v_mfma_f32_16x16x32_bf16 v[56:59], v[140:143], v[168:171], v[56:59]
	v_mfma_f32_16x16x32_bf16 v[44:47], v[132:135], v[176:179], v[44:47]
	v_mfma_f32_16x16x32_bf16 v[40:43], v[140:143], v[176:179], v[40:43]
	v_mfma_f32_16x16x32_bf16 v[28:31], v[132:135], v[184:187], v[28:31]
	v_mfma_f32_16x16x32_bf16 v[24:27], v[140:143], v[184:187], v[24:27]
	v_mfma_f32_16x16x32_bf16 v[12:15], v[132:135], v[194:197], v[12:15]
	v_mfma_f32_16x16x32_bf16 v[8:11], v[140:143], v[194:197], v[8:11]
	v_mfma_f32_16x16x32_bf16 v[52:55], v[144:147], v[164:167], v[52:55]
	v_mfma_f32_16x16x32_bf16 v[48:51], v[152:155], v[164:167], v[48:51]
	v_mfma_f32_16x16x32_bf16 v[36:39], v[144:147], v[172:175], v[36:39]
	v_mfma_f32_16x16x32_bf16 v[32:35], v[152:155], v[172:175], v[32:35]
	v_mfma_f32_16x16x32_bf16 v[20:23], v[144:147], v[180:183], v[20:23]
	v_mfma_f32_16x16x32_bf16 v[16:19], v[152:155], v[180:183], v[16:19]
	v_mfma_f32_16x16x32_bf16 v[4:7], v[144:147], v[188:191], v[4:7]
	v_mfma_f32_16x16x32_bf16 v[0:3], v[152:155], v[188:191], v[0:3]
	v_mfma_f32_16x16x32_bf16 v[52:55], v[148:151], v[168:171], v[52:55]
	v_mfma_f32_16x16x32_bf16 v[48:51], v[160:163], v[168:171], v[48:51]
	v_mfma_f32_16x16x32_bf16 v[36:39], v[148:151], v[176:179], v[36:39]
	v_mfma_f32_16x16x32_bf16 v[32:35], v[160:163], v[176:179], v[32:35]
	v_mfma_f32_16x16x32_bf16 v[20:23], v[148:151], v[184:187], v[20:23]
	v_mfma_f32_16x16x32_bf16 v[16:19], v[160:163], v[184:187], v[16:19]
	v_mfma_f32_16x16x32_bf16 v[4:7], v[148:151], v[194:197], v[4:7]
	v_mfma_f32_16x16x32_bf16 v[0:3], v[160:163], v[194:197], v[0:3]
	s_setprio 0
	s_barrier
	s_add_u32 s85, s85, 0x100
	s_addc_u32 vcc_lo, vcc_lo, 0
	s_add_u32 vcc_hi, vcc_hi, 0x100
	s_addc_u32 s79, s79, 0
	s_add_u32 s28, s28, 0x100
	s_addc_u32 s29, s29, 0
	s_cmp_ge_i32 s62, s40
	s_mov_b32 s30, s62
	s_cbranch_scc0 .LBB0_343
	s_mov_b32 s79, 0xc00000
	s_and_b64 vcc, exec, s[18:19]
	s_cbranch_vccz .LBB0_346

; #define PG8_STAGE(bufoff, gbase, voff) do { _Pragma("unroll") for (int _i = 0; _i < 2; ++_i) \
;         asm volatile("s_mov_b32 m0, %0\n\ts_nop 0\n\tglobal_load_lds_dwordx4 %1, %2" :: "s"(ldsb + (unsigned)((bufoff) + _i * 8192)), "v"((voff)[_i]), "s"(gbase) : "m0", "memory"); } while (0)
; #define PG8_WAIT_V(n) asm volatile("s_waitcnt vmcnt(" #n ")" ::: "memory")
; #define PG8_BAR __builtin_amdgcn_s_barrier()
; template <class Epi, class Sched, bool ALIGN_EPI = false, bool SP2 = false>
; __device__ __forceinline__ void gemm_phase(PG8_LAS unsigned char* lds, const Gemm g, const Sched& S, const Epi& E, const int wv) {
;     ...
;     for (int i = 0; i < 2; ++i) { int R, C; stage_rc(tid * 16 + i * 8192, R, C); const int Rb = Epi::PERM ? ((R & ~31) + perm32(R & 31)) : R;
;         voffA[i] = (unsigned)(R * K + C) * 2u; voffB[i] = (unsigned)(Rb * Kb + C) * 2u; }
;     const size_t kstep = (size_t)(BK * 2);
;     const size_t hstepA = (size_t)HALF * K * 2, hstepB = (size_t)HALF * Kb * 2;
;     const size_t tstepA = 2 * hstepA, tstepB = 2 * hstepB;
;     const unsigned ldsw = (unsigned)wid * 1024u;
;     const unsigned ldsb = (unsigned)(size_t)lds + ldsw;
;     const int aoff = lds_byte(wr * 64 + fr, fq * 8), boff = lds_byte(wc * 32 + fr, fq * 8);
;     ...
;     if constexpr (SP2) {
;         PG8_STAGE(PG8_SB(0, 0), cB, voffB); PG8_STAGE(PG8_SB(0, 1), cB + hstepB, voffB); PG8_STAGE(PG8_SA(0, 0), cA, voffA); PG8_STAGE(PG8_SA(0, 1), cA + hstepA, voffA);
;         if (wr == 1) PG8_BAR;
;         PG8_WAIT_V(2); PG8_BAR;
;         PG8_STAGE(PG8_SB(1, 0), cB + kstep, voffB); PG8_STAGE(PG8_SA(1, 0), cA + kstep, voffA); PG8_STAGE(PG8_SB(1, 1), cB + hstepB + kstep, voffB);
;         PG8_WAIT_V(6); PG8_BAR;
.LBB0_547:
	v_readlane_b32 s2, v254, 22
	s_bfe_u32 s85, s2, 0x80010
	s_bfe_u32 s40, s2, 0x40018
	s_add_u32 s8, s12, 0xd26f000
	s_addc_u32 s9, s13, 0
	s_add_u32 s10, s12, 0x43e000
	s_addc_u32 s11, s13, 0
	s_lshl_b64 s[16:17], s[42:43], 2
	s_add_u32 s2, s12, s16
	s_addc_u32 s16, s13, s17
	s_add_u32 s47, s2, 0xd4000
	s_addc_u32 s48, s16, 0
	v_bfe_u32 v1, v0, 4, 2
	s_add_u32 s12, s12, 0x3b98f000
	v_and_b32_e32 v157, 15, v0
	v_lshlrev_b32_e32 v2, 4, v1
	v_lshlrev_b32_e32 v3, 2, v0
	s_addc_u32 s13, s13, 0
	v_lshl_or_b32 v2, v157, 6, v2
	s_lshl_b32 s2, s15, 13
	v_and_b32_e32 v3, 32, v3
	v_bitop3_b32 v4, v2, s2, v3 bitop3:0xde
	s_lshl_b32 s2, s14, 5
	s_and_b32 s50, s2, 0x60
	s_lshl_b32 s49, s15, 6
	s_lshl_b32 s2, s50, 7
	s_add_i32 s51, s33, 0x18000
	s_add_u32 s16, s24, 0x80
	s_waitcnt vmcnt(2)
	s_barrier
	s_addc_u32 s17, s25, 0
	s_mov_b32 m0, s51
	s_nop 0
	global_load_lds_dwordx4 v151, s[16:17]
	s_add_i32 s52, s33, 0x1a000
	s_add_i32 s53, s33, 0x8000
	s_mov_b32 m0, s52
	s_nop 0
	global_load_lds_dwordx4 v155, s[16:17]
	s_add_u32 s16, s26, 0x80
	s_addc_u32 s17, s27, 0
	s_mov_b32 m0, s53
	s_nop 0
	global_load_lds_dwordx4 v147, s[16:17]
	s_add_i32 s54, s33, 0xa000
	s_add_i32 s55, s33, 0x1c000
	s_mov_b32 m0, s54
	s_nop 0
	global_load_lds_dwordx4 v153, s[16:17]
	s_add_u32 s16, s24, 0x80080
	s_addc_u32 s17, s25, 0
	s_add_i32 s56, s33, 0x1e000
	s_add_i32 s57, s33, 0xc000
	s_mov_b32 m0, s55
	s_nop 0
	global_load_lds_dwordx4 v151, s[16:17]
	s_cmp_lt_u32 s14, 4
	v_bitop3_b32 v2, v2, s2, v3 bitop3:0xde
	s_mov_b32 m0, s56
	s_nop 0
	global_load_lds_dwordx4 v155, s[16:17]
	s_cselect_b64 s[14:15], -1, 0
	s_ashr_i32 s2, s49, 31
	s_waitcnt vmcnt(6)
	v_mov_b32_e32 v145, s2
	s_mov_b32 s2, s18
	v_lshl_or_b32 v159, v1, 3, s50
	v_and_b32_e32 v1, 3, v0
	v_bfe_u32 v161, v0, 2, 4
	v_and_b32_e32 v0, 60, v0
	v_writelane_b32 v254, s2, 20
	v_lshl_or_b32 v165, v1, 6, v0
	v_or_b32_e32 v144, s49, v161
	v_lshlrev_b32_e32 v146, 3, v1
	s_add_i32 s58, s33, 0xe000
	s_ashr_i32 s60, s70, 31
	s_mov_b32 s65, 0
	v_add_u32_e32 v166, 0, v2
	v_add_u32_e32 v253, 0x10000, v166
	v_add_u32_e32 v252, 0x14000, v166
	v_add_u32_e32 v251, 0x18000, v166
	v_add_u32_e32 v250, 0x1c000, v166
	v_add_u32_e32 v167, 0, v4
	v_writelane_b32 v254, s3, 21
	s_mov_b32 s16, s18
	s_barrier
	s_branch .LBB0_550

; #define PG8_STAGE(bufoff, gbase, voff) do { _Pragma("unroll") for (int _i = 0; _i < 2; ++_i) \
;         asm volatile("s_mov_b32 m0, %0\n\ts_nop 0\n\tglobal_load_lds_dwordx4 %1, %2" :: "s"(ldsb + (unsigned)((bufoff) + _i * 8192)), "v"((voff)[_i]), "s"(gbase) : "m0", "memory"); } while (0)
; #define PG8_LDA(dst, b, h) do { _Pragma("unroll") for (int m = 0; m < 4; ++m) _Pragma("unroll") for (int k = 0; k < 2; ++k) dst[m][k] = *(const PG8_LAS bf16x8*)(lds + PG8_SA(b, h) + aoff + m * 2048 + k * 1024); } while (0)
; #define PG8_LDB(dst, b, h) do { _Pragma("unroll") for (int n = 0; n < 2; ++n) _Pragma("unroll") for (int k = 0; k < 2; ++k) dst[n][k] = *(const PG8_LAS bf16x8*)(lds + PG8_SB(b, h) + boff + n * 2048 + k * 1024); } while (0)
; #define PG8_MMA(ai, bj, At, Bt) do { __builtin_amdgcn_s_setprio(1); _Pragma("unroll") for (int m = 0; m < 4; ++m) _Pragma("unroll") for (int n = 0; n < 2; ++n) _Pragma("unroll") for (int k = 0; k < 2; ++k) \
;         acc[ai][bj][m][n] = __builtin_amdgcn_mfma_f32_16x16x32_bf16(Bt[n][k], At[m][k], acc[ai][bj][m][n], 0, 0, 0); __builtin_amdgcn_s_setprio(0); } while (0)
; #define PG8_WAIT_V(n) asm volatile("s_waitcnt vmcnt(" #n ")" ::: "memory")
; template <class Epi, class Sched, bool ALIGN_EPI = false, bool SP2 = false>
; __device__ __forceinline__ void gemm_phase(PG8_LAS unsigned char* lds, const Gemm g, const Sched& S, const Epi& E, const int wv) {
;     ...
;         for (int t = 0; t < nt; t += 2) {
;             const bool last = (t == nt - 2);
;             const char* a1 = cA + (size_t)(t + 1) * kstep;
;             const char* a2 = last ? nA : cA + (size_t)(t + 2) * kstep; const char* b2 = last ? nB : cB + (size_t)(t + 2) * kstep;
;             const char* a3 = a2 + kstep; const char* b3 = b2 + kstep;
;             if (last && has_next) S.a_ready(nxt);
;             if constexpr (SP2) {
;             PG8_LDB(B0, 0, 0); PG8_LDB(B1, 0, 1); PG8_SCHED; PG8_LDA(At, 0, 0); PG8_STAGE(PG8_SA(1, 1), a1 + hstepA, voffA);
;             PG8_WAIT_V(8); PG8_WAIT_L(0); PG8_BAR; PG8_MMA(0, 0, At, B0); PG8_MMA(0, 1, At, B1); PG8_BAR; PG8_SCHED;
;             PG8_LDA(At, 0, 1); PG8_STAGE(PG8_SB(0, 0), b2, voffB); PG8_STAGE(PG8_SB(0, 1), b2 + hstepB, voffB); PG8_STAGE(PG8_SA(0, 0), a2, voffA);
;             PG8_WAIT_V(8); PG8_WAIT_L(0); PG8_BAR; PG8_MMA(1, 0, At, B0); PG8_MMA(1, 1, At, B1); PG8_BAR; PG8_SCHED;
.LBB0_563:
	ds_read_b128 v[128:131], v253
	ds_read_b128 v[132:135], v253 offset:1024
	ds_read_b128 v[136:139], v253 offset:2048
	ds_read_b128 v[140:143], v253 offset:3072
	ds_read_b128 v[168:171], v252
	ds_read_b128 v[172:175], v252 offset:1024
	ds_read_b128 v[176:179], v252 offset:2048
	ds_read_b128 v[180:183], v252 offset:3072
	s_add_i32 s92, s24, 2
	s_cmp_eq_u32 s62, s24
	s_cselect_b32 s28, s20, s79
	s_cselect_b32 s29, s21, s88
	s_cselect_b32 s26, s87, s89
	s_cselect_b32 s27, s86, s90
	s_add_u32 s24, s28, 0x80
	s_addc_u32 s25, s29, 0
	ds_read_b128 v[184:187], v167
	ds_read_b128 v[188:191], v167 offset:1024
	ds_read_b128 v[194:197], v167 offset:2048
	ds_read_b128 v[198:201], v167 offset:3072
	ds_read_b128 v[202:205], v167 offset:4096
	ds_read_b128 v[206:209], v167 offset:5120
	ds_read_b128 v[210:213], v167 offset:6144
	ds_read_b128 v[214:217], v167 offset:7168
	s_add_u32 s96, s79, 0x83f80
	s_addc_u32 s97, s88, 0
	s_mov_b32 m0, s57
	s_nop 0
	global_load_lds_dwordx4 v147, s[96:97]
	s_nop 0
	s_mov_b32 m0, s58
	s_nop 0
	global_load_lds_dwordx4 v153, s[96:97]
	s_waitcnt vmcnt(8) lgkmcnt(0)
	s_setprio 1
	s_barrier
	v_mfma_f32_16x16x32_bf16 v[124:127], v[128:131], v[184:187], v[124:127]
	v_mfma_f32_16x16x32_bf16 v[120:123], v[136:139], v[184:187], v[120:123]
	v_mfma_f32_16x16x32_bf16 v[108:111], v[128:131], v[194:197], v[108:111]
	v_mfma_f32_16x16x32_bf16 v[104:107], v[136:139], v[194:197], v[104:107]
	v_mfma_f32_16x16x32_bf16 v[92:95], v[128:131], v[202:205], v[92:95]
	v_mfma_f32_16x16x32_bf16 v[88:91], v[136:139], v[202:205], v[88:91]
	v_mfma_f32_16x16x32_bf16 v[76:79], v[128:131], v[210:213], v[76:79]
	v_mfma_f32_16x16x32_bf16 v[72:75], v[136:139], v[210:213], v[72:75]
	v_mfma_f32_16x16x32_bf16 v[124:127], v[132:135], v[188:191], v[124:127]
	v_mfma_f32_16x16x32_bf16 v[120:123], v[140:143], v[188:191], v[120:123]
	v_mfma_f32_16x16x32_bf16 v[108:111], v[132:135], v[198:201], v[108:111]
	v_mfma_f32_16x16x32_bf16 v[104:107], v[140:143], v[198:201], v[104:107]
	v_mfma_f32_16x16x32_bf16 v[92:95], v[132:135], v[206:209], v[92:95]
	v_mfma_f32_16x16x32_bf16 v[88:91], v[140:143], v[206:209], v[88:91]
	v_mfma_f32_16x16x32_bf16 v[76:79], v[132:135], v[214:217], v[76:79]
	v_mfma_f32_16x16x32_bf16 v[72:75], v[140:143], v[214:217], v[72:75]
	v_mfma_f32_16x16x32_bf16 v[116:119], v[168:171], v[184:187], v[116:119]
	v_mfma_f32_16x16x32_bf16 v[112:115], v[176:179], v[184:187], v[112:115]
	v_mfma_f32_16x16x32_bf16 v[100:103], v[168:171], v[194:197], v[100:103]
	v_mfma_f32_16x16x32_bf16 v[96:99], v[176:179], v[194:197], v[96:99]
	v_mfma_f32_16x16x32_bf16 v[84:87], v[168:171], v[202:205], v[84:87]
	v_mfma_f32_16x16x32_bf16 v[80:83], v[176:179], v[202:205], v[80:83]
	v_mfma_f32_16x16x32_bf16 v[68:71], v[168:171], v[210:213], v[68:71]
	v_mfma_f32_16x16x32_bf16 v[64:67], v[176:179], v[210:213], v[64:67]
	v_mfma_f32_16x16x32_bf16 v[116:119], v[172:175], v[188:191], v[116:119]
	v_mfma_f32_16x16x32_bf16 v[112:115], v[180:183], v[188:191], v[112:115]
	v_mfma_f32_16x16x32_bf16 v[100:103], v[172:175], v[198:201], v[100:103]
	v_mfma_f32_16x16x32_bf16 v[96:99], v[180:183], v[198:201], v[96:99]
	v_mfma_f32_16x16x32_bf16 v[84:87], v[172:175], v[206:209], v[84:87]
	v_mfma_f32_16x16x32_bf16 v[80:83], v[180:183], v[206:209], v[80:83]
	v_mfma_f32_16x16x32_bf16 v[68:71], v[172:175], v[214:217], v[68:71]
	v_mfma_f32_16x16x32_bf16 v[64:67], v[180:183], v[214:217], v[64:67]
	s_setprio 0
	s_barrier
	ds_read_b128 v[184:187], v167 offset:16384
	ds_read_b128 v[188:191], v167 offset:17408
	ds_read_b128 v[194:197], v167 offset:18432
	ds_read_b128 v[198:201], v167 offset:19456
	ds_read_b128 v[202:205], v167 offset:20480
	ds_read_b128 v[206:209], v167 offset:21504
	ds_read_b128 v[210:213], v167 offset:22528
	ds_read_b128 v[214:217], v167 offset:23552
	s_mov_b32 m0, s34
	s_nop 0
	global_load_lds_dwordx4 v151, s[26:27]
	s_add_u32 s96, s26, 0x80000
	s_mov_b32 m0, s35
	s_nop 0
	global_load_lds_dwordx4 v155, s[26:27]
	s_addc_u32 s97, s27, 0
	s_mov_b32 m0, s36
	s_nop 0
	global_load_lds_dwordx4 v151, s[96:97]
	s_nop 0
	s_mov_b32 m0, s37
	s_nop 0
	global_load_lds_dwordx4 v155, s[96:97]
	s_nop 0
	s_mov_b32 m0, s33
	s_nop 0
	global_load_lds_dwordx4 v147, s[28:29]
	s_nop 0
	s_mov_b32 m0, s44
	s_nop 0
	global_load_lds_dwordx4 v153, s[28:29]
	s_waitcnt vmcnt(8) lgkmcnt(0)
	s_setprio 1
	s_barrier
	v_mfma_f32_16x16x32_bf16 v[60:63], v[128:131], v[184:187], v[60:63]
	v_mfma_f32_16x16x32_bf16 v[56:59], v[136:139], v[184:187], v[56:59]
	v_mfma_f32_16x16x32_bf16 v[44:47], v[128:131], v[194:197], v[44:47]
	v_mfma_f32_16x16x32_bf16 v[40:43], v[136:139], v[194:197], v[40:43]
	v_mfma_f32_16x16x32_bf16 v[28:31], v[128:131], v[202:205], v[28:31]
	v_mfma_f32_16x16x32_bf16 v[24:27], v[136:139], v[202:205], v[24:27]
	v_mfma_f32_16x16x32_bf16 v[12:15], v[128:131], v[210:213], v[12:15]
	v_mfma_f32_16x16x32_bf16 v[8:11], v[136:139], v[210:213], v[8:11]
	v_mfma_f32_16x16x32_bf16 v[60:63], v[132:135], v[188:191], v[60:63]
	v_mfma_f32_16x16x32_bf16 v[56:59], v[140:143], v[188:191], v[56:59]
	v_mfma_f32_16x16x32_bf16 v[44:47], v[132:135], v[198:201], v[44:47]
	v_mfma_f32_16x16x32_bf16 v[40:43], v[140:143], v[198:201], v[40:43]
	v_mfma_f32_16x16x32_bf16 v[28:31], v[132:135], v[206:209], v[28:31]
	v_mfma_f32_16x16x32_bf16 v[24:27], v[140:143], v[206:209], v[24:27]
	v_mfma_f32_16x16x32_bf16 v[12:15], v[132:135], v[214:217], v[12:15]
	v_mfma_f32_16x16x32_bf16 v[8:11], v[140:143], v[214:217], v[8:11]
	v_mfma_f32_16x16x32_bf16 v[52:55], v[168:171], v[184:187], v[52:55]
	v_mfma_f32_16x16x32_bf16 v[48:51], v[176:179], v[184:187], v[48:51]
	v_mfma_f32_16x16x32_bf16 v[36:39], v[168:171], v[194:197], v[36:39]
	v_mfma_f32_16x16x32_bf16 v[32:35], v[176:179], v[194:197], v[32:35]
	v_mfma_f32_16x16x32_bf16 v[20:23], v[168:171], v[202:205], v[20:23]
	v_mfma_f32_16x16x32_bf16 v[16:19], v[176:179], v[202:205], v[16:19]
	v_mfma_f32_16x16x32_bf16 v[4:7], v[168:171], v[210:213], v[4:7]
	v_mfma_f32_16x16x32_bf16 v[0:3], v[176:179], v[210:213], v[0:3]
	v_mfma_f32_16x16x32_bf16 v[52:55], v[172:175], v[188:191], v[52:55]
	v_mfma_f32_16x16x32_bf16 v[48:51], v[180:183], v[188:191], v[48:51]
	v_mfma_f32_16x16x32_bf16 v[36:39], v[172:175], v[198:201], v[36:39]
	v_mfma_f32_16x16x32_bf16 v[32:35], v[180:183], v[198:201], v[32:35]
	v_mfma_f32_16x16x32_bf16 v[20:23], v[172:175], v[206:209], v[20:23]
	v_mfma_f32_16x16x32_bf16 v[16:19], v[180:183], v[206:209], v[16:19]
	v_mfma_f32_16x16x32_bf16 v[4:7], v[172:175], v[214:217], v[4:7]
	v_mfma_f32_16x16x32_bf16 v[0:3], v[180:183], v[214:217], v[0:3]
	s_setprio 0
	s_barrier
; #define PG8_STAGE(bufoff, gbase, voff) do { _Pragma("unroll") for (int _i = 0; _i < 2; ++_i) \
;         asm volatile("s_mov_b32 m0, %0\n\ts_nop 0\n\tglobal_load_lds_dwordx4 %1, %2" :: "s"(ldsb + (unsigned)((bufoff) + _i * 8192)), "v"((voff)[_i]), "s"(gbase) : "m0", "memory"); } while (0)
; #define PG8_LDA(dst, b, h) do { _Pragma("unroll") for (int m = 0; m < 4; ++m) _Pragma("unroll") for (int k = 0; k < 2; ++k) dst[m][k] = *(const PG8_LAS bf16x8*)(lds + PG8_SA(b, h) + aoff + m * 2048 + k * 1024); } while (0)
; #define PG8_LDB(dst, b, h) do { _Pragma("unroll") for (int n = 0; n < 2; ++n) _Pragma("unroll") for (int k = 0; k < 2; ++k) dst[n][k] = *(const PG8_LAS bf16x8*)(lds + PG8_SB(b, h) + boff + n * 2048 + k * 1024); } while (0)
; #define PG8_MMA(ai, bj, At, Bt) do { __builtin_amdgcn_s_setprio(1); _Pragma("unroll") for (int m = 0; m < 4; ++m) _Pragma("unroll") for (int n = 0; n < 2; ++n) _Pragma("unroll") for (int k = 0; k < 2; ++k) \
;         acc[ai][bj][m][n] = __builtin_amdgcn_mfma_f32_16x16x32_bf16(Bt[n][k], At[m][k], acc[ai][bj][m][n], 0, 0, 0); __builtin_amdgcn_s_setprio(0); } while (0)
; #define PG8_WAIT_V(n) asm volatile("s_waitcnt vmcnt(" #n ")" ::: "memory")
; #define PG8_WAIT_L(n) asm volatile("s_waitcnt lgkmcnt(" #n ")" ::: "memory")
; #define PG8_BAR __builtin_amdgcn_s_barrier()
; template <class Epi, class Sched, bool ALIGN_EPI = false, bool SP2 = false>
; __device__ __forceinline__ void gemm_phase(PG8_LAS unsigned char* lds, const Gemm g, const Sched& S, const Epi& E, const int wv) {
;     ...
;         for (int t = 0; t < nt; t += 2) {
;             const bool last = (t == nt - 2);
;             const char* a1 = cA + (size_t)(t + 1) * kstep;
;             const char* a2 = last ? nA : cA + (size_t)(t + 2) * kstep; const char* b2 = last ? nB : cB + (size_t)(t + 2) * kstep;
;             const char* a3 = a2 + kstep; const char* b3 = b2 + kstep;
;     ...
;             PG8_LDB(B0, 1, 0); PG8_LDB(B1, 1, 1); PG8_SCHED; PG8_LDA(At, 1, 0); PG8_STAGE(PG8_SA(0, 1), a2 + hstepA, voffA);
;             PG8_WAIT_V(8); PG8_WAIT_L(0); PG8_BAR; PG8_MMA(0, 0, At, B0); PG8_MMA(0, 1, At, B1); PG8_BAR; PG8_SCHED;
;             PG8_LDA(At, 1, 1); PG8_STAGE(PG8_SB(1, 0), b3, voffB); PG8_STAGE(PG8_SB(1, 1), b3 + hstepB, voffB); PG8_STAGE(PG8_SA(1, 0), a3, voffA);
;             PG8_WAIT_V(8); PG8_WAIT_L(0); PG8_BAR; PG8_MMA(1, 0, At, B0); PG8_MMA(1, 1, At, B1); PG8_BAR; PG8_SCHED;
	ds_read_b128 v[128:131], v251
	ds_read_b128 v[132:135], v251 offset:1024
	ds_read_b128 v[136:139], v251 offset:2048
	ds_read_b128 v[140:143], v251 offset:3072
	ds_read_b128 v[168:171], v250
	ds_read_b128 v[172:175], v250 offset:1024
	ds_read_b128 v[176:179], v250 offset:2048
	ds_read_b128 v[180:183], v250 offset:3072
	ds_read_b128 v[184:187], v167 offset:32768
	ds_read_b128 v[188:191], v167 offset:33792
	ds_read_b128 v[194:197], v167 offset:34816
	ds_read_b128 v[198:201], v167 offset:35840
	ds_read_b128 v[202:205], v167 offset:36864
	ds_read_b128 v[206:209], v167 offset:37888
	ds_read_b128 v[210:213], v167 offset:38912
	ds_read_b128 v[214:217], v167 offset:39936
	s_add_u32 s28, s28, 0x84000
	s_addc_u32 s29, s29, 0
	s_mov_b32 m0, s45
	s_nop 0
	global_load_lds_dwordx4 v147, s[28:29]
	s_nop 0
	s_mov_b32 m0, s46
	s_nop 0
	global_load_lds_dwordx4 v153, s[28:29]
	s_waitcnt vmcnt(8) lgkmcnt(0)
	s_setprio 1
	s_barrier
	v_mfma_f32_16x16x32_bf16 v[124:127], v[128:131], v[184:187], v[124:127]
	v_mfma_f32_16x16x32_bf16 v[120:123], v[136:139], v[184:187], v[120:123]
	v_mfma_f32_16x16x32_bf16 v[108:111], v[128:131], v[194:197], v[108:111]
	v_mfma_f32_16x16x32_bf16 v[104:107], v[136:139], v[194:197], v[104:107]
	v_mfma_f32_16x16x32_bf16 v[92:95], v[128:131], v[202:205], v[92:95]
	v_mfma_f32_16x16x32_bf16 v[88:91], v[136:139], v[202:205], v[88:91]
	v_mfma_f32_16x16x32_bf16 v[76:79], v[128:131], v[210:213], v[76:79]
	v_mfma_f32_16x16x32_bf16 v[72:75], v[136:139], v[210:213], v[72:75]
	v_mfma_f32_16x16x32_bf16 v[124:127], v[132:135], v[188:191], v[124:127]
	v_mfma_f32_16x16x32_bf16 v[120:123], v[140:143], v[188:191], v[120:123]
	v_mfma_f32_16x16x32_bf16 v[108:111], v[132:135], v[198:201], v[108:111]
	v_mfma_f32_16x16x32_bf16 v[104:107], v[140:143], v[198:201], v[104:107]
	v_mfma_f32_16x16x32_bf16 v[92:95], v[132:135], v[206:209], v[92:95]
	v_mfma_f32_16x16x32_bf16 v[88:91], v[140:143], v[206:209], v[88:91]
	v_mfma_f32_16x16x32_bf16 v[76:79], v[132:135], v[214:217], v[76:79]
	v_mfma_f32_16x16x32_bf16 v[72:75], v[140:143], v[214:217], v[72:75]
	v_mfma_f32_16x16x32_bf16 v[116:119], v[168:171], v[184:187], v[116:119]
	v_mfma_f32_16x16x32_bf16 v[112:115], v[176:179], v[184:187], v[112:115]
	v_mfma_f32_16x16x32_bf16 v[100:103], v[168:171], v[194:197], v[100:103]
	v_mfma_f32_16x16x32_bf16 v[96:99], v[176:179], v[194:197], v[96:99]
	v_mfma_f32_16x16x32_bf16 v[84:87], v[168:171], v[202:205], v[84:87]
	v_mfma_f32_16x16x32_bf16 v[80:83], v[176:179], v[202:205], v[80:83]
	v_mfma_f32_16x16x32_bf16 v[68:71], v[168:171], v[210:213], v[68:71]
	v_mfma_f32_16x16x32_bf16 v[64:67], v[176:179], v[210:213], v[64:67]
	v_mfma_f32_16x16x32_bf16 v[116:119], v[172:175], v[188:191], v[116:119]
	v_mfma_f32_16x16x32_bf16 v[112:115], v[180:183], v[188:191], v[112:115]
	v_mfma_f32_16x16x32_bf16 v[100:103], v[172:175], v[198:201], v[100:103]
	v_mfma_f32_16x16x32_bf16 v[96:99], v[180:183], v[198:201], v[96:99]
	v_mfma_f32_16x16x32_bf16 v[84:87], v[172:175], v[206:209], v[84:87]
	v_mfma_f32_16x16x32_bf16 v[80:83], v[180:183], v[206:209], v[80:83]
	v_mfma_f32_16x16x32_bf16 v[68:71], v[172:175], v[214:217], v[68:71]
	v_mfma_f32_16x16x32_bf16 v[64:67], v[180:183], v[214:217], v[64:67]
	s_setprio 0
	s_barrier
	ds_read_b128 v[184:187], v167 offset:49152
	ds_read_b128 v[188:191], v167 offset:50176
	ds_read_b128 v[194:197], v167 offset:51200
	ds_read_b128 v[198:201], v167 offset:52224
	ds_read_b128 v[202:205], v167 offset:53248
	ds_read_b128 v[206:209], v167 offset:54272
	ds_read_b128 v[210:213], v167 offset:55296
	ds_read_b128 v[214:217], v167 offset:56320
	s_add_u32 s28, s26, 0x80
	s_addc_u32 s29, s27, 0
	s_mov_b32 m0, s51
	s_nop 0
	global_load_lds_dwordx4 v151, s[28:29]
	s_add_u32 s26, s26, 0x80080
	s_mov_b32 m0, s52
	s_nop 0
	global_load_lds_dwordx4 v155, s[28:29]
	s_addc_u32 s27, s27, 0
	s_mov_b32 m0, s55
	s_nop 0
	global_load_lds_dwordx4 v151, s[26:27]
	s_nop 0
	s_mov_b32 m0, s56
	s_nop 0
	global_load_lds_dwordx4 v155, s[26:27]
	s_nop 0
	s_mov_b32 m0, s53
	s_nop 0
	global_load_lds_dwordx4 v147, s[24:25]
	s_nop 0
	s_mov_b32 m0, s54
	s_nop 0
	global_load_lds_dwordx4 v153, s[24:25]
	s_waitcnt vmcnt(8) lgkmcnt(0)
	s_setprio 1
	s_barrier
	v_mfma_f32_16x16x32_bf16 v[60:63], v[128:131], v[184:187], v[60:63]
	v_mfma_f32_16x16x32_bf16 v[56:59], v[136:139], v[184:187], v[56:59]
	v_mfma_f32_16x16x32_bf16 v[44:47], v[128:131], v[194:197], v[44:47]
	v_mfma_f32_16x16x32_bf16 v[40:43], v[136:139], v[194:197], v[40:43]
	v_mfma_f32_16x16x32_bf16 v[28:31], v[128:131], v[202:205], v[28:31]
	v_mfma_f32_16x16x32_bf16 v[24:27], v[136:139], v[202:205], v[24:27]
	v_mfma_f32_16x16x32_bf16 v[12:15], v[128:131], v[210:213], v[12:15]
	v_mfma_f32_16x16x32_bf16 v[8:11], v[136:139], v[210:213], v[8:11]
	v_mfma_f32_16x16x32_bf16 v[60:63], v[132:135], v[188:191], v[60:63]
	v_mfma_f32_16x16x32_bf16 v[56:59], v[140:143], v[188:191], v[56:59]
	v_mfma_f32_16x16x32_bf16 v[44:47], v[132:135], v[198:201], v[44:47]
	v_mfma_f32_16x16x32_bf16 v[40:43], v[140:143], v[198:201], v[40:43]
	v_mfma_f32_16x16x32_bf16 v[28:31], v[132:135], v[206:209], v[28:31]
	v_mfma_f32_16x16x32_bf16 v[24:27], v[140:143], v[206:209], v[24:27]
	v_mfma_f32_16x16x32_bf16 v[12:15], v[132:135], v[214:217], v[12:15]
	v_mfma_f32_16x16x32_bf16 v[8:11], v[140:143], v[214:217], v[8:11]
	v_mfma_f32_16x16x32_bf16 v[52:55], v[168:171], v[184:187], v[52:55]
	v_mfma_f32_16x16x32_bf16 v[48:51], v[176:179], v[184:187], v[48:51]
	v_mfma_f32_16x16x32_bf16 v[36:39], v[168:171], v[194:197], v[36:39]
	v_mfma_f32_16x16x32_bf16 v[32:35], v[176:179], v[194:197], v[32:35]
	v_mfma_f32_16x16x32_bf16 v[20:23], v[168:171], v[202:205], v[20:23]
	v_mfma_f32_16x16x32_bf16 v[16:19], v[176:179], v[202:205], v[16:19]
	v_mfma_f32_16x16x32_bf16 v[4:7], v[168:171], v[210:213], v[4:7]
	v_mfma_f32_16x16x32_bf16 v[0:3], v[176:179], v[210:213], v[0:3]
	v_mfma_f32_16x16x32_bf16 v[52:55], v[172:175], v[188:191], v[52:55]
	v_mfma_f32_16x16x32_bf16 v[48:51], v[180:183], v[188:191], v[48:51]
	v_mfma_f32_16x16x32_bf16 v[36:39], v[172:175], v[198:201], v[36:39]
	v_mfma_f32_16x16x32_bf16 v[32:35], v[180:183], v[198:201], v[32:35]
	v_mfma_f32_16x16x32_bf16 v[20:23], v[172:175], v[206:209], v[20:23]
	v_mfma_f32_16x16x32_bf16 v[16:19], v[180:183], v[206:209], v[16:19]
	v_mfma_f32_16x16x32_bf16 v[4:7], v[172:175], v[214:217], v[4:7]
	v_mfma_f32_16x16x32_bf16 v[0:3], v[180:183], v[214:217], v[0:3]
	s_setprio 0
	s_barrier
	s_add_u32 s79, s79, 0x100
	s_addc_u32 s88, s88, 0
	s_add_u32 s89, s89, 0x100
	s_addc_u32 s90, s90, 0
	s_cmp_ge_i32 s92, s85
	s_mov_b32 s24, s92
	s_cbranch_scc0 .LBB0_563
	v_readlane_b32 s96, v254, 47
	v_readlane_b32 s97, v254, 48
	v_readlane_b32 s90, v254, 52
	s_mov_b32 s79, 0xc00000
	s_branch .LBB0_566

; #define PG8_STAGE(bufoff, gbase, voff) do { _Pragma("unroll") for (int _i = 0; _i < 2; ++_i) \
;         asm volatile("s_mov_b32 m0, %0\n\ts_nop 0\n\tglobal_load_lds_dwordx4 %1, %2" :: "s"(ldsb + (unsigned)((bufoff) + _i * 8192)), "v"((voff)[_i]), "s"(gbase) : "m0", "memory"); } while (0)
; #define PG8_WAIT_V(n) asm volatile("s_waitcnt vmcnt(" #n ")" ::: "memory")
; #define PG8_BAR __builtin_amdgcn_s_barrier()
; template <class Epi, class Sched, bool ALIGN_EPI = false, bool SP2 = false>
; __device__ __forceinline__ void gemm_phase(PG8_LAS unsigned char* lds, const Gemm g, const Sched& S, const Epi& E, const int wv) {
;     ...
;     for (int i = 0; i < 2; ++i) { int R, C; stage_rc(tid * 16 + i * 8192, R, C); const int Rb = Epi::PERM ? ((R & ~31) + perm32(R & 31)) : R;
;         voffA[i] = (unsigned)(R * K + C) * 2u; voffB[i] = (unsigned)(Rb * Kb + C) * 2u; }
;     const size_t kstep = (size_t)(BK * 2);
;     const size_t hstepA = (size_t)HALF * K * 2, hstepB = (size_t)HALF * Kb * 2;
;     const size_t tstepA = 2 * hstepA, tstepB = 2 * hstepB;
;     const unsigned ldsw = (unsigned)wid * 1024u;
;     const unsigned ldsb = (unsigned)(size_t)lds + ldsw;
;     const int aoff = lds_byte(wr * 64 + fr, fq * 8), boff = lds_byte(wc * 32 + fr, fq * 8);
;     ...
;     if constexpr (SP2) {
;         PG8_STAGE(PG8_SB(0, 0), cB, voffB); PG8_STAGE(PG8_SB(0, 1), cB + hstepB, voffB); PG8_STAGE(PG8_SA(0, 0), cA, voffA); PG8_STAGE(PG8_SA(0, 1), cA + hstepA, voffA);
;         if (wr == 1) PG8_BAR;
;         PG8_WAIT_V(2); PG8_BAR;
;         PG8_STAGE(PG8_SB(1, 0), cB + kstep, voffB); PG8_STAGE(PG8_SA(1, 0), cA + kstep, voffA); PG8_STAGE(PG8_SB(1, 1), cB + hstepB + kstep, voffB);
;         PG8_WAIT_V(6); PG8_BAR;
.LBB0_743:
	s_bfe_u32 s40, s5, 0x80010
	s_add_u32 s8, s12, 0x1d16f000
	s_addc_u32 s9, s13, 0
	s_add_u32 s10, s12, 0x14000
	s_addc_u32 s11, s13, 0
	v_bfe_u32 v2, v0, 4, 2
	s_add_u32 s12, s12, 0x15000
	v_and_b32_e32 v1, 15, v0
	v_lshlrev_b32_e32 v3, 4, v2
	v_lshlrev_b32_e32 v4, 2, v0
	s_addc_u32 s13, s13, 0
	v_lshl_or_b32 v3, v1, 6, v3
	s_lshl_b32 s2, s14, 13
	v_and_b32_e32 v4, 32, v4
	v_bitop3_b32 v5, v3, s2, v4 bitop3:0xde
	s_lshl_b32 s2, s4, 5
	s_and_b32 s2, s2, 0x60
	s_lshl_b32 s48, s14, 6
	s_lshl_b32 s5, s2, 7
	s_add_i32 s49, s36, 0x18000
	s_add_u32 s14, s24, 0x80
	s_waitcnt vmcnt(2)
	s_barrier
	s_addc_u32 s15, s25, 0
	s_mov_b32 m0, s49
	s_nop 0
	global_load_lds_dwordx4 v129, s[14:15]
	s_add_i32 s50, s36, 0x1a000
	s_add_i32 s51, s36, 0x8000
	s_mov_b32 m0, s50
	s_nop 0
	global_load_lds_dwordx4 v131, s[14:15]
	s_add_u32 s14, s26, 0x80
	s_addc_u32 s15, s27, 0
	s_mov_b32 m0, s51
	s_nop 0
	global_load_lds_dwordx4 v128, s[14:15]
	s_add_i32 s52, s36, 0xa000
	s_add_i32 s53, s36, 0x1c000
	s_mov_b32 m0, s52
	s_nop 0
	global_load_lds_dwordx4 v130, s[14:15]
	s_add_u32 s14, s24, 0x20080
	s_addc_u32 s15, s25, 0
	s_mov_b32 m0, s53
	s_nop 0
	global_load_lds_dwordx4 v129, s[14:15]
	s_add_i32 s54, s36, 0x1e000
	s_mov_b32 m0, s54
	s_nop 0
	global_load_lds_dwordx4 v131, s[14:15]
	s_waitcnt vmcnt(6)
	v_lshl_or_b32 v132, v2, 3, s2
	s_add_i32 s55, s36, 0xc000
	v_and_b32_e32 v2, 3, v0
	v_bfe_u32 v133, v0, 2, 4
	v_and_b32_e32 v0, 60, v0
	v_bitop3_b32 v3, v3, s5, v4 bitop3:0xde
	s_cmp_lt_u32 s4, 4
	v_lshl_or_b32 v134, v2, 6, v0
	v_lshlrev_b32_e32 v0, 3, v2
	v_lshlrev_b32_e32 v1, 4, v1
	s_cselect_b64 s[14:15], -1, 0
	v_add_u32_e32 v135, -16, v1
	v_add_u32_e32 v136, 0xf0, v1
	v_add_u32_e32 v137, 0x1f0, v1
	v_add_u32_e32 v138, 0x2f0, v1
	s_add_i32 s87, s36, 0xe000
	s_ashr_i32 s4, s70, 31
	s_mov_b32 s5, 0
	v_add_u32_e32 v139, 0, v3
	v_add_u32_e32 v253, 0x10000, v139
	v_add_u32_e32 v252, 0x14000, v139
	v_add_u32_e32 v251, 0x18000, v139
	v_add_u32_e32 v250, 0x1c000, v139
	v_add_u32_e32 v140, 0, v5
	s_lshl_b32 s16, s2, 1
	v_lshlrev_b32_e32 v192, 1, v0
	s_barrier
	s_branch .LBB0_746

; #define PG8_STAGE(bufoff, gbase, voff) do { _Pragma("unroll") for (int _i = 0; _i < 2; ++_i) \
;         asm volatile("s_mov_b32 m0, %0\n\ts_nop 0\n\tglobal_load_lds_dwordx4 %1, %2" :: "s"(ldsb + (unsigned)((bufoff) + _i * 8192)), "v"((voff)[_i]), "s"(gbase) : "m0", "memory"); } while (0)
; #define PG8_LDA(dst, b, h) do { _Pragma("unroll") for (int m = 0; m < 4; ++m) _Pragma("unroll") for (int k = 0; k < 2; ++k) dst[m][k] = *(const PG8_LAS bf16x8*)(lds + PG8_SA(b, h) + aoff + m * 2048 + k * 1024); } while (0)
; #define PG8_LDB(dst, b, h) do { _Pragma("unroll") for (int n = 0; n < 2; ++n) _Pragma("unroll") for (int k = 0; k < 2; ++k) dst[n][k] = *(const PG8_LAS bf16x8*)(lds + PG8_SB(b, h) + boff + n * 2048 + k * 1024); } while (0)
; #define PG8_MMA(ai, bj, At, Bt) do { __builtin_amdgcn_s_setprio(1); _Pragma("unroll") for (int m = 0; m < 4; ++m) _Pragma("unroll") for (int n = 0; n < 2; ++n) _Pragma("unroll") for (int k = 0; k < 2; ++k) \
;         acc[ai][bj][m][n] = __builtin_amdgcn_mfma_f32_16x16x32_bf16(Bt[n][k], At[m][k], acc[ai][bj][m][n], 0, 0, 0); __builtin_amdgcn_s_setprio(0); } while (0)
; #define PG8_WAIT_V(n) asm volatile("s_waitcnt vmcnt(" #n ")" ::: "memory")
; template <class Epi, class Sched, bool ALIGN_EPI = false, bool SP2 = false>
; __device__ __forceinline__ void gemm_phase(PG8_LAS unsigned char* lds, const Gemm g, const Sched& S, const Epi& E, const int wv) {
;     ...
;         for (int t = 0; t < nt; t += 2) {
;             const bool last = (t == nt - 2);
;             const char* a1 = cA + (size_t)(t + 1) * kstep;
;             const char* a2 = last ? nA : cA + (size_t)(t + 2) * kstep; const char* b2 = last ? nB : cB + (size_t)(t + 2) * kstep;
;             const char* a3 = a2 + kstep; const char* b3 = b2 + kstep;
;             if (last && has_next) S.a_ready(nxt);
;             if constexpr (SP2) {
;             PG8_LDB(B0, 0, 0); PG8_LDB(B1, 0, 1); PG8_SCHED; PG8_LDA(At, 0, 0); PG8_STAGE(PG8_SA(1, 1), a1 + hstepA, voffA);
;             PG8_WAIT_V(8); PG8_WAIT_L(0); PG8_BAR; PG8_MMA(0, 0, At, B0); PG8_MMA(0, 1, At, B1); PG8_BAR; PG8_SCHED;
;             PG8_LDA(At, 0, 1); PG8_STAGE(PG8_SB(0, 0), b2, voffB); PG8_STAGE(PG8_SB(0, 1), b2 + hstepB, voffB); PG8_STAGE(PG8_SA(0, 0), a2, voffA);
;             PG8_WAIT_V(8); PG8_WAIT_L(0); PG8_BAR; PG8_MMA(1, 0, At, B0); PG8_MMA(1, 1, At, B1); PG8_BAR; PG8_SCHED;
.LBB0_756:
	ds_read_b128 v[142:145], v253
	ds_read_b128 v[146:149], v253 offset:1024
	ds_read_b128 v[150:153], v253 offset:2048
	ds_read_b128 v[154:157], v253 offset:3072
	ds_read_b128 v[158:161], v252
	ds_read_b128 v[162:165], v252 offset:1024
	ds_read_b128 v[166:169], v252 offset:2048
	ds_read_b128 v[170:173], v252 offset:3072
	s_add_i32 s79, s24, 2
	s_cmp_eq_u32 s60, s24
	s_cselect_b32 s28, s18, s62
	s_cselect_b32 s29, s19, s65
	s_cselect_b32 s26, s58, s71
	s_cselect_b32 s27, s56, s77
	s_add_u32 s24, s28, 0x80
	s_addc_u32 s25, s29, 0
	ds_read_b128 v[174:177], v140
	ds_read_b128 v[178:181], v140 offset:1024
	ds_read_b128 v[182:185], v140 offset:2048
	ds_read_b128 v[186:189], v140 offset:3072
	ds_read_b128 v[194:197], v140 offset:4096
	ds_read_b128 v[198:201], v140 offset:5120
	ds_read_b128 v[202:205], v140 offset:6144
	ds_read_b128 v[206:209], v140 offset:7168
	s_add_u32 s88, s62, 0x1ff80
	s_addc_u32 s89, s65, 0
	s_mov_b32 m0, s55
	s_nop 0
	global_load_lds_dwordx4 v128, s[88:89]
	s_nop 0
	s_mov_b32 m0, s87
	s_nop 0
	global_load_lds_dwordx4 v130, s[88:89]
	s_waitcnt vmcnt(8) lgkmcnt(0)
	s_setprio 1
	s_barrier
	v_mfma_f32_16x16x32_bf16 v[124:127], v[142:145], v[174:177], v[124:127]
	v_mfma_f32_16x16x32_bf16 v[120:123], v[150:153], v[174:177], v[120:123]
	v_mfma_f32_16x16x32_bf16 v[116:119], v[142:145], v[182:185], v[116:119]
	v_mfma_f32_16x16x32_bf16 v[112:115], v[150:153], v[182:185], v[112:115]
	v_mfma_f32_16x16x32_bf16 v[108:111], v[142:145], v[194:197], v[108:111]
	v_mfma_f32_16x16x32_bf16 v[104:107], v[150:153], v[194:197], v[104:107]
	v_mfma_f32_16x16x32_bf16 v[100:103], v[142:145], v[202:205], v[100:103]
	v_mfma_f32_16x16x32_bf16 v[96:99], v[150:153], v[202:205], v[96:99]
	v_mfma_f32_16x16x32_bf16 v[124:127], v[146:149], v[178:181], v[124:127]
	v_mfma_f32_16x16x32_bf16 v[120:123], v[154:157], v[178:181], v[120:123]
	v_mfma_f32_16x16x32_bf16 v[116:119], v[146:149], v[186:189], v[116:119]
	v_mfma_f32_16x16x32_bf16 v[112:115], v[154:157], v[186:189], v[112:115]
	v_mfma_f32_16x16x32_bf16 v[108:111], v[146:149], v[198:201], v[108:111]
	v_mfma_f32_16x16x32_bf16 v[104:107], v[154:157], v[198:201], v[104:107]
	v_mfma_f32_16x16x32_bf16 v[100:103], v[146:149], v[206:209], v[100:103]
	v_mfma_f32_16x16x32_bf16 v[96:99], v[154:157], v[206:209], v[96:99]
	v_mfma_f32_16x16x32_bf16 v[60:63], v[158:161], v[174:177], v[60:63]
	v_mfma_f32_16x16x32_bf16 v[56:59], v[166:169], v[174:177], v[56:59]
	v_mfma_f32_16x16x32_bf16 v[52:55], v[158:161], v[182:185], v[52:55]
	v_mfma_f32_16x16x32_bf16 v[48:51], v[166:169], v[182:185], v[48:51]
	v_mfma_f32_16x16x32_bf16 v[44:47], v[158:161], v[194:197], v[44:47]
	v_mfma_f32_16x16x32_bf16 v[40:43], v[166:169], v[194:197], v[40:43]
	v_mfma_f32_16x16x32_bf16 v[36:39], v[158:161], v[202:205], v[36:39]
	v_mfma_f32_16x16x32_bf16 v[32:35], v[166:169], v[202:205], v[32:35]
	v_mfma_f32_16x16x32_bf16 v[60:63], v[162:165], v[178:181], v[60:63]
	v_mfma_f32_16x16x32_bf16 v[56:59], v[170:173], v[178:181], v[56:59]
	v_mfma_f32_16x16x32_bf16 v[52:55], v[162:165], v[186:189], v[52:55]
	v_mfma_f32_16x16x32_bf16 v[48:51], v[170:173], v[186:189], v[48:51]
	v_mfma_f32_16x16x32_bf16 v[44:47], v[162:165], v[198:201], v[44:47]
	v_mfma_f32_16x16x32_bf16 v[40:43], v[170:173], v[198:201], v[40:43]
	v_mfma_f32_16x16x32_bf16 v[36:39], v[162:165], v[206:209], v[36:39]
	v_mfma_f32_16x16x32_bf16 v[32:35], v[170:173], v[206:209], v[32:35]
	s_setprio 0
	s_barrier
	ds_read_b128 v[174:177], v140 offset:16384
	ds_read_b128 v[178:181], v140 offset:17408
	ds_read_b128 v[182:185], v140 offset:18432
	ds_read_b128 v[186:189], v140 offset:19456
	ds_read_b128 v[194:197], v140 offset:20480
	ds_read_b128 v[198:201], v140 offset:21504
	ds_read_b128 v[202:205], v140 offset:22528
	ds_read_b128 v[206:209], v140 offset:23552
	s_mov_b32 m0, s37
	s_nop 0
	global_load_lds_dwordx4 v129, s[26:27]
	s_add_u32 s88, s26, 0x20000
	s_mov_b32 m0, s42
	s_nop 0
	global_load_lds_dwordx4 v131, s[26:27]
	s_addc_u32 s89, s27, 0
	s_mov_b32 m0, s43
	s_nop 0
	global_load_lds_dwordx4 v129, s[88:89]
	s_nop 0
	s_mov_b32 m0, s44
	s_nop 0
	global_load_lds_dwordx4 v131, s[88:89]
	s_nop 0
	s_mov_b32 m0, s36
	s_nop 0
	global_load_lds_dwordx4 v128, s[28:29]
	s_nop 0
	s_mov_b32 m0, s45
	s_nop 0
	global_load_lds_dwordx4 v130, s[28:29]
	s_waitcnt vmcnt(8) lgkmcnt(0)
	s_setprio 1
	s_barrier
	v_mfma_f32_16x16x32_bf16 v[92:95], v[142:145], v[174:177], v[92:95]
	v_mfma_f32_16x16x32_bf16 v[88:91], v[150:153], v[174:177], v[88:91]
	v_mfma_f32_16x16x32_bf16 v[84:87], v[142:145], v[182:185], v[84:87]
	v_mfma_f32_16x16x32_bf16 v[80:83], v[150:153], v[182:185], v[80:83]
	v_mfma_f32_16x16x32_bf16 v[76:79], v[142:145], v[194:197], v[76:79]
	v_mfma_f32_16x16x32_bf16 v[72:75], v[150:153], v[194:197], v[72:75]
	v_mfma_f32_16x16x32_bf16 v[68:71], v[142:145], v[202:205], v[68:71]
	v_mfma_f32_16x16x32_bf16 v[64:67], v[150:153], v[202:205], v[64:67]
	v_mfma_f32_16x16x32_bf16 v[92:95], v[146:149], v[178:181], v[92:95]
	v_mfma_f32_16x16x32_bf16 v[88:91], v[154:157], v[178:181], v[88:91]
	v_mfma_f32_16x16x32_bf16 v[84:87], v[146:149], v[186:189], v[84:87]
	v_mfma_f32_16x16x32_bf16 v[80:83], v[154:157], v[186:189], v[80:83]
	v_mfma_f32_16x16x32_bf16 v[76:79], v[146:149], v[198:201], v[76:79]
	v_mfma_f32_16x16x32_bf16 v[72:75], v[154:157], v[198:201], v[72:75]
	v_mfma_f32_16x16x32_bf16 v[68:71], v[146:149], v[206:209], v[68:71]
	v_mfma_f32_16x16x32_bf16 v[64:67], v[154:157], v[206:209], v[64:67]
	v_mfma_f32_16x16x32_bf16 v[28:31], v[158:161], v[174:177], v[28:31]
	v_mfma_f32_16x16x32_bf16 v[24:27], v[166:169], v[174:177], v[24:27]
	v_mfma_f32_16x16x32_bf16 v[20:23], v[158:161], v[182:185], v[20:23]
	v_mfma_f32_16x16x32_bf16 v[16:19], v[166:169], v[182:185], v[16:19]
	v_mfma_f32_16x16x32_bf16 v[12:15], v[158:161], v[194:197], v[12:15]
	v_mfma_f32_16x16x32_bf16 v[8:11], v[166:169], v[194:197], v[8:11]
	v_mfma_f32_16x16x32_bf16 v[4:7], v[158:161], v[202:205], v[4:7]
	v_mfma_f32_16x16x32_bf16 v[0:3], v[166:169], v[202:205], v[0:3]
	v_mfma_f32_16x16x32_bf16 v[28:31], v[162:165], v[178:181], v[28:31]
	v_mfma_f32_16x16x32_bf16 v[24:27], v[170:173], v[178:181], v[24:27]
	v_mfma_f32_16x16x32_bf16 v[20:23], v[162:165], v[186:189], v[20:23]
	v_mfma_f32_16x16x32_bf16 v[16:19], v[170:173], v[186:189], v[16:19]
	v_mfma_f32_16x16x32_bf16 v[12:15], v[162:165], v[198:201], v[12:15]
	v_mfma_f32_16x16x32_bf16 v[8:11], v[170:173], v[198:201], v[8:11]
	v_mfma_f32_16x16x32_bf16 v[4:7], v[162:165], v[206:209], v[4:7]
	v_mfma_f32_16x16x32_bf16 v[0:3], v[170:173], v[206:209], v[0:3]
	s_setprio 0
	s_barrier
; #define PG8_STAGE(bufoff, gbase, voff) do { _Pragma("unroll") for (int _i = 0; _i < 2; ++_i) \
;         asm volatile("s_mov_b32 m0, %0\n\ts_nop 0\n\tglobal_load_lds_dwordx4 %1, %2" :: "s"(ldsb + (unsigned)((bufoff) + _i * 8192)), "v"((voff)[_i]), "s"(gbase) : "m0", "memory"); } while (0)
; #define PG8_LDA(dst, b, h) do { _Pragma("unroll") for (int m = 0; m < 4; ++m) _Pragma("unroll") for (int k = 0; k < 2; ++k) dst[m][k] = *(const PG8_LAS bf16x8*)(lds + PG8_SA(b, h) + aoff + m * 2048 + k * 1024); } while (0)
; #define PG8_LDB(dst, b, h) do { _Pragma("unroll") for (int n = 0; n < 2; ++n) _Pragma("unroll") for (int k = 0; k < 2; ++k) dst[n][k] = *(const PG8_LAS bf16x8*)(lds + PG8_SB(b, h) + boff + n * 2048 + k * 1024); } while (0)
; #define PG8_MMA(ai, bj, At, Bt) do { __builtin_amdgcn_s_setprio(1); _Pragma("unroll") for (int m = 0; m < 4; ++m) _Pragma("unroll") for (int n = 0; n < 2; ++n) _Pragma("unroll") for (int k = 0; k < 2; ++k) \
;         acc[ai][bj][m][n] = __builtin_amdgcn_mfma_f32_16x16x32_bf16(Bt[n][k], At[m][k], acc[ai][bj][m][n], 0, 0, 0); __builtin_amdgcn_s_setprio(0); } while (0)
; #define PG8_WAIT_V(n) asm volatile("s_waitcnt vmcnt(" #n ")" ::: "memory")
; #define PG8_WAIT_L(n) asm volatile("s_waitcnt lgkmcnt(" #n ")" ::: "memory")
; #define PG8_BAR __builtin_amdgcn_s_barrier()
; #define PG8_SCHED __builtin_amdgcn_sched_barrier(0)
; template <class Epi, class Sched, bool ALIGN_EPI = false, bool SP2 = false>
; __device__ __forceinline__ void gemm_phase(PG8_LAS unsigned char* lds, const Gemm g, const Sched& S, const Epi& E, const int wv) {
;     ...
;             PG8_LDB(B0, 1, 0); PG8_LDB(B1, 1, 1); PG8_SCHED; PG8_LDA(At, 1, 0); PG8_STAGE(PG8_SA(0, 1), a2 + hstepA, voffA);
;             PG8_WAIT_V(8); PG8_WAIT_L(0); PG8_BAR; PG8_MMA(0, 0, At, B0); PG8_MMA(0, 1, At, B1); PG8_BAR; PG8_SCHED;
;             PG8_LDA(At, 1, 1); PG8_STAGE(PG8_SB(1, 0), b3, voffB); PG8_STAGE(PG8_SB(1, 1), b3 + hstepB, voffB); PG8_STAGE(PG8_SA(1, 0), a3, voffA);
;             PG8_WAIT_V(8); PG8_WAIT_L(0); PG8_BAR; PG8_MMA(1, 0, At, B0); PG8_MMA(1, 1, At, B1); PG8_BAR; PG8_SCHED;
	ds_read_b128 v[142:145], v251
	ds_read_b128 v[146:149], v251 offset:1024
	ds_read_b128 v[150:153], v251 offset:2048
	ds_read_b128 v[154:157], v251 offset:3072
	ds_read_b128 v[158:161], v250
	ds_read_b128 v[162:165], v250 offset:1024
	ds_read_b128 v[166:169], v250 offset:2048
	ds_read_b128 v[170:173], v250 offset:3072
	ds_read_b128 v[174:177], v140 offset:32768
	ds_read_b128 v[178:181], v140 offset:33792
	ds_read_b128 v[182:185], v140 offset:34816
	ds_read_b128 v[186:189], v140 offset:35840
	ds_read_b128 v[194:197], v140 offset:36864
	ds_read_b128 v[198:201], v140 offset:37888
	ds_read_b128 v[202:205], v140 offset:38912
	ds_read_b128 v[206:209], v140 offset:39936
	s_add_u32 s28, s28, 0x20000
	s_addc_u32 s29, s29, 0
	s_mov_b32 m0, s46
	s_nop 0
	global_load_lds_dwordx4 v128, s[28:29]
	s_nop 0
	s_mov_b32 m0, s47
	s_nop 0
	global_load_lds_dwordx4 v130, s[28:29]
	s_waitcnt vmcnt(8) lgkmcnt(0)
	s_setprio 1
	s_barrier
	v_mfma_f32_16x16x32_bf16 v[124:127], v[142:145], v[174:177], v[124:127]
	v_mfma_f32_16x16x32_bf16 v[120:123], v[150:153], v[174:177], v[120:123]
	v_mfma_f32_16x16x32_bf16 v[116:119], v[142:145], v[182:185], v[116:119]
	v_mfma_f32_16x16x32_bf16 v[112:115], v[150:153], v[182:185], v[112:115]
	v_mfma_f32_16x16x32_bf16 v[108:111], v[142:145], v[194:197], v[108:111]
	v_mfma_f32_16x16x32_bf16 v[104:107], v[150:153], v[194:197], v[104:107]
	v_mfma_f32_16x16x32_bf16 v[100:103], v[142:145], v[202:205], v[100:103]
	v_mfma_f32_16x16x32_bf16 v[96:99], v[150:153], v[202:205], v[96:99]
	v_mfma_f32_16x16x32_bf16 v[124:127], v[146:149], v[178:181], v[124:127]
	v_mfma_f32_16x16x32_bf16 v[120:123], v[154:157], v[178:181], v[120:123]
	v_mfma_f32_16x16x32_bf16 v[116:119], v[146:149], v[186:189], v[116:119]
	v_mfma_f32_16x16x32_bf16 v[112:115], v[154:157], v[186:189], v[112:115]
	v_mfma_f32_16x16x32_bf16 v[108:111], v[146:149], v[198:201], v[108:111]
	v_mfma_f32_16x16x32_bf16 v[104:107], v[154:157], v[198:201], v[104:107]
	v_mfma_f32_16x16x32_bf16 v[100:103], v[146:149], v[206:209], v[100:103]
	v_mfma_f32_16x16x32_bf16 v[96:99], v[154:157], v[206:209], v[96:99]
	v_mfma_f32_16x16x32_bf16 v[60:63], v[158:161], v[174:177], v[60:63]
	v_mfma_f32_16x16x32_bf16 v[56:59], v[166:169], v[174:177], v[56:59]
	v_mfma_f32_16x16x32_bf16 v[52:55], v[158:161], v[182:185], v[52:55]
	v_mfma_f32_16x16x32_bf16 v[48:51], v[166:169], v[182:185], v[48:51]
	v_mfma_f32_16x16x32_bf16 v[44:47], v[158:161], v[194:197], v[44:47]
	v_mfma_f32_16x16x32_bf16 v[40:43], v[166:169], v[194:197], v[40:43]
	v_mfma_f32_16x16x32_bf16 v[36:39], v[158:161], v[202:205], v[36:39]
	v_mfma_f32_16x16x32_bf16 v[32:35], v[166:169], v[202:205], v[32:35]
	v_mfma_f32_16x16x32_bf16 v[60:63], v[162:165], v[178:181], v[60:63]
	v_mfma_f32_16x16x32_bf16 v[56:59], v[170:173], v[178:181], v[56:59]
	v_mfma_f32_16x16x32_bf16 v[52:55], v[162:165], v[186:189], v[52:55]
	v_mfma_f32_16x16x32_bf16 v[48:51], v[170:173], v[186:189], v[48:51]
	v_mfma_f32_16x16x32_bf16 v[44:47], v[162:165], v[198:201], v[44:47]
	v_mfma_f32_16x16x32_bf16 v[40:43], v[170:173], v[198:201], v[40:43]
	v_mfma_f32_16x16x32_bf16 v[36:39], v[162:165], v[206:209], v[36:39]
	v_mfma_f32_16x16x32_bf16 v[32:35], v[170:173], v[206:209], v[32:35]
	s_setprio 0
	s_barrier
	ds_read_b128 v[174:177], v140 offset:49152
	ds_read_b128 v[178:181], v140 offset:50176
	ds_read_b128 v[182:185], v140 offset:51200
	ds_read_b128 v[186:189], v140 offset:52224
	ds_read_b128 v[194:197], v140 offset:53248
	ds_read_b128 v[198:201], v140 offset:54272
	ds_read_b128 v[202:205], v140 offset:55296
	ds_read_b128 v[206:209], v140 offset:56320
	s_add_u32 s28, s26, 0x80
	s_addc_u32 s29, s27, 0
	s_mov_b32 m0, s49
	s_nop 0
	global_load_lds_dwordx4 v129, s[28:29]
	s_add_u32 s26, s26, 0x20080
	s_mov_b32 m0, s50
	s_nop 0
	global_load_lds_dwordx4 v131, s[28:29]
	s_addc_u32 s27, s27, 0
	s_mov_b32 m0, s53
	s_nop 0
	global_load_lds_dwordx4 v129, s[26:27]
	s_nop 0
	s_mov_b32 m0, s54
	s_nop 0
	global_load_lds_dwordx4 v131, s[26:27]
	s_nop 0
	s_mov_b32 m0, s51
	s_nop 0
	global_load_lds_dwordx4 v128, s[24:25]
	s_nop 0
	s_mov_b32 m0, s52
	s_nop 0
	global_load_lds_dwordx4 v130, s[24:25]
	s_waitcnt vmcnt(8) lgkmcnt(0)
	s_setprio 1
	s_barrier
	v_mfma_f32_16x16x32_bf16 v[92:95], v[142:145], v[174:177], v[92:95]
	v_mfma_f32_16x16x32_bf16 v[88:91], v[150:153], v[174:177], v[88:91]
	v_mfma_f32_16x16x32_bf16 v[84:87], v[142:145], v[182:185], v[84:87]
	v_mfma_f32_16x16x32_bf16 v[80:83], v[150:153], v[182:185], v[80:83]
	v_mfma_f32_16x16x32_bf16 v[76:79], v[142:145], v[194:197], v[76:79]
	v_mfma_f32_16x16x32_bf16 v[72:75], v[150:153], v[194:197], v[72:75]
	v_mfma_f32_16x16x32_bf16 v[68:71], v[142:145], v[202:205], v[68:71]
	v_mfma_f32_16x16x32_bf16 v[64:67], v[150:153], v[202:205], v[64:67]
	v_mfma_f32_16x16x32_bf16 v[92:95], v[146:149], v[178:181], v[92:95]
	v_mfma_f32_16x16x32_bf16 v[88:91], v[154:157], v[178:181], v[88:91]
	v_mfma_f32_16x16x32_bf16 v[84:87], v[146:149], v[186:189], v[84:87]
	v_mfma_f32_16x16x32_bf16 v[80:83], v[154:157], v[186:189], v[80:83]
	v_mfma_f32_16x16x32_bf16 v[76:79], v[146:149], v[198:201], v[76:79]
	v_mfma_f32_16x16x32_bf16 v[72:75], v[154:157], v[198:201], v[72:75]
	v_mfma_f32_16x16x32_bf16 v[68:71], v[146:149], v[206:209], v[68:71]
	v_mfma_f32_16x16x32_bf16 v[64:67], v[154:157], v[206:209], v[64:67]
	v_mfma_f32_16x16x32_bf16 v[28:31], v[158:161], v[174:177], v[28:31]
	v_mfma_f32_16x16x32_bf16 v[24:27], v[166:169], v[174:177], v[24:27]
	v_mfma_f32_16x16x32_bf16 v[20:23], v[158:161], v[182:185], v[20:23]
	v_mfma_f32_16x16x32_bf16 v[16:19], v[166:169], v[182:185], v[16:19]
	v_mfma_f32_16x16x32_bf16 v[12:15], v[158:161], v[194:197], v[12:15]
	v_mfma_f32_16x16x32_bf16 v[8:11], v[166:169], v[194:197], v[8:11]
	v_mfma_f32_16x16x32_bf16 v[4:7], v[158:161], v[202:205], v[4:7]
	v_mfma_f32_16x16x32_bf16 v[0:3], v[166:169], v[202:205], v[0:3]
	v_mfma_f32_16x16x32_bf16 v[28:31], v[162:165], v[178:181], v[28:31]
	v_mfma_f32_16x16x32_bf16 v[24:27], v[170:173], v[178:181], v[24:27]
	v_mfma_f32_16x16x32_bf16 v[20:23], v[162:165], v[186:189], v[20:23]
	v_mfma_f32_16x16x32_bf16 v[16:19], v[170:173], v[186:189], v[16:19]
	v_mfma_f32_16x16x32_bf16 v[12:15], v[162:165], v[198:201], v[12:15]
	v_mfma_f32_16x16x32_bf16 v[8:11], v[170:173], v[198:201], v[8:11]
	v_mfma_f32_16x16x32_bf16 v[4:7], v[162:165], v[206:209], v[4:7]
	v_mfma_f32_16x16x32_bf16 v[0:3], v[170:173], v[206:209], v[0:3]
	s_setprio 0
	s_barrier
	s_add_u32 s62, s62, 0x100
	s_addc_u32 s65, s65, 0
	s_add_u32 s71, s71, 0x100
	s_addc_u32 s77, s77, 0
	s_cmp_ge_i32 s79, s40
	s_mov_b32 s24, s79
	s_cbranch_scc0 .LBB0_756
	s_mov_b32 s79, 0xc00000
	s_and_b64 vcc, exec, s[14:15]
	s_cbranch_vccz .LBB0_759

; __device__ __forceinline__ int tid_of(int wave_s) { int w = wave_s; asm volatile("" : "+s"(w)); int l; asm volatile("v_mbcnt_lo_u32_b32 %0, -1, 0\n\tv_mbcnt_hi_u32_b32 %0, -1, %0" : "=v"(l)); return w * 64 + l; }
; #define PG8_STAGE(bufoff, gbase, voff) do { _Pragma("unroll") for (int _i = 0; _i < 2; ++_i) \
;         asm volatile("s_mov_b32 m0, %0\n\ts_nop 0\n\tglobal_load_lds_dwordx4 %1, %2" :: "s"(ldsb + (unsigned)((bufoff) + _i * 8192)), "v"((voff)[_i]), "s"(gbase) : "m0", "memory"); } while (0)
; #define PG8_WAIT_V(n) asm volatile("s_waitcnt vmcnt(" #n ")" ::: "memory")
; #define PG8_BAR __builtin_amdgcn_s_barrier()
; template <class Epi, class Sched, bool ALIGN_EPI = false, bool SP2 = false>
; __device__ __forceinline__ void gemm_phase(PG8_LAS unsigned char* lds, const Gemm g, const Sched& S, const Epi& E, const int wv) {
;     ...
;     const int tid = tid_of(wv), wid = wid_, lane = tid & 63, wr = wid >> 2, wc = wid & 3, fr = lane & 15, fq = lane >> 4;
;     const int K = g.ld, Kb = g.ldb ? g.ldb : g.ld;
;     unsigned voffA[2], voffB[2];
; #pragma unroll
;     for (int i = 0; i < 2; ++i) { int R, C; stage_rc(tid * 16 + i * 8192, R, C); const int Rb = Epi::PERM ? ((R & ~31) + perm32(R & 31)) : R;
;         voffA[i] = (unsigned)(R * K + C) * 2u; voffB[i] = (unsigned)(Rb * Kb + C) * 2u; }
;     const size_t kstep = (size_t)(BK * 2);
;     const size_t hstepA = (size_t)HALF * K * 2, hstepB = (size_t)HALF * Kb * 2;
;     const size_t tstepA = 2 * hstepA, tstepB = 2 * hstepB;
;     const unsigned ldsw = (unsigned)wid * 1024u;
;     const unsigned ldsb = (unsigned)(size_t)lds + ldsw;
;     const int aoff = lds_byte(wr * 64 + fr, fq * 8), boff = lds_byte(wc * 32 + fr, fq * 8);
;     ...
;         PG8_STAGE(PG8_SB(0, 0), cB, voffB); PG8_STAGE(PG8_SB(0, 1), cB + hstepB, voffB); PG8_STAGE(PG8_SA(0, 0), cA, voffA); PG8_STAGE(PG8_SA(0, 1), cA + hstepA, voffA);
;         if (wr == 1) PG8_BAR;
;         PG8_WAIT_V(2); PG8_BAR;
;         PG8_STAGE(PG8_SB(1, 0), cB + kstep, voffB); PG8_STAGE(PG8_SA(1, 0), cA + kstep, voffA); PG8_STAGE(PG8_SB(1, 1), cB + hstepB + kstep, voffB);
;         PG8_WAIT_V(6); PG8_BAR;
.LBB0_801:
	s_bfe_u32 s65, s8, 0x80010
	s_add_u32 s8, s10, 0x1eaef000
	s_addc_u32 s9, s11, 0
	s_add_u32 s10, s10, 0x2046f000
	s_addc_u32 s11, s11, 0
	v_and_b32_e32 v1, 48, v0
	s_lshl_b32 s44, s13, 6
	s_lshl_b32 s2, s13, 13
	v_lshlrev_b32_e32 v2, 6, v0
	s_movk_i32 s13, 0x3c0
	v_and_or_b32 v1, v2, s13, v1
	v_lshlrev_b32_e32 v2, 2, v0
	v_and_b32_e32 v2, 32, v2
	v_bitop3_b32 v3, v1, s2, v2 bitop3:0xde
	s_lshl_b32 s2, s12, 5
	s_and_b32 s2, s2, 0x60
	s_lshl_b32 s13, s2, 7
	s_add_i32 s45, s31, 0x18000
	s_add_u32 s14, s20, 0x80
	s_waitcnt vmcnt(2)
	s_barrier
	s_addc_u32 s15, s21, 0
	s_mov_b32 m0, s45
	s_nop 0
	global_load_lds_dwordx4 v131, s[14:15]
	s_add_i32 s46, s31, 0x1a000
	s_add_i32 s47, s31, 0x8000
	s_mov_b32 m0, s46
	s_nop 0
	global_load_lds_dwordx4 v133, s[14:15]
	s_add_u32 s14, s22, 0x80
	s_addc_u32 s15, s23, 0
	s_mov_b32 m0, s47
	s_nop 0
	global_load_lds_dwordx4 v130, s[14:15]
	s_add_i32 s48, s31, 0xa000
	s_add_i32 s49, s31, 0x1c000
	s_mov_b32 m0, s48
	s_nop 0
	global_load_lds_dwordx4 v132, s[14:15]
	s_add_u32 s14, s20, 0x10080
	s_addc_u32 s15, s21, 0
	s_mov_b32 m0, s49
	s_nop 0
	global_load_lds_dwordx4 v131, s[14:15]
	s_add_i32 s50, s31, 0x1e000
	s_mov_b32 m0, s50
	s_nop 0
	global_load_lds_dwordx4 v133, s[14:15]
	v_bitop3_b32 v1, v1, s13, v2 bitop3:0xde
	s_waitcnt vmcnt(6)
	s_add_i32 s51, s31, 0xc000
	v_and_b32_e32 v2, 3, v0
	v_bfe_u32 v134, v0, 2, 4
	v_and_b32_e32 v0, 60, v0
	s_cmp_lt_u32 s12, 4
	v_lshl_or_b32 v135, v2, 6, v0
	v_lshl_or_b32 v0, v2, 3, s2
	s_cselect_b64 s[12:13], -1, 0
	s_add_i32 s52, s31, 0xe000
	s_ashr_i32 s53, s70, 31
	s_ashr_i32 s54, s26, 31
	s_mov_b32 s55, 0
	v_add_u32_e32 v136, 0, v1
	v_add_u32_e32 v253, 0x10000, v136
	v_add_u32_e32 v252, 0x14000, v136
	v_add_u32_e32 v251, 0x18000, v136
	v_add_u32_e32 v250, 0x1c000, v136
	v_add_u32_e32 v137, 0, v3
	v_lshlrev_b32_e32 v192, 1, v0
	s_barrier
	s_branch .LBB0_804

; #define PG8_STAGE(bufoff, gbase, voff) do { _Pragma("unroll") for (int _i = 0; _i < 2; ++_i) \
;         asm volatile("s_mov_b32 m0, %0\n\ts_nop 0\n\tglobal_load_lds_dwordx4 %1, %2" :: "s"(ldsb + (unsigned)((bufoff) + _i * 8192)), "v"((voff)[_i]), "s"(gbase) : "m0", "memory"); } while (0)
; #define PG8_LDA(dst, b, h) do { _Pragma("unroll") for (int m = 0; m < 4; ++m) _Pragma("unroll") for (int k = 0; k < 2; ++k) dst[m][k] = *(const PG8_LAS bf16x8*)(lds + PG8_SA(b, h) + aoff + m * 2048 + k * 1024); } while (0)
; #define PG8_LDB(dst, b, h) do { _Pragma("unroll") for (int n = 0; n < 2; ++n) _Pragma("unroll") for (int k = 0; k < 2; ++k) dst[n][k] = *(const PG8_LAS bf16x8*)(lds + PG8_SB(b, h) + boff + n * 2048 + k * 1024); } while (0)
; #define PG8_MMA(ai, bj, At, Bt) do { __builtin_amdgcn_s_setprio(1); _Pragma("unroll") for (int m = 0; m < 4; ++m) _Pragma("unroll") for (int n = 0; n < 2; ++n) _Pragma("unroll") for (int k = 0; k < 2; ++k) \
;         acc[ai][bj][m][n] = __builtin_amdgcn_mfma_f32_16x16x32_bf16(Bt[n][k], At[m][k], acc[ai][bj][m][n], 0, 0, 0); __builtin_amdgcn_s_setprio(0); } while (0)
; #define PG8_WAIT_V(n) asm volatile("s_waitcnt vmcnt(" #n ")" ::: "memory")
; #define PG8_WAIT_L(n) asm volatile("s_waitcnt lgkmcnt(" #n ")" ::: "memory")
; template <class Epi, class Sched, bool ALIGN_EPI = false, bool SP2 = false>
; __device__ __forceinline__ void gemm_phase(PG8_LAS unsigned char* lds, const Gemm g, const Sched& S, const Epi& E, const int wv) {
;     ...
;             const bool last = (t == nt - 2);
;             const char* a1 = cA + (size_t)(t + 1) * kstep;
;             const char* a2 = last ? nA : cA + (size_t)(t + 2) * kstep; const char* b2 = last ? nB : cB + (size_t)(t + 2) * kstep;
;             const char* a3 = a2 + kstep; const char* b3 = b2 + kstep;
;             if (last && has_next) S.a_ready(nxt);
;             if constexpr (SP2) {
;             PG8_LDB(B0, 0, 0); PG8_LDB(B1, 0, 1); PG8_SCHED; PG8_LDA(At, 0, 0); PG8_STAGE(PG8_SA(1, 1), a1 + hstepA, voffA);
;             PG8_WAIT_V(8); PG8_WAIT_L(0); PG8_BAR; PG8_MMA(0, 0, At, B0); PG8_MMA(0, 1, At, B1); PG8_BAR; PG8_SCHED;
;             PG8_LDA(At, 0, 1); PG8_STAGE(PG8_SB(0, 0), b2, voffB); PG8_STAGE(PG8_SB(0, 1), b2 + hstepB, voffB); PG8_STAGE(PG8_SA(0, 0), a2, voffA);
;             PG8_WAIT_V(8); PG8_WAIT_L(0); PG8_BAR; PG8_MMA(1, 0, At, B0); PG8_MMA(1, 1, At, B1); PG8_BAR; PG8_SCHED;
.LBB0_810:
	ds_read_b128 v[138:141], v253
	ds_read_b128 v[142:145], v253 offset:1024
	ds_read_b128 v[146:149], v253 offset:2048
	ds_read_b128 v[150:153], v253 offset:3072
	ds_read_b128 v[154:157], v252
	ds_read_b128 v[158:161], v252 offset:1024
	ds_read_b128 v[162:165], v252 offset:2048
	ds_read_b128 v[166:169], v252 offset:3072
	s_add_i32 s85, s20, 2
	s_cmp_eq_u32 s62, s20
	s_cselect_b32 s24, s14, s77
	s_cselect_b32 s25, s15, s79
	s_cselect_b32 s22, s72, s83
	s_cselect_b32 s23, s71, s84
	s_add_u32 s20, s24, 0x80
	s_addc_u32 s21, s25, 0
	ds_read_b128 v[170:173], v137
	ds_read_b128 v[174:177], v137 offset:1024
	ds_read_b128 v[178:181], v137 offset:2048
	ds_read_b128 v[182:185], v137 offset:3072
	ds_read_b128 v[186:189], v137 offset:4096
	ds_read_b128 v[194:197], v137 offset:5120
	ds_read_b128 v[198:201], v137 offset:6144
	ds_read_b128 v[202:205], v137 offset:7168
	s_add_u32 s86, s77, 0xff80
	s_addc_u32 s87, s79, 0
	s_mov_b32 m0, s51
	s_nop 0
	global_load_lds_dwordx4 v130, s[86:87]
	s_nop 0
	s_mov_b32 m0, s52
	s_nop 0
	global_load_lds_dwordx4 v132, s[86:87]
	s_waitcnt vmcnt(8) lgkmcnt(0)
	s_setprio 1
	s_barrier
	v_mfma_f32_16x16x32_bf16 v[124:127], v[138:141], v[170:173], v[124:127]
	v_mfma_f32_16x16x32_bf16 v[120:123], v[146:149], v[170:173], v[120:123]
	v_mfma_f32_16x16x32_bf16 v[108:111], v[138:141], v[178:181], v[108:111]
	v_mfma_f32_16x16x32_bf16 v[104:107], v[146:149], v[178:181], v[104:107]
	v_mfma_f32_16x16x32_bf16 v[92:95], v[138:141], v[186:189], v[92:95]
	v_mfma_f32_16x16x32_bf16 v[88:91], v[146:149], v[186:189], v[88:91]
	v_mfma_f32_16x16x32_bf16 v[76:79], v[138:141], v[198:201], v[76:79]
	v_mfma_f32_16x16x32_bf16 v[72:75], v[146:149], v[198:201], v[72:75]
	v_mfma_f32_16x16x32_bf16 v[124:127], v[142:145], v[174:177], v[124:127]
	v_mfma_f32_16x16x32_bf16 v[120:123], v[150:153], v[174:177], v[120:123]
	v_mfma_f32_16x16x32_bf16 v[108:111], v[142:145], v[182:185], v[108:111]
	v_mfma_f32_16x16x32_bf16 v[104:107], v[150:153], v[182:185], v[104:107]
	v_mfma_f32_16x16x32_bf16 v[92:95], v[142:145], v[194:197], v[92:95]
	v_mfma_f32_16x16x32_bf16 v[88:91], v[150:153], v[194:197], v[88:91]
	v_mfma_f32_16x16x32_bf16 v[76:79], v[142:145], v[202:205], v[76:79]
	v_mfma_f32_16x16x32_bf16 v[72:75], v[150:153], v[202:205], v[72:75]
	v_mfma_f32_16x16x32_bf16 v[116:119], v[154:157], v[170:173], v[116:119]
	v_mfma_f32_16x16x32_bf16 v[112:115], v[162:165], v[170:173], v[112:115]
	v_mfma_f32_16x16x32_bf16 v[100:103], v[154:157], v[178:181], v[100:103]
	v_mfma_f32_16x16x32_bf16 v[96:99], v[162:165], v[178:181], v[96:99]
	v_mfma_f32_16x16x32_bf16 v[84:87], v[154:157], v[186:189], v[84:87]
	v_mfma_f32_16x16x32_bf16 v[80:83], v[162:165], v[186:189], v[80:83]
	v_mfma_f32_16x16x32_bf16 v[68:71], v[154:157], v[198:201], v[68:71]
	v_mfma_f32_16x16x32_bf16 v[64:67], v[162:165], v[198:201], v[64:67]
	v_mfma_f32_16x16x32_bf16 v[116:119], v[158:161], v[174:177], v[116:119]
	v_mfma_f32_16x16x32_bf16 v[112:115], v[166:169], v[174:177], v[112:115]
	v_mfma_f32_16x16x32_bf16 v[100:103], v[158:161], v[182:185], v[100:103]
	v_mfma_f32_16x16x32_bf16 v[96:99], v[166:169], v[182:185], v[96:99]
	v_mfma_f32_16x16x32_bf16 v[84:87], v[158:161], v[194:197], v[84:87]
	v_mfma_f32_16x16x32_bf16 v[80:83], v[166:169], v[194:197], v[80:83]
	v_mfma_f32_16x16x32_bf16 v[68:71], v[158:161], v[202:205], v[68:71]
	v_mfma_f32_16x16x32_bf16 v[64:67], v[166:169], v[202:205], v[64:67]
	s_setprio 0
	s_barrier
	ds_read_b128 v[170:173], v137 offset:16384
	ds_read_b128 v[174:177], v137 offset:17408
	ds_read_b128 v[178:181], v137 offset:18432
	ds_read_b128 v[182:185], v137 offset:19456
	ds_read_b128 v[186:189], v137 offset:20480
	ds_read_b128 v[194:197], v137 offset:21504
	ds_read_b128 v[198:201], v137 offset:22528
	ds_read_b128 v[202:205], v137 offset:23552
	s_mov_b32 m0, s33
	s_nop 0
	global_load_lds_dwordx4 v131, s[22:23]
	s_add_u32 s86, s22, 0x10000
	s_mov_b32 m0, s34
	s_nop 0
	global_load_lds_dwordx4 v133, s[22:23]
	s_addc_u32 s87, s23, 0
	s_mov_b32 m0, s35
	s_nop 0
	global_load_lds_dwordx4 v131, s[86:87]
	s_nop 0
	s_mov_b32 m0, s36
	s_nop 0
	global_load_lds_dwordx4 v133, s[86:87]
	s_nop 0
	s_mov_b32 m0, s31
	s_nop 0
	global_load_lds_dwordx4 v130, s[24:25]
	s_nop 0
	s_mov_b32 m0, s37
	s_nop 0
	global_load_lds_dwordx4 v132, s[24:25]
	s_waitcnt vmcnt(8) lgkmcnt(0)
	s_setprio 1
	s_barrier
	v_mfma_f32_16x16x32_bf16 v[60:63], v[138:141], v[170:173], v[60:63]
	v_mfma_f32_16x16x32_bf16 v[56:59], v[146:149], v[170:173], v[56:59]
	v_mfma_f32_16x16x32_bf16 v[44:47], v[138:141], v[178:181], v[44:47]
	v_mfma_f32_16x16x32_bf16 v[40:43], v[146:149], v[178:181], v[40:43]
	v_mfma_f32_16x16x32_bf16 v[28:31], v[138:141], v[186:189], v[28:31]
	v_mfma_f32_16x16x32_bf16 v[24:27], v[146:149], v[186:189], v[24:27]
	v_mfma_f32_16x16x32_bf16 v[12:15], v[138:141], v[198:201], v[12:15]
	v_mfma_f32_16x16x32_bf16 v[8:11], v[146:149], v[198:201], v[8:11]
	v_mfma_f32_16x16x32_bf16 v[60:63], v[142:145], v[174:177], v[60:63]
	v_mfma_f32_16x16x32_bf16 v[56:59], v[150:153], v[174:177], v[56:59]
	v_mfma_f32_16x16x32_bf16 v[44:47], v[142:145], v[182:185], v[44:47]
	v_mfma_f32_16x16x32_bf16 v[40:43], v[150:153], v[182:185], v[40:43]
	v_mfma_f32_16x16x32_bf16 v[28:31], v[142:145], v[194:197], v[28:31]
	v_mfma_f32_16x16x32_bf16 v[24:27], v[150:153], v[194:197], v[24:27]
	v_mfma_f32_16x16x32_bf16 v[12:15], v[142:145], v[202:205], v[12:15]
	v_mfma_f32_16x16x32_bf16 v[8:11], v[150:153], v[202:205], v[8:11]
	v_mfma_f32_16x16x32_bf16 v[52:55], v[154:157], v[170:173], v[52:55]
	v_mfma_f32_16x16x32_bf16 v[48:51], v[162:165], v[170:173], v[48:51]
	v_mfma_f32_16x16x32_bf16 v[36:39], v[154:157], v[178:181], v[36:39]
	v_mfma_f32_16x16x32_bf16 v[32:35], v[162:165], v[178:181], v[32:35]
	v_mfma_f32_16x16x32_bf16 v[20:23], v[154:157], v[186:189], v[20:23]
	v_mfma_f32_16x16x32_bf16 v[16:19], v[162:165], v[186:189], v[16:19]
	v_mfma_f32_16x16x32_bf16 v[4:7], v[154:157], v[198:201], v[4:7]
	v_mfma_f32_16x16x32_bf16 v[0:3], v[162:165], v[198:201], v[0:3]
	v_mfma_f32_16x16x32_bf16 v[52:55], v[158:161], v[174:177], v[52:55]
	v_mfma_f32_16x16x32_bf16 v[48:51], v[166:169], v[174:177], v[48:51]
	v_mfma_f32_16x16x32_bf16 v[36:39], v[158:161], v[182:185], v[36:39]
	v_mfma_f32_16x16x32_bf16 v[32:35], v[166:169], v[182:185], v[32:35]
	v_mfma_f32_16x16x32_bf16 v[20:23], v[158:161], v[194:197], v[20:23]
	v_mfma_f32_16x16x32_bf16 v[16:19], v[166:169], v[194:197], v[16:19]
	v_mfma_f32_16x16x32_bf16 v[4:7], v[158:161], v[202:205], v[4:7]
	v_mfma_f32_16x16x32_bf16 v[0:3], v[166:169], v[202:205], v[0:3]
	s_setprio 0
	s_barrier
; #define PG8_STAGE(bufoff, gbase, voff) do { _Pragma("unroll") for (int _i = 0; _i < 2; ++_i) \
;         asm volatile("s_mov_b32 m0, %0\n\ts_nop 0\n\tglobal_load_lds_dwordx4 %1, %2" :: "s"(ldsb + (unsigned)((bufoff) + _i * 8192)), "v"((voff)[_i]), "s"(gbase) : "m0", "memory"); } while (0)
; #define PG8_LDA(dst, b, h) do { _Pragma("unroll") for (int m = 0; m < 4; ++m) _Pragma("unroll") for (int k = 0; k < 2; ++k) dst[m][k] = *(const PG8_LAS bf16x8*)(lds + PG8_SA(b, h) + aoff + m * 2048 + k * 1024); } while (0)
; #define PG8_LDB(dst, b, h) do { _Pragma("unroll") for (int n = 0; n < 2; ++n) _Pragma("unroll") for (int k = 0; k < 2; ++k) dst[n][k] = *(const PG8_LAS bf16x8*)(lds + PG8_SB(b, h) + boff + n * 2048 + k * 1024); } while (0)
; #define PG8_MMA(ai, bj, At, Bt) do { __builtin_amdgcn_s_setprio(1); _Pragma("unroll") for (int m = 0; m < 4; ++m) _Pragma("unroll") for (int n = 0; n < 2; ++n) _Pragma("unroll") for (int k = 0; k < 2; ++k) \
;         acc[ai][bj][m][n] = __builtin_amdgcn_mfma_f32_16x16x32_bf16(Bt[n][k], At[m][k], acc[ai][bj][m][n], 0, 0, 0); __builtin_amdgcn_s_setprio(0); } while (0)
; #define PG8_WAIT_V(n) asm volatile("s_waitcnt vmcnt(" #n ")" ::: "memory")
; #define PG8_WAIT_L(n) asm volatile("s_waitcnt lgkmcnt(" #n ")" ::: "memory")
; #define PG8_BAR __builtin_amdgcn_s_barrier()
; #define PG8_SCHED __builtin_amdgcn_sched_barrier(0)
; template <class Epi, class Sched, bool ALIGN_EPI = false, bool SP2 = false>
; __device__ __forceinline__ void gemm_phase(PG8_LAS unsigned char* lds, const Gemm g, const Sched& S, const Epi& E, const int wv) {
;     ...
;             PG8_LDB(B0, 1, 0); PG8_LDB(B1, 1, 1); PG8_SCHED; PG8_LDA(At, 1, 0); PG8_STAGE(PG8_SA(0, 1), a2 + hstepA, voffA);
;             PG8_WAIT_V(8); PG8_WAIT_L(0); PG8_BAR; PG8_MMA(0, 0, At, B0); PG8_MMA(0, 1, At, B1); PG8_BAR; PG8_SCHED;
;             PG8_LDA(At, 1, 1); PG8_STAGE(PG8_SB(1, 0), b3, voffB); PG8_STAGE(PG8_SB(1, 1), b3 + hstepB, voffB); PG8_STAGE(PG8_SA(1, 0), a3, voffA);
;             PG8_WAIT_V(8); PG8_WAIT_L(0); PG8_BAR; PG8_MMA(1, 0, At, B0); PG8_MMA(1, 1, At, B1); PG8_BAR; PG8_SCHED;
	ds_read_b128 v[138:141], v251
	ds_read_b128 v[142:145], v251 offset:1024
	ds_read_b128 v[146:149], v251 offset:2048
	ds_read_b128 v[150:153], v251 offset:3072
	ds_read_b128 v[154:157], v250
	ds_read_b128 v[158:161], v250 offset:1024
	ds_read_b128 v[162:165], v250 offset:2048
	ds_read_b128 v[166:169], v250 offset:3072
	ds_read_b128 v[170:173], v137 offset:32768
	ds_read_b128 v[174:177], v137 offset:33792
	ds_read_b128 v[178:181], v137 offset:34816
	ds_read_b128 v[182:185], v137 offset:35840
	ds_read_b128 v[186:189], v137 offset:36864
	ds_read_b128 v[194:197], v137 offset:37888
	ds_read_b128 v[198:201], v137 offset:38912
	ds_read_b128 v[202:205], v137 offset:39936
	s_add_u32 s24, s24, 0x10000
	s_addc_u32 s25, s25, 0
	s_mov_b32 m0, s42
	s_nop 0
	global_load_lds_dwordx4 v130, s[24:25]
	s_nop 0
	s_mov_b32 m0, s43
	s_nop 0
	global_load_lds_dwordx4 v132, s[24:25]
	s_waitcnt vmcnt(8) lgkmcnt(0)
	s_setprio 1
	s_barrier
	v_mfma_f32_16x16x32_bf16 v[124:127], v[138:141], v[170:173], v[124:127]
	v_mfma_f32_16x16x32_bf16 v[120:123], v[146:149], v[170:173], v[120:123]
	v_mfma_f32_16x16x32_bf16 v[108:111], v[138:141], v[178:181], v[108:111]
	v_mfma_f32_16x16x32_bf16 v[104:107], v[146:149], v[178:181], v[104:107]
	v_mfma_f32_16x16x32_bf16 v[92:95], v[138:141], v[186:189], v[92:95]
	v_mfma_f32_16x16x32_bf16 v[88:91], v[146:149], v[186:189], v[88:91]
	v_mfma_f32_16x16x32_bf16 v[76:79], v[138:141], v[198:201], v[76:79]
	v_mfma_f32_16x16x32_bf16 v[72:75], v[146:149], v[198:201], v[72:75]
	v_mfma_f32_16x16x32_bf16 v[124:127], v[142:145], v[174:177], v[124:127]
	v_mfma_f32_16x16x32_bf16 v[120:123], v[150:153], v[174:177], v[120:123]
	v_mfma_f32_16x16x32_bf16 v[108:111], v[142:145], v[182:185], v[108:111]
	v_mfma_f32_16x16x32_bf16 v[104:107], v[150:153], v[182:185], v[104:107]
	v_mfma_f32_16x16x32_bf16 v[92:95], v[142:145], v[194:197], v[92:95]
	v_mfma_f32_16x16x32_bf16 v[88:91], v[150:153], v[194:197], v[88:91]
	v_mfma_f32_16x16x32_bf16 v[76:79], v[142:145], v[202:205], v[76:79]
	v_mfma_f32_16x16x32_bf16 v[72:75], v[150:153], v[202:205], v[72:75]
	v_mfma_f32_16x16x32_bf16 v[116:119], v[154:157], v[170:173], v[116:119]
	v_mfma_f32_16x16x32_bf16 v[112:115], v[162:165], v[170:173], v[112:115]
	v_mfma_f32_16x16x32_bf16 v[100:103], v[154:157], v[178:181], v[100:103]
	v_mfma_f32_16x16x32_bf16 v[96:99], v[162:165], v[178:181], v[96:99]
	v_mfma_f32_16x16x32_bf16 v[84:87], v[154:157], v[186:189], v[84:87]
	v_mfma_f32_16x16x32_bf16 v[80:83], v[162:165], v[186:189], v[80:83]
	v_mfma_f32_16x16x32_bf16 v[68:71], v[154:157], v[198:201], v[68:71]
	v_mfma_f32_16x16x32_bf16 v[64:67], v[162:165], v[198:201], v[64:67]
	v_mfma_f32_16x16x32_bf16 v[116:119], v[158:161], v[174:177], v[116:119]
	v_mfma_f32_16x16x32_bf16 v[112:115], v[166:169], v[174:177], v[112:115]
	v_mfma_f32_16x16x32_bf16 v[100:103], v[158:161], v[182:185], v[100:103]
	v_mfma_f32_16x16x32_bf16 v[96:99], v[166:169], v[182:185], v[96:99]
	v_mfma_f32_16x16x32_bf16 v[84:87], v[158:161], v[194:197], v[84:87]
	v_mfma_f32_16x16x32_bf16 v[80:83], v[166:169], v[194:197], v[80:83]
	v_mfma_f32_16x16x32_bf16 v[68:71], v[158:161], v[202:205], v[68:71]
	v_mfma_f32_16x16x32_bf16 v[64:67], v[166:169], v[202:205], v[64:67]
	s_setprio 0
	s_barrier
	ds_read_b128 v[170:173], v137 offset:49152
	ds_read_b128 v[174:177], v137 offset:50176
	ds_read_b128 v[178:181], v137 offset:51200
	ds_read_b128 v[182:185], v137 offset:52224
	ds_read_b128 v[186:189], v137 offset:53248
	ds_read_b128 v[194:197], v137 offset:54272
	ds_read_b128 v[198:201], v137 offset:55296
	ds_read_b128 v[202:205], v137 offset:56320
	s_add_u32 s24, s22, 0x80
	s_addc_u32 s25, s23, 0
	s_mov_b32 m0, s45
	s_nop 0
	global_load_lds_dwordx4 v131, s[24:25]
	s_add_u32 s22, s22, 0x10080
	s_mov_b32 m0, s46
	s_nop 0
	global_load_lds_dwordx4 v133, s[24:25]
	s_addc_u32 s23, s23, 0
	s_mov_b32 m0, s49
	s_nop 0
	global_load_lds_dwordx4 v131, s[22:23]
	s_nop 0
	s_mov_b32 m0, s50
	s_nop 0
	global_load_lds_dwordx4 v133, s[22:23]
	s_nop 0
	s_mov_b32 m0, s47
	s_nop 0
	global_load_lds_dwordx4 v130, s[20:21]
	s_nop 0
	s_mov_b32 m0, s48
	s_nop 0
	global_load_lds_dwordx4 v132, s[20:21]
	s_waitcnt vmcnt(8) lgkmcnt(0)
	s_setprio 1
	s_barrier
	v_mfma_f32_16x16x32_bf16 v[60:63], v[138:141], v[170:173], v[60:63]
	v_mfma_f32_16x16x32_bf16 v[56:59], v[146:149], v[170:173], v[56:59]
	v_mfma_f32_16x16x32_bf16 v[44:47], v[138:141], v[178:181], v[44:47]
	v_mfma_f32_16x16x32_bf16 v[40:43], v[146:149], v[178:181], v[40:43]
	v_mfma_f32_16x16x32_bf16 v[28:31], v[138:141], v[186:189], v[28:31]
	v_mfma_f32_16x16x32_bf16 v[24:27], v[146:149], v[186:189], v[24:27]
	v_mfma_f32_16x16x32_bf16 v[12:15], v[138:141], v[198:201], v[12:15]
	v_mfma_f32_16x16x32_bf16 v[8:11], v[146:149], v[198:201], v[8:11]
	v_mfma_f32_16x16x32_bf16 v[60:63], v[142:145], v[174:177], v[60:63]
	v_mfma_f32_16x16x32_bf16 v[56:59], v[150:153], v[174:177], v[56:59]
	v_mfma_f32_16x16x32_bf16 v[44:47], v[142:145], v[182:185], v[44:47]
	v_mfma_f32_16x16x32_bf16 v[40:43], v[150:153], v[182:185], v[40:43]
	v_mfma_f32_16x16x32_bf16 v[28:31], v[142:145], v[194:197], v[28:31]
	v_mfma_f32_16x16x32_bf16 v[24:27], v[150:153], v[194:197], v[24:27]
	v_mfma_f32_16x16x32_bf16 v[12:15], v[142:145], v[202:205], v[12:15]
	v_mfma_f32_16x16x32_bf16 v[8:11], v[150:153], v[202:205], v[8:11]
	v_mfma_f32_16x16x32_bf16 v[52:55], v[154:157], v[170:173], v[52:55]
	v_mfma_f32_16x16x32_bf16 v[48:51], v[162:165], v[170:173], v[48:51]
	v_mfma_f32_16x16x32_bf16 v[36:39], v[154:157], v[178:181], v[36:39]
	v_mfma_f32_16x16x32_bf16 v[32:35], v[162:165], v[178:181], v[32:35]
	v_mfma_f32_16x16x32_bf16 v[20:23], v[154:157], v[186:189], v[20:23]
	v_mfma_f32_16x16x32_bf16 v[16:19], v[162:165], v[186:189], v[16:19]
	v_mfma_f32_16x16x32_bf16 v[4:7], v[154:157], v[198:201], v[4:7]
	v_mfma_f32_16x16x32_bf16 v[0:3], v[162:165], v[198:201], v[0:3]
	v_mfma_f32_16x16x32_bf16 v[52:55], v[158:161], v[174:177], v[52:55]
	v_mfma_f32_16x16x32_bf16 v[48:51], v[166:169], v[174:177], v[48:51]
	v_mfma_f32_16x16x32_bf16 v[36:39], v[158:161], v[182:185], v[36:39]
	v_mfma_f32_16x16x32_bf16 v[32:35], v[166:169], v[182:185], v[32:35]
	v_mfma_f32_16x16x32_bf16 v[20:23], v[158:161], v[194:197], v[20:23]
	v_mfma_f32_16x16x32_bf16 v[16:19], v[166:169], v[194:197], v[16:19]
	v_mfma_f32_16x16x32_bf16 v[4:7], v[158:161], v[202:205], v[4:7]
	v_mfma_f32_16x16x32_bf16 v[0:3], v[166:169], v[202:205], v[0:3]
	s_setprio 0
	s_barrier
	s_add_u32 s77, s77, 0x100
	s_addc_u32 s79, s79, 0
	s_add_u32 s83, s83, 0x100
	s_addc_u32 s84, s84, 0
	s_cmp_ge_i32 s85, s65
	s_mov_b32 s20, s85
	s_cbranch_scc0 .LBB0_810
	s_mov_b32 s79, 0xc00000
	s_and_b64 vcc, exec, s[12:13]
	s_cbranch_vccz .LBB0_813

; __device__ __forceinline__ int tid_of(int wave_s) { int w = wave_s; asm volatile("" : "+s"(w)); int l; asm volatile("v_mbcnt_lo_u32_b32 %0, -1, 0\n\tv_mbcnt_hi_u32_b32 %0, -1, %0" : "=v"(l)); return w * 64 + l; }
; #define PG8_STAGE(bufoff, gbase, voff) do { _Pragma("unroll") for (int _i = 0; _i < 2; ++_i) \
;         asm volatile("s_mov_b32 m0, %0\n\ts_nop 0\n\tglobal_load_lds_dwordx4 %1, %2" :: "s"(ldsb + (unsigned)((bufoff) + _i * 8192)), "v"((voff)[_i]), "s"(gbase) : "m0", "memory"); } while (0)
; #define PG8_WAIT_V(n) asm volatile("s_waitcnt vmcnt(" #n ")" ::: "memory")
; #define PG8_BAR __builtin_amdgcn_s_barrier()
; template <class Epi, class Sched, bool ALIGN_EPI = false, bool SP2 = false>
; __device__ __forceinline__ void gemm_phase(PG8_LAS unsigned char* lds, const Gemm g, const Sched& S, const Epi& E, const int wv) {
;     ...
;     const int tid = tid_of(wv), wid = wid_, lane = tid & 63, wr = wid >> 2, wc = wid & 3, fr = lane & 15, fq = lane >> 4;
;     const int K = g.ld, Kb = g.ldb ? g.ldb : g.ld;
;     unsigned voffA[2], voffB[2];
; #pragma unroll
;     for (int i = 0; i < 2; ++i) { int R, C; stage_rc(tid * 16 + i * 8192, R, C); const int Rb = Epi::PERM ? ((R & ~31) + perm32(R & 31)) : R;
;         voffA[i] = (unsigned)(R * K + C) * 2u; voffB[i] = (unsigned)(Rb * Kb + C) * 2u; }
;     const size_t kstep = (size_t)(BK * 2);
;     const size_t hstepA = (size_t)HALF * K * 2, hstepB = (size_t)HALF * Kb * 2;
;     const size_t tstepA = 2 * hstepA, tstepB = 2 * hstepB;
;     const unsigned ldsw = (unsigned)wid * 1024u;
;     const unsigned ldsb = (unsigned)(size_t)lds + ldsw;
;     const int aoff = lds_byte(wr * 64 + fr, fq * 8), boff = lds_byte(wc * 32 + fr, fq * 8);
;     ...
;         PG8_STAGE(PG8_SB(0, 0), cB, voffB); PG8_STAGE(PG8_SB(0, 1), cB + hstepB, voffB); PG8_STAGE(PG8_SA(0, 0), cA, voffA); PG8_STAGE(PG8_SA(0, 1), cA + hstepA, voffA);
;         if (wr == 1) PG8_BAR;
;         PG8_WAIT_V(2); PG8_BAR;
;         PG8_STAGE(PG8_SB(1, 0), cB + kstep, voffB); PG8_STAGE(PG8_SA(1, 0), cA + kstep, voffA); PG8_STAGE(PG8_SB(1, 1), cB + hstepB + kstep, voffB);
;         PG8_WAIT_V(6); PG8_BAR;
.LBB0_855:
	s_bfe_u32 s55, s11, 0x80010
	s_add_u32 s8, s8, 0x23fef000
	s_addc_u32 s9, s9, 0
	v_and_b32_e32 v1, 48, v0
	s_lshl_b32 s2, s12, 6
	s_lshl_b32 s11, s12, 13
	v_lshlrev_b32_e32 v2, 6, v0
	s_movk_i32 s12, 0x3c0
	v_and_or_b32 v1, v2, s12, v1
	v_lshlrev_b32_e32 v2, 2, v0
	v_and_b32_e32 v2, 32, v2
	v_bitop3_b32 v3, v1, s11, v2 bitop3:0xde
	s_lshl_b32 s11, s10, 5
	s_and_b32 s14, s11, 0x60
	s_lshl_b32 s11, s14, 7
	s_add_i32 s36, s27, 0x18000
	s_add_u32 s12, s18, 0x80
	s_waitcnt vmcnt(2)
	s_barrier
	s_addc_u32 s13, s19, 0
	s_mov_b32 m0, s36
	s_nop 0
	global_load_lds_dwordx4 v129, s[12:13]
	s_add_i32 s37, s27, 0x1a000
	s_add_i32 s40, s27, 0x8000
	s_mov_b32 m0, s37
	s_nop 0
	global_load_lds_dwordx4 v131, s[12:13]
	s_add_u32 s12, s20, 0x80
	s_addc_u32 s13, s21, 0
	s_mov_b32 m0, s40
	s_nop 0
	global_load_lds_dwordx4 v128, s[12:13]
	s_add_i32 s42, s27, 0xa000
	s_add_i32 s43, s27, 0x1c000
	s_mov_b32 m0, s42
	s_nop 0
	global_load_lds_dwordx4 v130, s[12:13]
	s_add_u32 s12, s18, 0x20080
	s_addc_u32 s13, s19, 0
	s_mov_b32 m0, s43
	s_nop 0
	global_load_lds_dwordx4 v129, s[12:13]
	s_add_i32 s44, s27, 0x1e000
	s_mov_b32 m0, s44
	s_nop 0
	global_load_lds_dwordx4 v131, s[12:13]
	v_bitop3_b32 v1, v1, s11, v2 bitop3:0xde
	s_waitcnt vmcnt(6)
	s_add_i32 s45, s27, 0xc000
	v_and_b32_e32 v2, 3, v0
	v_lshrrev_b32_e32 v4, 2, v0
	v_and_b32_e32 v0, 60, v0
	s_cmp_lt_u32 s10, 4
	v_lshl_or_b32 v132, v2, 6, v0
	v_lshl_or_b32 v0, v2, 3, s14
	s_cselect_b64 s[10:11], -1, 0
	v_and_or_b32 v133, v4, 15, s2
	s_add_i32 s46, s27, 0xe000
	s_ashr_i32 s47, s70, 31
	s_ashr_i32 s48, s4, 31
	s_mov_b32 s49, 0
	v_add_u32_e32 v134, 0, v1
	v_add_u32_e32 v253, 0x10000, v134
	v_add_u32_e32 v252, 0x14000, v134
	v_add_u32_e32 v251, 0x18000, v134
	v_add_u32_e32 v250, 0x1c000, v134
	v_add_u32_e32 v135, 0, v3
	v_lshlrev_b32_e32 v136, 1, v0
	s_barrier
	s_branch .LBB0_858

; #define PG8_STAGE(bufoff, gbase, voff) do { _Pragma("unroll") for (int _i = 0; _i < 2; ++_i) \
;         asm volatile("s_mov_b32 m0, %0\n\ts_nop 0\n\tglobal_load_lds_dwordx4 %1, %2" :: "s"(ldsb + (unsigned)((bufoff) + _i * 8192)), "v"((voff)[_i]), "s"(gbase) : "m0", "memory"); } while (0)
; #define PG8_LDA(dst, b, h) do { _Pragma("unroll") for (int m = 0; m < 4; ++m) _Pragma("unroll") for (int k = 0; k < 2; ++k) dst[m][k] = *(const PG8_LAS bf16x8*)(lds + PG8_SA(b, h) + aoff + m * 2048 + k * 1024); } while (0)
; #define PG8_LDB(dst, b, h) do { _Pragma("unroll") for (int n = 0; n < 2; ++n) _Pragma("unroll") for (int k = 0; k < 2; ++k) dst[n][k] = *(const PG8_LAS bf16x8*)(lds + PG8_SB(b, h) + boff + n * 2048 + k * 1024); } while (0)
; #define PG8_MMA(ai, bj, At, Bt) do { __builtin_amdgcn_s_setprio(1); _Pragma("unroll") for (int m = 0; m < 4; ++m) _Pragma("unroll") for (int n = 0; n < 2; ++n) _Pragma("unroll") for (int k = 0; k < 2; ++k) \
;         acc[ai][bj][m][n] = __builtin_amdgcn_mfma_f32_16x16x32_bf16(Bt[n][k], At[m][k], acc[ai][bj][m][n], 0, 0, 0); __builtin_amdgcn_s_setprio(0); } while (0)
; #define PG8_WAIT_V(n) asm volatile("s_waitcnt vmcnt(" #n ")" ::: "memory")
; #define PG8_WAIT_L(n) asm volatile("s_waitcnt lgkmcnt(" #n ")" ::: "memory")
; template <class Epi, class Sched, bool ALIGN_EPI = false, bool SP2 = false>
; __device__ __forceinline__ void gemm_phase(PG8_LAS unsigned char* lds, const Gemm g, const Sched& S, const Epi& E, const int wv) {
;     ...
;             const bool last = (t == nt - 2);
;             const char* a1 = cA + (size_t)(t + 1) * kstep;
;             const char* a2 = last ? nA : cA + (size_t)(t + 2) * kstep; const char* b2 = last ? nB : cB + (size_t)(t + 2) * kstep;
;             const char* a3 = a2 + kstep; const char* b3 = b2 + kstep;
;             if (last && has_next) S.a_ready(nxt);
;             if constexpr (SP2) {
;             PG8_LDB(B0, 0, 0); PG8_LDB(B1, 0, 1); PG8_SCHED; PG8_LDA(At, 0, 0); PG8_STAGE(PG8_SA(1, 1), a1 + hstepA, voffA);
;             PG8_WAIT_V(8); PG8_WAIT_L(0); PG8_BAR; PG8_MMA(0, 0, At, B0); PG8_MMA(0, 1, At, B1); PG8_BAR; PG8_SCHED;
;             PG8_LDA(At, 0, 1); PG8_STAGE(PG8_SB(0, 0), b2, voffB); PG8_STAGE(PG8_SB(0, 1), b2 + hstepB, voffB); PG8_STAGE(PG8_SA(0, 0), a2, voffA);
;             PG8_WAIT_V(8); PG8_WAIT_L(0); PG8_BAR; PG8_MMA(1, 0, At, B0); PG8_MMA(1, 1, At, B1); PG8_BAR; PG8_SCHED;
.LBB0_864:
	ds_read_b128 v[138:141], v253
	ds_read_b128 v[142:145], v253 offset:1024
	ds_read_b128 v[146:149], v253 offset:2048
	ds_read_b128 v[150:153], v253 offset:3072
	ds_read_b128 v[154:157], v252
	ds_read_b128 v[158:161], v252 offset:1024
	ds_read_b128 v[162:165], v252 offset:2048
	ds_read_b128 v[166:169], v252 offset:3072
	s_add_i32 s72, s18, 2
	s_cmp_eq_u32 s58, s18
	s_cselect_b32 s22, s12, s60
	s_cselect_b32 s23, s13, s62
	s_cselect_b32 s20, s57, s65
	s_cselect_b32 s21, s56, s71
	s_add_u32 s18, s22, 0x80
	s_addc_u32 s19, s23, 0
	ds_read_b128 v[170:173], v135
	ds_read_b128 v[174:177], v135 offset:1024
	ds_read_b128 v[178:181], v135 offset:2048
	ds_read_b128 v[182:185], v135 offset:3072
	ds_read_b128 v[186:189], v135 offset:4096
	ds_read_b128 v[194:197], v135 offset:5120
	ds_read_b128 v[198:201], v135 offset:6144
	ds_read_b128 v[202:205], v135 offset:7168
	s_add_u32 s84, s60, 0x1ff80
	s_addc_u32 s85, s62, 0
	s_mov_b32 m0, s45
	s_nop 0
	global_load_lds_dwordx4 v128, s[84:85]
	s_nop 0
	s_mov_b32 m0, s46
	s_nop 0
	global_load_lds_dwordx4 v130, s[84:85]
	s_waitcnt vmcnt(8) lgkmcnt(0)
	s_setprio 1
	s_barrier
	v_mfma_f32_16x16x32_bf16 v[124:127], v[138:141], v[170:173], v[124:127]
	v_mfma_f32_16x16x32_bf16 v[120:123], v[146:149], v[170:173], v[120:123]
	v_mfma_f32_16x16x32_bf16 v[108:111], v[138:141], v[178:181], v[108:111]
	v_mfma_f32_16x16x32_bf16 v[104:107], v[146:149], v[178:181], v[104:107]
	v_mfma_f32_16x16x32_bf16 v[92:95], v[138:141], v[186:189], v[92:95]
	v_mfma_f32_16x16x32_bf16 v[88:91], v[146:149], v[186:189], v[88:91]
	v_mfma_f32_16x16x32_bf16 v[76:79], v[138:141], v[198:201], v[76:79]
	v_mfma_f32_16x16x32_bf16 v[72:75], v[146:149], v[198:201], v[72:75]
	v_mfma_f32_16x16x32_bf16 v[124:127], v[142:145], v[174:177], v[124:127]
	v_mfma_f32_16x16x32_bf16 v[120:123], v[150:153], v[174:177], v[120:123]
	v_mfma_f32_16x16x32_bf16 v[108:111], v[142:145], v[182:185], v[108:111]
	v_mfma_f32_16x16x32_bf16 v[104:107], v[150:153], v[182:185], v[104:107]
	v_mfma_f32_16x16x32_bf16 v[92:95], v[142:145], v[194:197], v[92:95]
	v_mfma_f32_16x16x32_bf16 v[88:91], v[150:153], v[194:197], v[88:91]
	v_mfma_f32_16x16x32_bf16 v[76:79], v[142:145], v[202:205], v[76:79]
	v_mfma_f32_16x16x32_bf16 v[72:75], v[150:153], v[202:205], v[72:75]
	v_mfma_f32_16x16x32_bf16 v[116:119], v[154:157], v[170:173], v[116:119]
	v_mfma_f32_16x16x32_bf16 v[112:115], v[162:165], v[170:173], v[112:115]
	v_mfma_f32_16x16x32_bf16 v[100:103], v[154:157], v[178:181], v[100:103]
	v_mfma_f32_16x16x32_bf16 v[96:99], v[162:165], v[178:181], v[96:99]
	v_mfma_f32_16x16x32_bf16 v[84:87], v[154:157], v[186:189], v[84:87]
	v_mfma_f32_16x16x32_bf16 v[80:83], v[162:165], v[186:189], v[80:83]
	v_mfma_f32_16x16x32_bf16 v[68:71], v[154:157], v[198:201], v[68:71]
	v_mfma_f32_16x16x32_bf16 v[64:67], v[162:165], v[198:201], v[64:67]
	v_mfma_f32_16x16x32_bf16 v[116:119], v[158:161], v[174:177], v[116:119]
	v_mfma_f32_16x16x32_bf16 v[112:115], v[166:169], v[174:177], v[112:115]
	v_mfma_f32_16x16x32_bf16 v[100:103], v[158:161], v[182:185], v[100:103]
	v_mfma_f32_16x16x32_bf16 v[96:99], v[166:169], v[182:185], v[96:99]
	v_mfma_f32_16x16x32_bf16 v[84:87], v[158:161], v[194:197], v[84:87]
	v_mfma_f32_16x16x32_bf16 v[80:83], v[166:169], v[194:197], v[80:83]
	v_mfma_f32_16x16x32_bf16 v[68:71], v[158:161], v[202:205], v[68:71]
	v_mfma_f32_16x16x32_bf16 v[64:67], v[166:169], v[202:205], v[64:67]
	s_setprio 0
	s_barrier
	ds_read_b128 v[170:173], v135 offset:16384
	ds_read_b128 v[174:177], v135 offset:17408
	ds_read_b128 v[178:181], v135 offset:18432
	ds_read_b128 v[182:185], v135 offset:19456
	ds_read_b128 v[186:189], v135 offset:20480
	ds_read_b128 v[194:197], v135 offset:21504
	ds_read_b128 v[198:201], v135 offset:22528
	ds_read_b128 v[202:205], v135 offset:23552
	s_mov_b32 m0, s28
	s_nop 0
	global_load_lds_dwordx4 v129, s[20:21]
	s_add_u32 s84, s20, 0x20000
	s_mov_b32 m0, s29
	s_nop 0
	global_load_lds_dwordx4 v131, s[20:21]
	s_addc_u32 s85, s21, 0
	s_mov_b32 m0, s30
	s_nop 0
	global_load_lds_dwordx4 v129, s[84:85]
	s_nop 0
	s_mov_b32 m0, s31
	s_nop 0
	global_load_lds_dwordx4 v131, s[84:85]
	s_nop 0
	s_mov_b32 m0, s27
	s_nop 0
	global_load_lds_dwordx4 v128, s[22:23]
	s_nop 0
	s_mov_b32 m0, s33
	s_nop 0
	global_load_lds_dwordx4 v130, s[22:23]
	s_waitcnt vmcnt(8) lgkmcnt(0)
	s_setprio 1
	s_barrier
	v_mfma_f32_16x16x32_bf16 v[60:63], v[138:141], v[170:173], v[60:63]
	v_mfma_f32_16x16x32_bf16 v[56:59], v[146:149], v[170:173], v[56:59]
	v_mfma_f32_16x16x32_bf16 v[44:47], v[138:141], v[178:181], v[44:47]
	v_mfma_f32_16x16x32_bf16 v[40:43], v[146:149], v[178:181], v[40:43]
	v_mfma_f32_16x16x32_bf16 v[28:31], v[138:141], v[186:189], v[28:31]
	v_mfma_f32_16x16x32_bf16 v[24:27], v[146:149], v[186:189], v[24:27]
	v_mfma_f32_16x16x32_bf16 v[12:15], v[138:141], v[198:201], v[12:15]
	v_mfma_f32_16x16x32_bf16 v[8:11], v[146:149], v[198:201], v[8:11]
	v_mfma_f32_16x16x32_bf16 v[60:63], v[142:145], v[174:177], v[60:63]
	v_mfma_f32_16x16x32_bf16 v[56:59], v[150:153], v[174:177], v[56:59]
	v_mfma_f32_16x16x32_bf16 v[44:47], v[142:145], v[182:185], v[44:47]
	v_mfma_f32_16x16x32_bf16 v[40:43], v[150:153], v[182:185], v[40:43]
	v_mfma_f32_16x16x32_bf16 v[28:31], v[142:145], v[194:197], v[28:31]
	v_mfma_f32_16x16x32_bf16 v[24:27], v[150:153], v[194:197], v[24:27]
	v_mfma_f32_16x16x32_bf16 v[12:15], v[142:145], v[202:205], v[12:15]
	v_mfma_f32_16x16x32_bf16 v[8:11], v[150:153], v[202:205], v[8:11]
	v_mfma_f32_16x16x32_bf16 v[52:55], v[154:157], v[170:173], v[52:55]
	v_mfma_f32_16x16x32_bf16 v[48:51], v[162:165], v[170:173], v[48:51]
	v_mfma_f32_16x16x32_bf16 v[36:39], v[154:157], v[178:181], v[36:39]
	v_mfma_f32_16x16x32_bf16 v[32:35], v[162:165], v[178:181], v[32:35]
	v_mfma_f32_16x16x32_bf16 v[20:23], v[154:157], v[186:189], v[20:23]
	v_mfma_f32_16x16x32_bf16 v[16:19], v[162:165], v[186:189], v[16:19]
	v_mfma_f32_16x16x32_bf16 v[4:7], v[154:157], v[198:201], v[4:7]
	v_mfma_f32_16x16x32_bf16 v[0:3], v[162:165], v[198:201], v[0:3]
	v_mfma_f32_16x16x32_bf16 v[52:55], v[158:161], v[174:177], v[52:55]
	v_mfma_f32_16x16x32_bf16 v[48:51], v[166:169], v[174:177], v[48:51]
	v_mfma_f32_16x16x32_bf16 v[36:39], v[158:161], v[182:185], v[36:39]
	v_mfma_f32_16x16x32_bf16 v[32:35], v[166:169], v[182:185], v[32:35]
	v_mfma_f32_16x16x32_bf16 v[20:23], v[158:161], v[194:197], v[20:23]
	v_mfma_f32_16x16x32_bf16 v[16:19], v[166:169], v[194:197], v[16:19]
	v_mfma_f32_16x16x32_bf16 v[4:7], v[158:161], v[202:205], v[4:7]
	v_mfma_f32_16x16x32_bf16 v[0:3], v[166:169], v[202:205], v[0:3]
	s_setprio 0
	s_barrier
; #define PG8_STAGE(bufoff, gbase, voff) do { _Pragma("unroll") for (int _i = 0; _i < 2; ++_i) \
;         asm volatile("s_mov_b32 m0, %0\n\ts_nop 0\n\tglobal_load_lds_dwordx4 %1, %2" :: "s"(ldsb + (unsigned)((bufoff) + _i * 8192)), "v"((voff)[_i]), "s"(gbase) : "m0", "memory"); } while (0)
; #define PG8_LDA(dst, b, h) do { _Pragma("unroll") for (int m = 0; m < 4; ++m) _Pragma("unroll") for (int k = 0; k < 2; ++k) dst[m][k] = *(const PG8_LAS bf16x8*)(lds + PG8_SA(b, h) + aoff + m * 2048 + k * 1024); } while (0)
; #define PG8_LDB(dst, b, h) do { _Pragma("unroll") for (int n = 0; n < 2; ++n) _Pragma("unroll") for (int k = 0; k < 2; ++k) dst[n][k] = *(const PG8_LAS bf16x8*)(lds + PG8_SB(b, h) + boff + n * 2048 + k * 1024); } while (0)
; #define PG8_MMA(ai, bj, At, Bt) do { __builtin_amdgcn_s_setprio(1); _Pragma("unroll") for (int m = 0; m < 4; ++m) _Pragma("unroll") for (int n = 0; n < 2; ++n) _Pragma("unroll") for (int k = 0; k < 2; ++k) \
;         acc[ai][bj][m][n] = __builtin_amdgcn_mfma_f32_16x16x32_bf16(Bt[n][k], At[m][k], acc[ai][bj][m][n], 0, 0, 0); __builtin_amdgcn_s_setprio(0); } while (0)
; #define PG8_WAIT_V(n) asm volatile("s_waitcnt vmcnt(" #n ")" ::: "memory")
; #define PG8_WAIT_L(n) asm volatile("s_waitcnt lgkmcnt(" #n ")" ::: "memory")
; #define PG8_BAR __builtin_amdgcn_s_barrier()
; #define PG8_SCHED __builtin_amdgcn_sched_barrier(0)
; template <class Epi, class Sched, bool ALIGN_EPI = false, bool SP2 = false>
; __device__ __forceinline__ void gemm_phase(PG8_LAS unsigned char* lds, const Gemm g, const Sched& S, const Epi& E, const int wv) {
;     ...
;             PG8_LDB(B0, 1, 0); PG8_LDB(B1, 1, 1); PG8_SCHED; PG8_LDA(At, 1, 0); PG8_STAGE(PG8_SA(0, 1), a2 + hstepA, voffA);
;             PG8_WAIT_V(8); PG8_WAIT_L(0); PG8_BAR; PG8_MMA(0, 0, At, B0); PG8_MMA(0, 1, At, B1); PG8_BAR; PG8_SCHED;
;             PG8_LDA(At, 1, 1); PG8_STAGE(PG8_SB(1, 0), b3, voffB); PG8_STAGE(PG8_SB(1, 1), b3 + hstepB, voffB); PG8_STAGE(PG8_SA(1, 0), a3, voffA);
;             PG8_WAIT_V(8); PG8_WAIT_L(0); PG8_BAR; PG8_MMA(1, 0, At, B0); PG8_MMA(1, 1, At, B1); PG8_BAR; PG8_SCHED;
	ds_read_b128 v[138:141], v251
	ds_read_b128 v[142:145], v251 offset:1024
	ds_read_b128 v[146:149], v251 offset:2048
	ds_read_b128 v[150:153], v251 offset:3072
	ds_read_b128 v[154:157], v250
	ds_read_b128 v[158:161], v250 offset:1024
	ds_read_b128 v[162:165], v250 offset:2048
	ds_read_b128 v[166:169], v250 offset:3072
	ds_read_b128 v[170:173], v135 offset:32768
	ds_read_b128 v[174:177], v135 offset:33792
	ds_read_b128 v[178:181], v135 offset:34816
	ds_read_b128 v[182:185], v135 offset:35840
	ds_read_b128 v[186:189], v135 offset:36864
	ds_read_b128 v[194:197], v135 offset:37888
	ds_read_b128 v[198:201], v135 offset:38912
	ds_read_b128 v[202:205], v135 offset:39936
	s_add_u32 s22, s22, 0x20000
	s_addc_u32 s23, s23, 0
	s_mov_b32 m0, s34
	s_nop 0
	global_load_lds_dwordx4 v128, s[22:23]
	s_nop 0
	s_mov_b32 m0, s35
	s_nop 0
	global_load_lds_dwordx4 v130, s[22:23]
	s_waitcnt vmcnt(8) lgkmcnt(0)
	s_setprio 1
	s_barrier
	v_mfma_f32_16x16x32_bf16 v[124:127], v[138:141], v[170:173], v[124:127]
	v_mfma_f32_16x16x32_bf16 v[120:123], v[146:149], v[170:173], v[120:123]
	v_mfma_f32_16x16x32_bf16 v[108:111], v[138:141], v[178:181], v[108:111]
	v_mfma_f32_16x16x32_bf16 v[104:107], v[146:149], v[178:181], v[104:107]
	v_mfma_f32_16x16x32_bf16 v[92:95], v[138:141], v[186:189], v[92:95]
	v_mfma_f32_16x16x32_bf16 v[88:91], v[146:149], v[186:189], v[88:91]
	v_mfma_f32_16x16x32_bf16 v[76:79], v[138:141], v[198:201], v[76:79]
	v_mfma_f32_16x16x32_bf16 v[72:75], v[146:149], v[198:201], v[72:75]
	v_mfma_f32_16x16x32_bf16 v[124:127], v[142:145], v[174:177], v[124:127]
	v_mfma_f32_16x16x32_bf16 v[120:123], v[150:153], v[174:177], v[120:123]
	v_mfma_f32_16x16x32_bf16 v[108:111], v[142:145], v[182:185], v[108:111]
	v_mfma_f32_16x16x32_bf16 v[104:107], v[150:153], v[182:185], v[104:107]
	v_mfma_f32_16x16x32_bf16 v[92:95], v[142:145], v[194:197], v[92:95]
	v_mfma_f32_16x16x32_bf16 v[88:91], v[150:153], v[194:197], v[88:91]
	v_mfma_f32_16x16x32_bf16 v[76:79], v[142:145], v[202:205], v[76:79]
	v_mfma_f32_16x16x32_bf16 v[72:75], v[150:153], v[202:205], v[72:75]
	v_mfma_f32_16x16x32_bf16 v[116:119], v[154:157], v[170:173], v[116:119]
	v_mfma_f32_16x16x32_bf16 v[112:115], v[162:165], v[170:173], v[112:115]
	v_mfma_f32_16x16x32_bf16 v[100:103], v[154:157], v[178:181], v[100:103]
	v_mfma_f32_16x16x32_bf16 v[96:99], v[162:165], v[178:181], v[96:99]
	v_mfma_f32_16x16x32_bf16 v[84:87], v[154:157], v[186:189], v[84:87]
	v_mfma_f32_16x16x32_bf16 v[80:83], v[162:165], v[186:189], v[80:83]
	v_mfma_f32_16x16x32_bf16 v[68:71], v[154:157], v[198:201], v[68:71]
	v_mfma_f32_16x16x32_bf16 v[64:67], v[162:165], v[198:201], v[64:67]
	v_mfma_f32_16x16x32_bf16 v[116:119], v[158:161], v[174:177], v[116:119]
	v_mfma_f32_16x16x32_bf16 v[112:115], v[166:169], v[174:177], v[112:115]
	v_mfma_f32_16x16x32_bf16 v[100:103], v[158:161], v[182:185], v[100:103]
	v_mfma_f32_16x16x32_bf16 v[96:99], v[166:169], v[182:185], v[96:99]
	v_mfma_f32_16x16x32_bf16 v[84:87], v[158:161], v[194:197], v[84:87]
	v_mfma_f32_16x16x32_bf16 v[80:83], v[166:169], v[194:197], v[80:83]
	v_mfma_f32_16x16x32_bf16 v[68:71], v[158:161], v[202:205], v[68:71]
	v_mfma_f32_16x16x32_bf16 v[64:67], v[166:169], v[202:205], v[64:67]
	s_setprio 0
	s_barrier
	ds_read_b128 v[170:173], v135 offset:49152
	ds_read_b128 v[174:177], v135 offset:50176
	ds_read_b128 v[178:181], v135 offset:51200
	ds_read_b128 v[182:185], v135 offset:52224
	ds_read_b128 v[186:189], v135 offset:53248
	ds_read_b128 v[194:197], v135 offset:54272
	ds_read_b128 v[198:201], v135 offset:55296
	ds_read_b128 v[202:205], v135 offset:56320
	s_add_u32 s22, s20, 0x80
	s_addc_u32 s23, s21, 0
	s_mov_b32 m0, s36
	s_nop 0
	global_load_lds_dwordx4 v129, s[22:23]
	s_add_u32 s20, s20, 0x20080
	s_mov_b32 m0, s37
	s_nop 0
	global_load_lds_dwordx4 v131, s[22:23]
	s_addc_u32 s21, s21, 0
	s_mov_b32 m0, s43
	s_nop 0
	global_load_lds_dwordx4 v129, s[20:21]
	s_nop 0
	s_mov_b32 m0, s44
	s_nop 0
	global_load_lds_dwordx4 v131, s[20:21]
	s_nop 0
	s_mov_b32 m0, s40
	s_nop 0
	global_load_lds_dwordx4 v128, s[18:19]
	s_nop 0
	s_mov_b32 m0, s42
	s_nop 0
	global_load_lds_dwordx4 v130, s[18:19]
	s_waitcnt vmcnt(8) lgkmcnt(0)
	s_setprio 1
	s_barrier
	v_mfma_f32_16x16x32_bf16 v[60:63], v[138:141], v[170:173], v[60:63]
	v_mfma_f32_16x16x32_bf16 v[56:59], v[146:149], v[170:173], v[56:59]
	v_mfma_f32_16x16x32_bf16 v[44:47], v[138:141], v[178:181], v[44:47]
	v_mfma_f32_16x16x32_bf16 v[40:43], v[146:149], v[178:181], v[40:43]
	v_mfma_f32_16x16x32_bf16 v[28:31], v[138:141], v[186:189], v[28:31]
	v_mfma_f32_16x16x32_bf16 v[24:27], v[146:149], v[186:189], v[24:27]
	v_mfma_f32_16x16x32_bf16 v[12:15], v[138:141], v[198:201], v[12:15]
	v_mfma_f32_16x16x32_bf16 v[8:11], v[146:149], v[198:201], v[8:11]
	v_mfma_f32_16x16x32_bf16 v[60:63], v[142:145], v[174:177], v[60:63]
	v_mfma_f32_16x16x32_bf16 v[56:59], v[150:153], v[174:177], v[56:59]
	v_mfma_f32_16x16x32_bf16 v[44:47], v[142:145], v[182:185], v[44:47]
	v_mfma_f32_16x16x32_bf16 v[40:43], v[150:153], v[182:185], v[40:43]
	v_mfma_f32_16x16x32_bf16 v[28:31], v[142:145], v[194:197], v[28:31]
	v_mfma_f32_16x16x32_bf16 v[24:27], v[150:153], v[194:197], v[24:27]
	v_mfma_f32_16x16x32_bf16 v[12:15], v[142:145], v[202:205], v[12:15]
	v_mfma_f32_16x16x32_bf16 v[8:11], v[150:153], v[202:205], v[8:11]
	v_mfma_f32_16x16x32_bf16 v[52:55], v[154:157], v[170:173], v[52:55]
	v_mfma_f32_16x16x32_bf16 v[48:51], v[162:165], v[170:173], v[48:51]
	v_mfma_f32_16x16x32_bf16 v[36:39], v[154:157], v[178:181], v[36:39]
	v_mfma_f32_16x16x32_bf16 v[32:35], v[162:165], v[178:181], v[32:35]
	v_mfma_f32_16x16x32_bf16 v[20:23], v[154:157], v[186:189], v[20:23]
	v_mfma_f32_16x16x32_bf16 v[16:19], v[162:165], v[186:189], v[16:19]
	v_mfma_f32_16x16x32_bf16 v[4:7], v[154:157], v[198:201], v[4:7]
	v_mfma_f32_16x16x32_bf16 v[0:3], v[162:165], v[198:201], v[0:3]
	v_mfma_f32_16x16x32_bf16 v[52:55], v[158:161], v[174:177], v[52:55]
	v_mfma_f32_16x16x32_bf16 v[48:51], v[166:169], v[174:177], v[48:51]
	v_mfma_f32_16x16x32_bf16 v[36:39], v[158:161], v[182:185], v[36:39]
	v_mfma_f32_16x16x32_bf16 v[32:35], v[166:169], v[182:185], v[32:35]
	v_mfma_f32_16x16x32_bf16 v[20:23], v[158:161], v[194:197], v[20:23]
	v_mfma_f32_16x16x32_bf16 v[16:19], v[166:169], v[194:197], v[16:19]
	v_mfma_f32_16x16x32_bf16 v[4:7], v[158:161], v[202:205], v[4:7]
	v_mfma_f32_16x16x32_bf16 v[0:3], v[166:169], v[202:205], v[0:3]
	s_setprio 0
	s_barrier
	s_add_u32 s60, s60, 0x100
	s_addc_u32 s62, s62, 0
	s_add_u32 s65, s65, 0x100
	s_addc_u32 s71, s71, 0
	s_cmp_ge_i32 s72, s55
	s_mov_b32 s18, s72
	s_cbranch_scc0 .LBB0_864
	s_and_b64 vcc, exec, s[10:11]
	s_cbranch_vccz .LBB0_867

; #define PG8_BAR __builtin_amdgcn_s_barrier()
; template <class Epi, class Sched, bool ALIGN_EPI = false, bool SP2 = false>
; __device__ __forceinline__ void gemm_phase(PG8_LAS unsigned char* lds, const Gemm g, const Sched& S, const Epi& E, const int wv) {
;     ...
;     const int tid = tid_of(wv), wid = wid_, lane = tid & 63, wr = wid >> 2, wc = wid & 3, fr = lane & 15, fq = lane >> 4;
;     const int K = g.ld, Kb = g.ldb ? g.ldb : g.ld;
;     unsigned voffA[2], voffB[2];
; #pragma unroll
;     for (int i = 0; i < 2; ++i) { int R, C; stage_rc(tid * 16 + i * 8192, R, C); const int Rb = Epi::PERM ? ((R & ~31) + perm32(R & 31)) : R;
;         voffA[i] = (unsigned)(R * K + C) * 2u; voffB[i] = (unsigned)(Rb * Kb + C) * 2u; }
;     const size_t kstep = (size_t)(BK * 2);
;     const size_t hstepA = (size_t)HALF * K * 2, hstepB = (size_t)HALF * Kb * 2;
;     const size_t tstepA = 2 * hstepA, tstepB = 2 * hstepB;
;     const unsigned ldsw = (unsigned)wid * 1024u;
;     const unsigned ldsb = (unsigned)(size_t)lds + ldsw;
;     const int aoff = lds_byte(wr * 64 + fr, fq * 8), boff = lds_byte(wc * 32 + fr, fq * 8);
;     ...
;         PG8_STAGE(PG8_SB(0, 0), cB, voffB); PG8_STAGE(PG8_SB(0, 1), cB + hstepB, voffB); PG8_STAGE(PG8_SA(0, 0), cA, voffA); PG8_STAGE(PG8_SA(0, 1), cA + hstepA, voffA);
;         if (wr == 1) PG8_BAR;
;         PG8_WAIT_V(2); PG8_BAR;
;         PG8_STAGE(PG8_SB(1, 0), cB + kstep, voffB); PG8_STAGE(PG8_SA(1, 0), cA + kstep, voffA); PG8_STAGE(PG8_SB(1, 1), cB + hstepB + kstep, voffB);
;         PG8_WAIT_V(6); PG8_BAR;
;     __device__ __forceinline__ void operator()(AccT acc, const pg8::Unit& u, int wr, int wc, int fr, int fq) const {
;         const int row0 = u.pm * 256 + wr * 64 + fr, col0 = u.pn * 256 + wc * 32 + 8 * fq, lane = fq * 16 + fr;
;         const int bidx = u.pm < 64 ? (u.pm >> 4) : 4;
;         const float* gp = gate + (size_t)bidx * MODW + col0;
;         f32x4 gv[2][2], gz[2][2];
; #pragma unroll
;         for (int bj = 0; bj < 2; ++bj)
; #pragma unroll
;             for (int n = 0; n < 2; ++n) { gv[bj][n] = *(const f32x4*)(gp + bj * 128 + n * 4) * coef;
;                 if (WZ) gz[bj][n] = *(const f32x4*)(gnext + col0 + bj * 128 + n * 4) * (*(const f32x4*)(scnext + (size_t)bidx * MODW + col0 + bj * 128 + n * 4) + 1.f); }
;         const int st4 = ((lane & 3) * 16 + (lane >> 2)) * 4, ld4 = ((lane & 15) * 4 + (lane >> 4)) * 4;
.LBB0_1012:
	v_readlane_b32 s14, v254, 56
	v_readlane_b32 s15, v254, 57
	s_bfe_u32 s40, s13, 0x80010
	s_bfe_u32 s25, s13, 0x40018
	s_lshl_b64 s[14:15], s[14:15], 2
	s_add_u32 s11, s8, s14
	s_addc_u32 s13, s9, s15
	s_add_u32 s14, s8, 0x44f000
	s_addc_u32 s15, s9, 0
	s_add_u32 s55, s11, 0x2a000
	s_addc_u32 s57, s13, 0
	v_readlane_b32 s18, v254, 62
	s_add_u32 s16, s8, 0x8c4f000
	v_readlane_b32 s19, v254, 63
	s_addc_u32 s17, s9, 0
	s_lshl_b64 s[18:19], s[18:19], 2
	s_add_u32 s6, s6, s18
	s_addc_u32 s7, s7, s19
	s_add_u32 s18, s6, 0x4000
	s_addc_u32 s19, s7, 0
	s_add_u32 s60, s11, 0x2e000
	s_addc_u32 s72, s13, 0
	v_bfe_u32 v1, v0, 4, 2
	s_add_u32 s20, s8, 0x3b98f000
	v_and_b32_e32 v212, 15, v0
	v_lshlrev_b32_e32 v2, 4, v1
	v_lshlrev_b32_e32 v3, 2, v0
	s_addc_u32 s21, s9, 0
	s_and_b32 s11, s12, 3
	v_lshl_or_b32 v2, v212, 6, v2
	s_lshl_b32 s6, s24, 13
	v_and_b32_e32 v3, 32, v3
	s_lshl_b32 s83, s24, 6
	v_bitop3_b32 v4, v2, s6, v3 bitop3:0xde
	s_lshl_b32 s13, s11, 5
	s_lshl_b32 s6, s11, 12
	s_add_i32 s84, s47, 0x18000
	v_bitop3_b32 v3, v2, s6, v3 bitop3:0xde
	s_add_u32 s6, s30, 0x80
	s_waitcnt vmcnt(2)
	s_barrier
	s_addc_u32 s7, s31, 0
	s_mov_b32 m0, s84
	s_nop 0
	global_load_lds_dwordx4 v209, s[6:7]
	s_add_i32 s71, s47, 0x1a000
	s_add_i32 s87, s47, 0x8000
	s_mov_b32 m0, s71
	s_nop 0
	global_load_lds_dwordx4 v211, s[6:7]
	s_add_u32 s6, s34, 0x80
	s_addc_u32 s7, s35, 0
	s_mov_b32 m0, s87
	s_nop 0
	global_load_lds_dwordx4 v208, s[6:7]
	s_add_i32 s89, s47, 0xa000
	s_add_i32 s92, s47, 0x1c000
	s_mov_b32 m0, s89
	s_nop 0
	global_load_lds_dwordx4 v210, s[6:7]
	s_add_u32 s6, s22, 0x80
	s_addc_u32 s7, s23, 0
	s_add_i32 s58, s47, 0x1e000
	s_add_i32 s88, s47, 0xc000
	s_mov_b32 m0, s92
	s_nop 0
	global_load_lds_dwordx4 v209, s[6:7]
	s_cmp_lt_u32 s12, 4
	s_mov_b32 m0, s58
	s_nop 0
	global_load_lds_dwordx4 v211, s[6:7]
	s_cselect_b64 s[22:23], -1, 0
	s_ashr_i32 s6, s83, 31
	s_add_i32 s93, s47, 0xe000
	s_lshl_b32 s11, s11, 2
	v_lshrrev_b32_e32 v5, 2, v0
	s_add_u32 s8, s8, s11
	s_waitcnt vmcnt(6)
	v_and_b32_e32 v2, 3, v0
	v_and_b32_e32 v6, 60, v0
	v_and_or_b32 v172, v5, 15, s83
	v_and_b32_e32 v5, 63, v0
	v_bfe_u32 v215, v0, 2, 4
	v_lshlrev_b32_e32 v0, 4, v212
	s_addc_u32 s9, s9, 0
	v_lshl_or_b32 v214, v2, 6, v6
	v_lshlrev_b32_e32 v2, 3, v2
	v_lshl_or_b32 v216, v1, 2, v0
	v_lshlrev_b32_e32 v0, 2, v5
	s_add_u32 s94, s8, 0x21e000
	v_lshl_or_b32 v213, v1, 3, s13
	v_mov_b32_e32 v173, s6
	v_or_b32_e32 v217, s13, v2
	v_xor_b32_e32 v218, 64, v0
	v_xor_b32_e32 v219, 0x80, v0
	s_mov_b32 s90, 0
	v_cmp_eq_u32_e64 s[6:7], 0, v1
	s_addc_u32 s97, s9, 0
	s_ashr_i32 s56, s70, 31
	v_add_u32_e32 v220, 0, v3
	v_add_u32_e32 v253, 0x10000, v220
	v_add_u32_e32 v252, 0x14000, v220
	v_add_u32_e32 v251, 0x18000, v220
	v_add_u32_e32 v250, 0x1c000, v220
	v_add_u32_e32 v221, 0, v4
	s_lshl_b32 s24, s13, 1
	v_lshlrev_b32_e32 v174, 1, v2
	s_barrier
	s_branch .LBB0_1015

; #define PG8_STAGE(bufoff, gbase, voff) do { _Pragma("unroll") for (int _i = 0; _i < 2; ++_i) \
;         asm volatile("s_mov_b32 m0, %0\n\ts_nop 0\n\tglobal_load_lds_dwordx4 %1, %2" :: "s"(ldsb + (unsigned)((bufoff) + _i * 8192)), "v"((voff)[_i]), "s"(gbase) : "m0", "memory"); } while (0)
; #define PG8_LDA(dst, b, h) do { _Pragma("unroll") for (int m = 0; m < 4; ++m) _Pragma("unroll") for (int k = 0; k < 2; ++k) dst[m][k] = *(const PG8_LAS bf16x8*)(lds + PG8_SA(b, h) + aoff + m * 2048 + k * 1024); } while (0)
; #define PG8_LDB(dst, b, h) do { _Pragma("unroll") for (int n = 0; n < 2; ++n) _Pragma("unroll") for (int k = 0; k < 2; ++k) dst[n][k] = *(const PG8_LAS bf16x8*)(lds + PG8_SB(b, h) + boff + n * 2048 + k * 1024); } while (0)
; #define PG8_MMA(ai, bj, At, Bt) do { __builtin_amdgcn_s_setprio(1); _Pragma("unroll") for (int m = 0; m < 4; ++m) _Pragma("unroll") for (int n = 0; n < 2; ++n) _Pragma("unroll") for (int k = 0; k < 2; ++k) \
;         acc[ai][bj][m][n] = __builtin_amdgcn_mfma_f32_16x16x32_bf16(Bt[n][k], At[m][k], acc[ai][bj][m][n], 0, 0, 0); __builtin_amdgcn_s_setprio(0); } while (0)
; #define PG8_WAIT_V(n) asm volatile("s_waitcnt vmcnt(" #n ")" ::: "memory")
; #define PG8_WAIT_L(n) asm volatile("s_waitcnt lgkmcnt(" #n ")" ::: "memory")
; template <class Epi, class Sched, bool ALIGN_EPI = false, bool SP2 = false>
; __device__ __forceinline__ void gemm_phase(PG8_LAS unsigned char* lds, const Gemm g, const Sched& S, const Epi& E, const int wv) {
;     ...
;             const bool last = (t == nt - 2);
;             const char* a1 = cA + (size_t)(t + 1) * kstep;
;             const char* a2 = last ? nA : cA + (size_t)(t + 2) * kstep; const char* b2 = last ? nB : cB + (size_t)(t + 2) * kstep;
;             const char* a3 = a2 + kstep; const char* b3 = b2 + kstep;
;             if (last && has_next) S.a_ready(nxt);
;             if constexpr (SP2) {
;             PG8_LDB(B0, 0, 0); PG8_LDB(B1, 0, 1); PG8_SCHED; PG8_LDA(At, 0, 0); PG8_STAGE(PG8_SA(1, 1), a1 + hstepA, voffA);
;             PG8_WAIT_V(8); PG8_WAIT_L(0); PG8_BAR; PG8_MMA(0, 0, At, B0); PG8_MMA(0, 1, At, B1); PG8_BAR; PG8_SCHED;
;             PG8_LDA(At, 0, 1); PG8_STAGE(PG8_SB(0, 0), b2, voffB); PG8_STAGE(PG8_SB(0, 1), b2 + hstepB, voffB); PG8_STAGE(PG8_SA(0, 0), a2, voffA);
;             PG8_WAIT_V(8); PG8_WAIT_L(0); PG8_BAR; PG8_MMA(1, 0, At, B0); PG8_MMA(1, 1, At, B1); PG8_BAR; PG8_SCHED;
.LBB0_1031:
	ds_read_b128 v[108:111], v253
	ds_read_b128 v[116:119], v253 offset:1024
	ds_read_b128 v[120:123], v253 offset:2048
	ds_read_b128 v[124:127], v253 offset:3072
	ds_read_b128 v[144:147], v252
	ds_read_b128 v[148:151], v252 offset:1024
	ds_read_b128 v[152:155], v252 offset:2048
	ds_read_b128 v[156:159], v252 offset:3072
	s_add_i32 s12, s34, 2
	s_cmp_eq_u32 s11, s34
	s_cselect_b32 s42, s26, vcc_lo
	s_cselect_b32 s43, s27, vcc_hi
	s_cselect_b32 s36, s28, s79
	s_cselect_b32 s37, s29, s62
	s_add_u32 s34, s42, 0x80
	s_addc_u32 s35, s43, 0
	ds_read_b128 v[160:163], v221
	ds_read_b128 v[164:167], v221 offset:1024
	ds_read_b128 v[168:171], v221 offset:2048
	ds_read_b128 v[176:179], v221 offset:3072
	ds_read_b128 v[180:183], v221 offset:4096
	ds_read_b128 v[184:187], v221 offset:5120
	ds_read_b128 v[188:191], v221 offset:6144
	ds_read_b128 v[194:197], v221 offset:7168
	s_mov_b32 m0, s88
	s_nop 0
	global_load_lds_dwordx4 v208, s[30:31]
	s_nop 0
	s_mov_b32 m0, s93
	s_nop 0
	global_load_lds_dwordx4 v210, s[30:31]
	s_waitcnt vmcnt(8) lgkmcnt(0)
	s_setprio 1
	s_barrier
	v_mfma_f32_16x16x32_bf16 v[140:143], v[108:111], v[160:163], v[140:143]
	v_mfma_f32_16x16x32_bf16 v[136:139], v[120:123], v[160:163], v[136:139]
	v_mfma_f32_16x16x32_bf16 v[112:115], v[108:111], v[168:171], v[112:115]
	v_mfma_f32_16x16x32_bf16 v[104:107], v[120:123], v[168:171], v[104:107]
	v_mfma_f32_16x16x32_bf16 v[92:95], v[108:111], v[180:183], v[92:95]
	v_mfma_f32_16x16x32_bf16 v[88:91], v[120:123], v[180:183], v[88:91]
	v_mfma_f32_16x16x32_bf16 v[76:79], v[108:111], v[188:191], v[76:79]
	v_mfma_f32_16x16x32_bf16 v[72:75], v[120:123], v[188:191], v[72:75]
	v_mfma_f32_16x16x32_bf16 v[140:143], v[116:119], v[164:167], v[140:143]
	v_mfma_f32_16x16x32_bf16 v[136:139], v[124:127], v[164:167], v[136:139]
	v_mfma_f32_16x16x32_bf16 v[112:115], v[116:119], v[176:179], v[112:115]
	v_mfma_f32_16x16x32_bf16 v[104:107], v[124:127], v[176:179], v[104:107]
	v_mfma_f32_16x16x32_bf16 v[92:95], v[116:119], v[184:187], v[92:95]
	v_mfma_f32_16x16x32_bf16 v[88:91], v[124:127], v[184:187], v[88:91]
	v_mfma_f32_16x16x32_bf16 v[76:79], v[116:119], v[194:197], v[76:79]
	v_mfma_f32_16x16x32_bf16 v[72:75], v[124:127], v[194:197], v[72:75]
	v_mfma_f32_16x16x32_bf16 v[132:135], v[144:147], v[160:163], v[132:135]
	v_mfma_f32_16x16x32_bf16 v[128:131], v[152:155], v[160:163], v[128:131]
	v_mfma_f32_16x16x32_bf16 v[100:103], v[144:147], v[168:171], v[100:103]
	v_mfma_f32_16x16x32_bf16 v[96:99], v[152:155], v[168:171], v[96:99]
	v_mfma_f32_16x16x32_bf16 v[84:87], v[144:147], v[180:183], v[84:87]
	v_mfma_f32_16x16x32_bf16 v[80:83], v[152:155], v[180:183], v[80:83]
	v_mfma_f32_16x16x32_bf16 v[68:71], v[144:147], v[188:191], v[68:71]
	v_mfma_f32_16x16x32_bf16 v[64:67], v[152:155], v[188:191], v[64:67]
	v_mfma_f32_16x16x32_bf16 v[132:135], v[148:151], v[164:167], v[132:135]
	v_mfma_f32_16x16x32_bf16 v[128:131], v[156:159], v[164:167], v[128:131]
	v_mfma_f32_16x16x32_bf16 v[100:103], v[148:151], v[176:179], v[100:103]
	v_mfma_f32_16x16x32_bf16 v[96:99], v[156:159], v[176:179], v[96:99]
	v_mfma_f32_16x16x32_bf16 v[84:87], v[148:151], v[184:187], v[84:87]
	v_mfma_f32_16x16x32_bf16 v[80:83], v[156:159], v[184:187], v[80:83]
	v_mfma_f32_16x16x32_bf16 v[68:71], v[148:151], v[194:197], v[68:71]
	v_mfma_f32_16x16x32_bf16 v[64:67], v[156:159], v[194:197], v[64:67]
	s_setprio 0
	s_barrier
	ds_read_b128 v[160:163], v221 offset:16384
	ds_read_b128 v[164:167], v221 offset:17408
	ds_read_b128 v[168:171], v221 offset:18432
	ds_read_b128 v[176:179], v221 offset:19456
	ds_read_b128 v[180:183], v221 offset:20480
	ds_read_b128 v[184:187], v221 offset:21504
	ds_read_b128 v[188:191], v221 offset:22528
	ds_read_b128 v[194:197], v221 offset:23552
	s_mov_b32 m0, s48
	s_nop 0
	global_load_lds_dwordx4 v209, s[36:37]
	s_add_u32 s44, s36, 0x80000
	s_mov_b32 m0, s49
	s_nop 0
	global_load_lds_dwordx4 v211, s[36:37]
	s_addc_u32 s45, s37, 0
	s_mov_b32 m0, s50
	s_nop 0
	global_load_lds_dwordx4 v209, s[44:45]
	s_nop 0
	s_mov_b32 m0, s51
	s_nop 0
	global_load_lds_dwordx4 v211, s[44:45]
	s_nop 0
	s_mov_b32 m0, s47
	s_nop 0
	global_load_lds_dwordx4 v208, s[42:43]
	s_nop 0
	s_mov_b32 m0, s52
	s_nop 0
	global_load_lds_dwordx4 v210, s[42:43]
	s_waitcnt vmcnt(8) lgkmcnt(0)
	s_setprio 1
	s_barrier
	v_mfma_f32_16x16x32_bf16 v[60:63], v[108:111], v[160:163], v[60:63]
	v_mfma_f32_16x16x32_bf16 v[56:59], v[120:123], v[160:163], v[56:59]
	v_mfma_f32_16x16x32_bf16 v[44:47], v[108:111], v[168:171], v[44:47]
	v_mfma_f32_16x16x32_bf16 v[40:43], v[120:123], v[168:171], v[40:43]
	v_mfma_f32_16x16x32_bf16 v[28:31], v[108:111], v[180:183], v[28:31]
	v_mfma_f32_16x16x32_bf16 v[24:27], v[120:123], v[180:183], v[24:27]
	v_mfma_f32_16x16x32_bf16 v[12:15], v[108:111], v[188:191], v[12:15]
	v_mfma_f32_16x16x32_bf16 v[8:11], v[120:123], v[188:191], v[8:11]
	v_mfma_f32_16x16x32_bf16 v[60:63], v[116:119], v[164:167], v[60:63]
	v_mfma_f32_16x16x32_bf16 v[56:59], v[124:127], v[164:167], v[56:59]
	v_mfma_f32_16x16x32_bf16 v[44:47], v[116:119], v[176:179], v[44:47]
	v_mfma_f32_16x16x32_bf16 v[40:43], v[124:127], v[176:179], v[40:43]
	v_mfma_f32_16x16x32_bf16 v[28:31], v[116:119], v[184:187], v[28:31]
	v_mfma_f32_16x16x32_bf16 v[24:27], v[124:127], v[184:187], v[24:27]
	v_mfma_f32_16x16x32_bf16 v[12:15], v[116:119], v[194:197], v[12:15]
	v_mfma_f32_16x16x32_bf16 v[8:11], v[124:127], v[194:197], v[8:11]
	v_mfma_f32_16x16x32_bf16 v[52:55], v[144:147], v[160:163], v[52:55]
	v_mfma_f32_16x16x32_bf16 v[48:51], v[152:155], v[160:163], v[48:51]
	v_mfma_f32_16x16x32_bf16 v[36:39], v[144:147], v[168:171], v[36:39]
	v_mfma_f32_16x16x32_bf16 v[32:35], v[152:155], v[168:171], v[32:35]
	v_mfma_f32_16x16x32_bf16 v[20:23], v[144:147], v[180:183], v[20:23]
	v_mfma_f32_16x16x32_bf16 v[16:19], v[152:155], v[180:183], v[16:19]
	v_mfma_f32_16x16x32_bf16 v[4:7], v[144:147], v[188:191], v[4:7]
	v_mfma_f32_16x16x32_bf16 v[0:3], v[152:155], v[188:191], v[0:3]
	v_mfma_f32_16x16x32_bf16 v[52:55], v[148:151], v[164:167], v[52:55]
	v_mfma_f32_16x16x32_bf16 v[48:51], v[156:159], v[164:167], v[48:51]
	v_mfma_f32_16x16x32_bf16 v[36:39], v[148:151], v[176:179], v[36:39]
	v_mfma_f32_16x16x32_bf16 v[32:35], v[156:159], v[176:179], v[32:35]
	v_mfma_f32_16x16x32_bf16 v[20:23], v[148:151], v[184:187], v[20:23]
	v_mfma_f32_16x16x32_bf16 v[16:19], v[156:159], v[184:187], v[16:19]
	v_mfma_f32_16x16x32_bf16 v[4:7], v[148:151], v[194:197], v[4:7]
	v_mfma_f32_16x16x32_bf16 v[0:3], v[156:159], v[194:197], v[0:3]
	s_setprio 0
	s_barrier
; #define PG8_STAGE(bufoff, gbase, voff) do { _Pragma("unroll") for (int _i = 0; _i < 2; ++_i) \
;         asm volatile("s_mov_b32 m0, %0\n\ts_nop 0\n\tglobal_load_lds_dwordx4 %1, %2" :: "s"(ldsb + (unsigned)((bufoff) + _i * 8192)), "v"((voff)[_i]), "s"(gbase) : "m0", "memory"); } while (0)
; #define PG8_LDA(dst, b, h) do { _Pragma("unroll") for (int m = 0; m < 4; ++m) _Pragma("unroll") for (int k = 0; k < 2; ++k) dst[m][k] = *(const PG8_LAS bf16x8*)(lds + PG8_SA(b, h) + aoff + m * 2048 + k * 1024); } while (0)
; #define PG8_LDB(dst, b, h) do { _Pragma("unroll") for (int n = 0; n < 2; ++n) _Pragma("unroll") for (int k = 0; k < 2; ++k) dst[n][k] = *(const PG8_LAS bf16x8*)(lds + PG8_SB(b, h) + boff + n * 2048 + k * 1024); } while (0)
; #define PG8_MMA(ai, bj, At, Bt) do { __builtin_amdgcn_s_setprio(1); _Pragma("unroll") for (int m = 0; m < 4; ++m) _Pragma("unroll") for (int n = 0; n < 2; ++n) _Pragma("unroll") for (int k = 0; k < 2; ++k) \
;         acc[ai][bj][m][n] = __builtin_amdgcn_mfma_f32_16x16x32_bf16(Bt[n][k], At[m][k], acc[ai][bj][m][n], 0, 0, 0); __builtin_amdgcn_s_setprio(0); } while (0)
; #define PG8_WAIT_V(n) asm volatile("s_waitcnt vmcnt(" #n ")" ::: "memory")
; #define PG8_WAIT_L(n) asm volatile("s_waitcnt lgkmcnt(" #n ")" ::: "memory")
; #define PG8_BAR __builtin_amdgcn_s_barrier()
; #define PG8_SCHED __builtin_amdgcn_sched_barrier(0)
; template <class Epi, class Sched, bool ALIGN_EPI = false, bool SP2 = false>
; __device__ __forceinline__ void gemm_phase(PG8_LAS unsigned char* lds, const Gemm g, const Sched& S, const Epi& E, const int wv) {
;     ...
;             PG8_LDB(B0, 1, 0); PG8_LDB(B1, 1, 1); PG8_SCHED; PG8_LDA(At, 1, 0); PG8_STAGE(PG8_SA(0, 1), a2 + hstepA, voffA);
;             PG8_WAIT_V(8); PG8_WAIT_L(0); PG8_BAR; PG8_MMA(0, 0, At, B0); PG8_MMA(0, 1, At, B1); PG8_BAR; PG8_SCHED;
;             PG8_LDA(At, 1, 1); PG8_STAGE(PG8_SB(1, 0), b3, voffB); PG8_STAGE(PG8_SB(1, 1), b3 + hstepB, voffB); PG8_STAGE(PG8_SA(1, 0), a3, voffA);
;             PG8_WAIT_V(8); PG8_WAIT_L(0); PG8_BAR; PG8_MMA(1, 0, At, B0); PG8_MMA(1, 1, At, B1); PG8_BAR; PG8_SCHED;
	ds_read_b128 v[108:111], v251
	ds_read_b128 v[116:119], v251 offset:1024
	ds_read_b128 v[120:123], v251 offset:2048
	ds_read_b128 v[124:127], v251 offset:3072
	ds_read_b128 v[144:147], v250
	ds_read_b128 v[148:151], v250 offset:1024
	ds_read_b128 v[152:155], v250 offset:2048
	ds_read_b128 v[156:159], v250 offset:3072
	ds_read_b128 v[160:163], v221 offset:32768
	ds_read_b128 v[164:167], v221 offset:33792
	ds_read_b128 v[168:171], v221 offset:34816
	ds_read_b128 v[176:179], v221 offset:35840
	ds_read_b128 v[180:183], v221 offset:36864
	ds_read_b128 v[184:187], v221 offset:37888
	ds_read_b128 v[188:191], v221 offset:38912
	ds_read_b128 v[194:197], v221 offset:39936
	s_add_u32 s42, s42, 0x84000
	s_addc_u32 s43, s43, 0
	s_mov_b32 m0, s53
	s_nop 0
	global_load_lds_dwordx4 v208, s[42:43]
	s_nop 0
	s_mov_b32 m0, s54
	s_nop 0
	global_load_lds_dwordx4 v210, s[42:43]
	s_waitcnt vmcnt(8) lgkmcnt(0)
	s_setprio 1
	s_barrier
	v_mfma_f32_16x16x32_bf16 v[140:143], v[108:111], v[160:163], v[140:143]
	v_mfma_f32_16x16x32_bf16 v[136:139], v[120:123], v[160:163], v[136:139]
	v_mfma_f32_16x16x32_bf16 v[112:115], v[108:111], v[168:171], v[112:115]
	v_mfma_f32_16x16x32_bf16 v[104:107], v[120:123], v[168:171], v[104:107]
	v_mfma_f32_16x16x32_bf16 v[92:95], v[108:111], v[180:183], v[92:95]
	v_mfma_f32_16x16x32_bf16 v[88:91], v[120:123], v[180:183], v[88:91]
	v_mfma_f32_16x16x32_bf16 v[76:79], v[108:111], v[188:191], v[76:79]
	v_mfma_f32_16x16x32_bf16 v[72:75], v[120:123], v[188:191], v[72:75]
	v_mfma_f32_16x16x32_bf16 v[140:143], v[116:119], v[164:167], v[140:143]
	v_mfma_f32_16x16x32_bf16 v[136:139], v[124:127], v[164:167], v[136:139]
	v_mfma_f32_16x16x32_bf16 v[112:115], v[116:119], v[176:179], v[112:115]
	v_mfma_f32_16x16x32_bf16 v[104:107], v[124:127], v[176:179], v[104:107]
	v_mfma_f32_16x16x32_bf16 v[92:95], v[116:119], v[184:187], v[92:95]
	v_mfma_f32_16x16x32_bf16 v[88:91], v[124:127], v[184:187], v[88:91]
	v_mfma_f32_16x16x32_bf16 v[76:79], v[116:119], v[194:197], v[76:79]
	v_mfma_f32_16x16x32_bf16 v[72:75], v[124:127], v[194:197], v[72:75]
	v_mfma_f32_16x16x32_bf16 v[132:135], v[144:147], v[160:163], v[132:135]
	v_mfma_f32_16x16x32_bf16 v[128:131], v[152:155], v[160:163], v[128:131]
	v_mfma_f32_16x16x32_bf16 v[100:103], v[144:147], v[168:171], v[100:103]
	v_mfma_f32_16x16x32_bf16 v[96:99], v[152:155], v[168:171], v[96:99]
	v_mfma_f32_16x16x32_bf16 v[84:87], v[144:147], v[180:183], v[84:87]
	v_mfma_f32_16x16x32_bf16 v[80:83], v[152:155], v[180:183], v[80:83]
	v_mfma_f32_16x16x32_bf16 v[68:71], v[144:147], v[188:191], v[68:71]
	v_mfma_f32_16x16x32_bf16 v[64:67], v[152:155], v[188:191], v[64:67]
	v_mfma_f32_16x16x32_bf16 v[132:135], v[148:151], v[164:167], v[132:135]
	v_mfma_f32_16x16x32_bf16 v[128:131], v[156:159], v[164:167], v[128:131]
	v_mfma_f32_16x16x32_bf16 v[100:103], v[148:151], v[176:179], v[100:103]
	v_mfma_f32_16x16x32_bf16 v[96:99], v[156:159], v[176:179], v[96:99]
	v_mfma_f32_16x16x32_bf16 v[84:87], v[148:151], v[184:187], v[84:87]
	v_mfma_f32_16x16x32_bf16 v[80:83], v[156:159], v[184:187], v[80:83]
	v_mfma_f32_16x16x32_bf16 v[68:71], v[148:151], v[194:197], v[68:71]
	v_mfma_f32_16x16x32_bf16 v[64:67], v[156:159], v[194:197], v[64:67]
	s_setprio 0
	s_barrier
	ds_read_b128 v[160:163], v221 offset:49152
	ds_read_b128 v[164:167], v221 offset:50176
	ds_read_b128 v[168:171], v221 offset:51200
	ds_read_b128 v[176:179], v221 offset:52224
	ds_read_b128 v[180:183], v221 offset:53248
	ds_read_b128 v[184:187], v221 offset:54272
	ds_read_b128 v[188:191], v221 offset:55296
	ds_read_b128 v[194:197], v221 offset:56320
	s_add_u32 s42, s36, 0x80
	s_addc_u32 s43, s37, 0
	s_mov_b32 m0, s84
	s_nop 0
	global_load_lds_dwordx4 v209, s[42:43]
	s_add_u32 s36, s36, 0x80080
	s_mov_b32 m0, s71
	s_nop 0
	global_load_lds_dwordx4 v211, s[42:43]
	s_addc_u32 s37, s37, 0
	s_mov_b32 m0, s92
	s_nop 0
	global_load_lds_dwordx4 v209, s[36:37]
	s_nop 0
	s_mov_b32 m0, s58
	s_nop 0
	global_load_lds_dwordx4 v211, s[36:37]
	s_nop 0
	s_mov_b32 m0, s87
	s_nop 0
	global_load_lds_dwordx4 v208, s[34:35]
	s_nop 0
	s_mov_b32 m0, s89
	s_nop 0
	global_load_lds_dwordx4 v210, s[34:35]
	s_waitcnt vmcnt(8) lgkmcnt(0)
	s_setprio 1
	s_barrier
	v_mfma_f32_16x16x32_bf16 v[60:63], v[108:111], v[160:163], v[60:63]
	v_mfma_f32_16x16x32_bf16 v[56:59], v[120:123], v[160:163], v[56:59]
	v_mfma_f32_16x16x32_bf16 v[44:47], v[108:111], v[168:171], v[44:47]
	v_mfma_f32_16x16x32_bf16 v[40:43], v[120:123], v[168:171], v[40:43]
	v_mfma_f32_16x16x32_bf16 v[28:31], v[108:111], v[180:183], v[28:31]
	v_mfma_f32_16x16x32_bf16 v[24:27], v[120:123], v[180:183], v[24:27]
	v_mfma_f32_16x16x32_bf16 v[12:15], v[108:111], v[188:191], v[12:15]
	v_mfma_f32_16x16x32_bf16 v[8:11], v[120:123], v[188:191], v[8:11]
	v_mfma_f32_16x16x32_bf16 v[60:63], v[116:119], v[164:167], v[60:63]
	v_mfma_f32_16x16x32_bf16 v[56:59], v[124:127], v[164:167], v[56:59]
	v_mfma_f32_16x16x32_bf16 v[44:47], v[116:119], v[176:179], v[44:47]
	v_mfma_f32_16x16x32_bf16 v[40:43], v[124:127], v[176:179], v[40:43]
	v_mfma_f32_16x16x32_bf16 v[28:31], v[116:119], v[184:187], v[28:31]
	v_mfma_f32_16x16x32_bf16 v[24:27], v[124:127], v[184:187], v[24:27]
	v_mfma_f32_16x16x32_bf16 v[12:15], v[116:119], v[194:197], v[12:15]
	v_mfma_f32_16x16x32_bf16 v[8:11], v[124:127], v[194:197], v[8:11]
	v_mfma_f32_16x16x32_bf16 v[52:55], v[144:147], v[160:163], v[52:55]
	v_mfma_f32_16x16x32_bf16 v[48:51], v[152:155], v[160:163], v[48:51]
	v_mfma_f32_16x16x32_bf16 v[36:39], v[144:147], v[168:171], v[36:39]
	v_mfma_f32_16x16x32_bf16 v[32:35], v[152:155], v[168:171], v[32:35]
	v_mfma_f32_16x16x32_bf16 v[20:23], v[144:147], v[180:183], v[20:23]
	v_mfma_f32_16x16x32_bf16 v[16:19], v[152:155], v[180:183], v[16:19]
	v_mfma_f32_16x16x32_bf16 v[4:7], v[144:147], v[188:191], v[4:7]
	v_mfma_f32_16x16x32_bf16 v[0:3], v[152:155], v[188:191], v[0:3]
	v_mfma_f32_16x16x32_bf16 v[52:55], v[148:151], v[164:167], v[52:55]
	v_mfma_f32_16x16x32_bf16 v[48:51], v[156:159], v[164:167], v[48:51]
	v_mfma_f32_16x16x32_bf16 v[36:39], v[148:151], v[176:179], v[36:39]
	v_mfma_f32_16x16x32_bf16 v[32:35], v[156:159], v[176:179], v[32:35]
	v_mfma_f32_16x16x32_bf16 v[20:23], v[148:151], v[184:187], v[20:23]
	v_mfma_f32_16x16x32_bf16 v[16:19], v[156:159], v[184:187], v[16:19]
	v_mfma_f32_16x16x32_bf16 v[4:7], v[148:151], v[194:197], v[4:7]
	v_mfma_f32_16x16x32_bf16 v[0:3], v[156:159], v[194:197], v[0:3]
	s_setprio 0
	s_barrier
	s_add_u32 vcc_lo, vcc_lo, 0x100
	s_addc_u32 vcc_hi, vcc_hi, 0
	s_add_u32 s79, s79, 0x100
	s_addc_u32 s62, s62, 0
	s_add_u32 s30, s30, 0x100
	s_addc_u32 s31, s31, 0
	s_cmp_ge_i32 s12, s40
	s_mov_b32 s34, s12
	s_cbranch_scc0 .LBB0_1031
	s_mov_b32 s79, 0xc00000
	s_and_b64 vcc, exec, s[22:23]
	s_cbranch_vccz .LBB0_1034

; __device__ __forceinline__ int tid_of(int wave_s) { int w = wave_s; asm volatile("" : "+s"(w)); int l; asm volatile("v_mbcnt_lo_u32_b32 %0, -1, 0\n\tv_mbcnt_hi_u32_b32 %0, -1, %0" : "=v"(l)); return w * 64 + l; }
; #define PG8_STAGE(bufoff, gbase, voff) do { _Pragma("unroll") for (int _i = 0; _i < 2; ++_i) \
;         asm volatile("s_mov_b32 m0, %0\n\ts_nop 0\n\tglobal_load_lds_dwordx4 %1, %2" :: "s"(ldsb + (unsigned)((bufoff) + _i * 8192)), "v"((voff)[_i]), "s"(gbase) : "m0", "memory"); } while (0)
; #define PG8_WAIT_V(n) asm volatile("s_waitcnt vmcnt(" #n ")" ::: "memory")
; #define PG8_BAR __builtin_amdgcn_s_barrier()
; template <class Epi, class Sched, bool ALIGN_EPI = false, bool SP2 = false>
; __device__ __forceinline__ void gemm_phase(PG8_LAS unsigned char* lds, const Gemm g, const Sched& S, const Epi& E, const int wv) {
;     ...
;     const int tid = tid_of(wv), wid = wid_, lane = tid & 63, wr = wid >> 2, wc = wid & 3, fr = lane & 15, fq = lane >> 4;
;     const int K = g.ld, Kb = g.ldb ? g.ldb : g.ld;
;     unsigned voffA[2], voffB[2];
; #pragma unroll
;     for (int i = 0; i < 2; ++i) { int R, C; stage_rc(tid * 16 + i * 8192, R, C); const int Rb = Epi::PERM ? ((R & ~31) + perm32(R & 31)) : R;
;         voffA[i] = (unsigned)(R * K + C) * 2u; voffB[i] = (unsigned)(Rb * Kb + C) * 2u; }
;     const size_t kstep = (size_t)(BK * 2);
;     const size_t hstepA = (size_t)HALF * K * 2, hstepB = (size_t)HALF * Kb * 2;
;     const size_t tstepA = 2 * hstepA, tstepB = 2 * hstepB;
;     const unsigned ldsw = (unsigned)wid * 1024u;
;     const unsigned ldsb = (unsigned)(size_t)lds + ldsw;
;     const int aoff = lds_byte(wr * 64 + fr, fq * 8), boff = lds_byte(wc * 32 + fr, fq * 8);
;     ...
;         PG8_STAGE(PG8_SB(0, 0), cB, voffB); PG8_STAGE(PG8_SB(0, 1), cB + hstepB, voffB); PG8_STAGE(PG8_SA(0, 0), cA, voffA); PG8_STAGE(PG8_SA(0, 1), cA + hstepA, voffA);
;         if (wr == 1) PG8_BAR;
;         PG8_WAIT_V(2); PG8_BAR;
;         PG8_STAGE(PG8_SB(1, 0), cB + kstep, voffB); PG8_STAGE(PG8_SA(1, 0), cA + kstep, voffA); PG8_STAGE(PG8_SB(1, 1), cB + hstepB + kstep, voffB);
;         PG8_WAIT_V(6); PG8_BAR;
.LBB0_1166:
	s_bfe_u32 s40, s10, 0x80010
	s_add_u32 s10, s14, 0xd26f000
	s_addc_u32 s11, s15, 0
	v_readlane_b32 s18, v254, 54
	s_add_u32 s12, s14, 0x43e000
	v_readlane_b32 s19, v254, 55
	s_addc_u32 s13, s15, 0
	s_lshl_b64 s[18:19], s[18:19], 2
	s_add_u32 s2, s14, s18
	s_addc_u32 s14, s15, s19
	v_bfe_u32 v1, v0, 4, 2
	s_add_u32 s44, s2, 0x142000
	v_and_b32_e32 v155, 15, v0
	v_lshlrev_b32_e32 v2, 3, v1
	v_lshlrev_b32_e32 v1, 4, v1
	v_lshlrev_b32_e32 v3, 2, v0
	s_addc_u32 s45, s14, 0
	v_lshl_or_b32 v1, v155, 6, v1
	s_lshl_b32 s2, s16, 13
	v_and_b32_e32 v3, 32, v3
	v_bitop3_b32 v4, v1, s2, v3 bitop3:0xde
	s_lshl_b32 s2, s7, 5
	s_and_b32 s47, s2, 0x60
	s_lshl_b32 s46, s16, 6
	s_lshl_b32 s2, s47, 7
	s_add_i32 s48, s31, 0x18000
	s_add_u32 s14, s22, 0x80
	s_waitcnt vmcnt(2)
	s_barrier
	s_addc_u32 s15, s23, 0
	s_mov_b32 m0, s48
	s_nop 0
	global_load_lds_dwordx4 v149, s[14:15]
	s_add_i32 s49, s31, 0x1a000
	s_add_i32 s50, s31, 0x8000
	s_mov_b32 m0, s49
	s_nop 0
	global_load_lds_dwordx4 v153, s[14:15]
	s_add_u32 s14, s24, 0x80
	s_addc_u32 s15, s25, 0
	s_mov_b32 m0, s50
	s_nop 0
	global_load_lds_dwordx4 v147, s[14:15]
	s_add_i32 s51, s31, 0xa000
	s_add_i32 s52, s31, 0x1c000
	s_mov_b32 m0, s51
	s_nop 0
	global_load_lds_dwordx4 v151, s[14:15]
	s_add_u32 s14, s22, 0x80080
	s_addc_u32 s15, s23, 0
	s_mov_b32 m0, s52
	s_nop 0
	global_load_lds_dwordx4 v149, s[14:15]
	s_add_i32 s53, s31, 0x1e000
	s_mov_b32 m0, s53
	s_nop 0
	global_load_lds_dwordx4 v153, s[14:15]
	v_bitop3_b32 v1, v1, s2, v3 bitop3:0xde
	s_waitcnt vmcnt(6)
	s_add_i32 s54, s31, 0xc000
	v_and_b32_e32 v3, 3, v0
	v_bfe_u32 v157, v0, 2, 4
	v_and_b32_e32 v0, 60, v0
	s_cmp_lt_u32 s7, 4
	v_lshl_or_b32 v159, v3, 6, v0
	v_lshlrev_b32_e32 v0, 3, v3
	s_cselect_b64 s[14:15], -1, 0
	s_add_i32 s55, s31, 0xe000
	s_ashr_i32 s56, s70, 31
	s_mov_b32 s7, s41
	s_lshr_b32 s57, s6, 3
	s_mov_b32 s58, 0
	v_add_u32_e32 v160, 0, v1
	v_add_u32_e32 v253, 0x10000, v160
	v_add_u32_e32 v252, 0x14000, v160
	v_add_u32_e32 v251, 0x18000, v160
	v_add_u32_e32 v250, 0x1c000, v160
	v_add_u32_e32 v161, 0, v4
	v_lshlrev_b32_e32 v192, 1, v0
	v_lshlrev_b32_e32 v162, 2, v2
	s_barrier
	s_branch .LBB0_1169

; #define PG8_STAGE(bufoff, gbase, voff) do { _Pragma("unroll") for (int _i = 0; _i < 2; ++_i) \
;         asm volatile("s_mov_b32 m0, %0\n\ts_nop 0\n\tglobal_load_lds_dwordx4 %1, %2" :: "s"(ldsb + (unsigned)((bufoff) + _i * 8192)), "v"((voff)[_i]), "s"(gbase) : "m0", "memory"); } while (0)
; #define PG8_LDA(dst, b, h) do { _Pragma("unroll") for (int m = 0; m < 4; ++m) _Pragma("unroll") for (int k = 0; k < 2; ++k) dst[m][k] = *(const PG8_LAS bf16x8*)(lds + PG8_SA(b, h) + aoff + m * 2048 + k * 1024); } while (0)
; #define PG8_LDB(dst, b, h) do { _Pragma("unroll") for (int n = 0; n < 2; ++n) _Pragma("unroll") for (int k = 0; k < 2; ++k) dst[n][k] = *(const PG8_LAS bf16x8*)(lds + PG8_SB(b, h) + boff + n * 2048 + k * 1024); } while (0)
; #define PG8_MMA(ai, bj, At, Bt) do { __builtin_amdgcn_s_setprio(1); _Pragma("unroll") for (int m = 0; m < 4; ++m) _Pragma("unroll") for (int n = 0; n < 2; ++n) _Pragma("unroll") for (int k = 0; k < 2; ++k) \
;         acc[ai][bj][m][n] = __builtin_amdgcn_mfma_f32_16x16x32_bf16(Bt[n][k], At[m][k], acc[ai][bj][m][n], 0, 0, 0); __builtin_amdgcn_s_setprio(0); } while (0)
; #define PG8_WAIT_V(n) asm volatile("s_waitcnt vmcnt(" #n ")" ::: "memory")
; #define PG8_WAIT_L(n) asm volatile("s_waitcnt lgkmcnt(" #n ")" ::: "memory")
; template <class Epi, class Sched, bool ALIGN_EPI = false, bool SP2 = false>
; __device__ __forceinline__ void gemm_phase(PG8_LAS unsigned char* lds, const Gemm g, const Sched& S, const Epi& E, const int wv) {
;     ...
;             const bool last = (t == nt - 2);
;             const char* a1 = cA + (size_t)(t + 1) * kstep;
;             const char* a2 = last ? nA : cA + (size_t)(t + 2) * kstep; const char* b2 = last ? nB : cB + (size_t)(t + 2) * kstep;
;             const char* a3 = a2 + kstep; const char* b3 = b2 + kstep;
;             if (last && has_next) S.a_ready(nxt);
;             if constexpr (SP2) {
;             PG8_LDB(B0, 0, 0); PG8_LDB(B1, 0, 1); PG8_SCHED; PG8_LDA(At, 0, 0); PG8_STAGE(PG8_SA(1, 1), a1 + hstepA, voffA);
;             PG8_WAIT_V(8); PG8_WAIT_L(0); PG8_BAR; PG8_MMA(0, 0, At, B0); PG8_MMA(0, 1, At, B1); PG8_BAR; PG8_SCHED;
;             PG8_LDA(At, 0, 1); PG8_STAGE(PG8_SB(0, 0), b2, voffB); PG8_STAGE(PG8_SB(0, 1), b2 + hstepB, voffB); PG8_STAGE(PG8_SA(0, 0), a2, voffA);
;             PG8_WAIT_V(8); PG8_WAIT_L(0); PG8_BAR; PG8_MMA(1, 0, At, B0); PG8_MMA(1, 1, At, B1); PG8_BAR; PG8_SCHED;
.LBB0_1175:
	ds_read_b128 v[80:83], v253
	ds_read_b128 v[84:87], v253 offset:1024
	ds_read_b128 v[88:91], v253 offset:2048
	ds_read_b128 v[92:95], v253 offset:3072
	ds_read_b128 v[164:167], v252
	ds_read_b128 v[168:171], v252 offset:1024
	ds_read_b128 v[172:175], v252 offset:2048
	ds_read_b128 v[176:179], v252 offset:3072
	s_add_i32 s88, s22, 2
	s_cmp_eq_u32 s62, s22
	s_cselect_b32 s26, s16, s79
	s_cselect_b32 s27, s17, s85
	s_cselect_b32 s24, s84, s86
	s_cselect_b32 s25, s83, s87
	s_add_u32 s22, s26, 0x80
	s_addc_u32 s23, s27, 0
	ds_read_b128 v[180:183], v161
	ds_read_b128 v[184:187], v161 offset:1024
	ds_read_b128 v[188:191], v161 offset:2048
	ds_read_b128 v[194:197], v161 offset:3072
	ds_read_b128 v[198:201], v161 offset:4096
	ds_read_b128 v[202:205], v161 offset:5120
	ds_read_b128 v[206:209], v161 offset:6144
	ds_read_b128 v[210:213], v161 offset:7168
	s_add_u32 s92, s79, 0x83f80
	s_addc_u32 s93, s85, 0
	s_mov_b32 m0, s54
	s_nop 0
	global_load_lds_dwordx4 v147, s[92:93]
	s_nop 0
	s_mov_b32 m0, s55
	s_nop 0
	global_load_lds_dwordx4 v151, s[92:93]
	s_waitcnt vmcnt(8) lgkmcnt(0)
	s_setprio 1
	s_barrier
	v_mfma_f32_16x16x32_bf16 v[140:143], v[80:83], v[180:183], v[140:143]
	v_mfma_f32_16x16x32_bf16 v[136:139], v[88:91], v[180:183], v[136:139]
	v_mfma_f32_16x16x32_bf16 v[124:127], v[80:83], v[188:191], v[124:127]
	v_mfma_f32_16x16x32_bf16 v[120:123], v[88:91], v[188:191], v[120:123]
	v_mfma_f32_16x16x32_bf16 v[108:111], v[80:83], v[198:201], v[108:111]
	v_mfma_f32_16x16x32_bf16 v[104:107], v[88:91], v[198:201], v[104:107]
	v_mfma_f32_16x16x32_bf16 v[76:79], v[80:83], v[206:209], v[76:79]
	v_mfma_f32_16x16x32_bf16 v[72:75], v[88:91], v[206:209], v[72:75]
	v_mfma_f32_16x16x32_bf16 v[140:143], v[84:87], v[184:187], v[140:143]
	v_mfma_f32_16x16x32_bf16 v[136:139], v[92:95], v[184:187], v[136:139]
	v_mfma_f32_16x16x32_bf16 v[124:127], v[84:87], v[194:197], v[124:127]
	v_mfma_f32_16x16x32_bf16 v[120:123], v[92:95], v[194:197], v[120:123]
	v_mfma_f32_16x16x32_bf16 v[108:111], v[84:87], v[202:205], v[108:111]
	v_mfma_f32_16x16x32_bf16 v[104:107], v[92:95], v[202:205], v[104:107]
	v_mfma_f32_16x16x32_bf16 v[76:79], v[84:87], v[210:213], v[76:79]
	v_mfma_f32_16x16x32_bf16 v[72:75], v[92:95], v[210:213], v[72:75]
	v_mfma_f32_16x16x32_bf16 v[132:135], v[164:167], v[180:183], v[132:135]
	v_mfma_f32_16x16x32_bf16 v[128:131], v[172:175], v[180:183], v[128:131]
	v_mfma_f32_16x16x32_bf16 v[116:119], v[164:167], v[188:191], v[116:119]
	v_mfma_f32_16x16x32_bf16 v[112:115], v[172:175], v[188:191], v[112:115]
	v_mfma_f32_16x16x32_bf16 v[100:103], v[164:167], v[198:201], v[100:103]
	v_mfma_f32_16x16x32_bf16 v[96:99], v[172:175], v[198:201], v[96:99]
	v_mfma_f32_16x16x32_bf16 v[68:71], v[164:167], v[206:209], v[68:71]
	v_mfma_f32_16x16x32_bf16 v[64:67], v[172:175], v[206:209], v[64:67]
	v_mfma_f32_16x16x32_bf16 v[132:135], v[168:171], v[184:187], v[132:135]
	v_mfma_f32_16x16x32_bf16 v[128:131], v[176:179], v[184:187], v[128:131]
	v_mfma_f32_16x16x32_bf16 v[116:119], v[168:171], v[194:197], v[116:119]
	v_mfma_f32_16x16x32_bf16 v[112:115], v[176:179], v[194:197], v[112:115]
	v_mfma_f32_16x16x32_bf16 v[100:103], v[168:171], v[202:205], v[100:103]
	v_mfma_f32_16x16x32_bf16 v[96:99], v[176:179], v[202:205], v[96:99]
	v_mfma_f32_16x16x32_bf16 v[68:71], v[168:171], v[210:213], v[68:71]
	v_mfma_f32_16x16x32_bf16 v[64:67], v[176:179], v[210:213], v[64:67]
	s_setprio 0
	s_barrier
	ds_read_b128 v[180:183], v161 offset:16384
	ds_read_b128 v[184:187], v161 offset:17408
	ds_read_b128 v[188:191], v161 offset:18432
	ds_read_b128 v[194:197], v161 offset:19456
	ds_read_b128 v[198:201], v161 offset:20480
	ds_read_b128 v[202:205], v161 offset:21504
	ds_read_b128 v[206:209], v161 offset:22528
	ds_read_b128 v[210:213], v161 offset:23552
	s_mov_b32 m0, s33
	s_nop 0
	global_load_lds_dwordx4 v149, s[24:25]
	s_add_u32 s92, s24, 0x80000
	s_mov_b32 m0, s34
	s_nop 0
	global_load_lds_dwordx4 v153, s[24:25]
	s_addc_u32 s93, s25, 0
	s_mov_b32 m0, s35
	s_nop 0
	global_load_lds_dwordx4 v149, s[92:93]
	s_nop 0
	s_mov_b32 m0, s36
	s_nop 0
	global_load_lds_dwordx4 v153, s[92:93]
	s_nop 0
	s_mov_b32 m0, s31
	s_nop 0
	global_load_lds_dwordx4 v147, s[26:27]
	s_nop 0
	s_mov_b32 m0, s37
	s_nop 0
	global_load_lds_dwordx4 v151, s[26:27]
	s_waitcnt vmcnt(8) lgkmcnt(0)
	s_setprio 1
	s_barrier
	v_mfma_f32_16x16x32_bf16 v[60:63], v[80:83], v[180:183], v[60:63]
	v_mfma_f32_16x16x32_bf16 v[56:59], v[88:91], v[180:183], v[56:59]
	v_mfma_f32_16x16x32_bf16 v[44:47], v[80:83], v[188:191], v[44:47]
	v_mfma_f32_16x16x32_bf16 v[40:43], v[88:91], v[188:191], v[40:43]
	v_mfma_f32_16x16x32_bf16 v[28:31], v[80:83], v[198:201], v[28:31]
	v_mfma_f32_16x16x32_bf16 v[24:27], v[88:91], v[198:201], v[24:27]
	v_mfma_f32_16x16x32_bf16 v[12:15], v[80:83], v[206:209], v[12:15]
	v_mfma_f32_16x16x32_bf16 v[8:11], v[88:91], v[206:209], v[8:11]
	v_mfma_f32_16x16x32_bf16 v[60:63], v[84:87], v[184:187], v[60:63]
	v_mfma_f32_16x16x32_bf16 v[56:59], v[92:95], v[184:187], v[56:59]
	v_mfma_f32_16x16x32_bf16 v[44:47], v[84:87], v[194:197], v[44:47]
	v_mfma_f32_16x16x32_bf16 v[40:43], v[92:95], v[194:197], v[40:43]
	v_mfma_f32_16x16x32_bf16 v[28:31], v[84:87], v[202:205], v[28:31]
	v_mfma_f32_16x16x32_bf16 v[24:27], v[92:95], v[202:205], v[24:27]
	v_mfma_f32_16x16x32_bf16 v[12:15], v[84:87], v[210:213], v[12:15]
	v_mfma_f32_16x16x32_bf16 v[8:11], v[92:95], v[210:213], v[8:11]
	v_mfma_f32_16x16x32_bf16 v[52:55], v[164:167], v[180:183], v[52:55]
	v_mfma_f32_16x16x32_bf16 v[48:51], v[172:175], v[180:183], v[48:51]
	v_mfma_f32_16x16x32_bf16 v[36:39], v[164:167], v[188:191], v[36:39]
	v_mfma_f32_16x16x32_bf16 v[32:35], v[172:175], v[188:191], v[32:35]
	v_mfma_f32_16x16x32_bf16 v[20:23], v[164:167], v[198:201], v[20:23]
	v_mfma_f32_16x16x32_bf16 v[16:19], v[172:175], v[198:201], v[16:19]
	v_mfma_f32_16x16x32_bf16 v[4:7], v[164:167], v[206:209], v[4:7]
	v_mfma_f32_16x16x32_bf16 v[0:3], v[172:175], v[206:209], v[0:3]
	v_mfma_f32_16x16x32_bf16 v[52:55], v[168:171], v[184:187], v[52:55]
	v_mfma_f32_16x16x32_bf16 v[48:51], v[176:179], v[184:187], v[48:51]
	v_mfma_f32_16x16x32_bf16 v[36:39], v[168:171], v[194:197], v[36:39]
	v_mfma_f32_16x16x32_bf16 v[32:35], v[176:179], v[194:197], v[32:35]
	v_mfma_f32_16x16x32_bf16 v[20:23], v[168:171], v[202:205], v[20:23]
	v_mfma_f32_16x16x32_bf16 v[16:19], v[176:179], v[202:205], v[16:19]
	v_mfma_f32_16x16x32_bf16 v[4:7], v[168:171], v[210:213], v[4:7]
	v_mfma_f32_16x16x32_bf16 v[0:3], v[176:179], v[210:213], v[0:3]
	s_setprio 0
	s_barrier
; #define PG8_STAGE(bufoff, gbase, voff) do { _Pragma("unroll") for (int _i = 0; _i < 2; ++_i) \
;         asm volatile("s_mov_b32 m0, %0\n\ts_nop 0\n\tglobal_load_lds_dwordx4 %1, %2" :: "s"(ldsb + (unsigned)((bufoff) + _i * 8192)), "v"((voff)[_i]), "s"(gbase) : "m0", "memory"); } while (0)
; #define PG8_LDA(dst, b, h) do { _Pragma("unroll") for (int m = 0; m < 4; ++m) _Pragma("unroll") for (int k = 0; k < 2; ++k) dst[m][k] = *(const PG8_LAS bf16x8*)(lds + PG8_SA(b, h) + aoff + m * 2048 + k * 1024); } while (0)
; #define PG8_LDB(dst, b, h) do { _Pragma("unroll") for (int n = 0; n < 2; ++n) _Pragma("unroll") for (int k = 0; k < 2; ++k) dst[n][k] = *(const PG8_LAS bf16x8*)(lds + PG8_SB(b, h) + boff + n * 2048 + k * 1024); } while (0)
; #define PG8_MMA(ai, bj, At, Bt) do { __builtin_amdgcn_s_setprio(1); _Pragma("unroll") for (int m = 0; m < 4; ++m) _Pragma("unroll") for (int n = 0; n < 2; ++n) _Pragma("unroll") for (int k = 0; k < 2; ++k) \
;         acc[ai][bj][m][n] = __builtin_amdgcn_mfma_f32_16x16x32_bf16(Bt[n][k], At[m][k], acc[ai][bj][m][n], 0, 0, 0); __builtin_amdgcn_s_setprio(0); } while (0)
; #define PG8_WAIT_V(n) asm volatile("s_waitcnt vmcnt(" #n ")" ::: "memory")
; #define PG8_WAIT_L(n) asm volatile("s_waitcnt lgkmcnt(" #n ")" ::: "memory")
; #define PG8_BAR __builtin_amdgcn_s_barrier()
; #define PG8_SCHED __builtin_amdgcn_sched_barrier(0)
; template <class Epi, class Sched, bool ALIGN_EPI = false, bool SP2 = false>
; __device__ __forceinline__ void gemm_phase(PG8_LAS unsigned char* lds, const Gemm g, const Sched& S, const Epi& E, const int wv) {
;     ...
;             PG8_LDB(B0, 1, 0); PG8_LDB(B1, 1, 1); PG8_SCHED; PG8_LDA(At, 1, 0); PG8_STAGE(PG8_SA(0, 1), a2 + hstepA, voffA);
;             PG8_WAIT_V(8); PG8_WAIT_L(0); PG8_BAR; PG8_MMA(0, 0, At, B0); PG8_MMA(0, 1, At, B1); PG8_BAR; PG8_SCHED;
;             PG8_LDA(At, 1, 1); PG8_STAGE(PG8_SB(1, 0), b3, voffB); PG8_STAGE(PG8_SB(1, 1), b3 + hstepB, voffB); PG8_STAGE(PG8_SA(1, 0), a3, voffA);
;             PG8_WAIT_V(8); PG8_WAIT_L(0); PG8_BAR; PG8_MMA(1, 0, At, B0); PG8_MMA(1, 1, At, B1); PG8_BAR; PG8_SCHED;
	ds_read_b128 v[80:83], v251
	ds_read_b128 v[84:87], v251 offset:1024
	ds_read_b128 v[88:91], v251 offset:2048
	ds_read_b128 v[92:95], v251 offset:3072
	ds_read_b128 v[164:167], v250
	ds_read_b128 v[168:171], v250 offset:1024
	ds_read_b128 v[172:175], v250 offset:2048
	ds_read_b128 v[176:179], v250 offset:3072
	ds_read_b128 v[180:183], v161 offset:32768
	ds_read_b128 v[184:187], v161 offset:33792
	ds_read_b128 v[188:191], v161 offset:34816
	ds_read_b128 v[194:197], v161 offset:35840
	ds_read_b128 v[198:201], v161 offset:36864
	ds_read_b128 v[202:205], v161 offset:37888
	ds_read_b128 v[206:209], v161 offset:38912
	ds_read_b128 v[210:213], v161 offset:39936
	s_add_u32 s26, s26, 0x84000
	s_addc_u32 s27, s27, 0
	s_mov_b32 m0, s42
	s_nop 0
	global_load_lds_dwordx4 v147, s[26:27]
	s_nop 0
	s_mov_b32 m0, s43
	s_nop 0
	global_load_lds_dwordx4 v151, s[26:27]
	s_waitcnt vmcnt(8) lgkmcnt(0)
	s_setprio 1
	s_barrier
	v_mfma_f32_16x16x32_bf16 v[140:143], v[80:83], v[180:183], v[140:143]
	v_mfma_f32_16x16x32_bf16 v[136:139], v[88:91], v[180:183], v[136:139]
	v_mfma_f32_16x16x32_bf16 v[124:127], v[80:83], v[188:191], v[124:127]
	v_mfma_f32_16x16x32_bf16 v[120:123], v[88:91], v[188:191], v[120:123]
	v_mfma_f32_16x16x32_bf16 v[108:111], v[80:83], v[198:201], v[108:111]
	v_mfma_f32_16x16x32_bf16 v[104:107], v[88:91], v[198:201], v[104:107]
	v_mfma_f32_16x16x32_bf16 v[76:79], v[80:83], v[206:209], v[76:79]
	v_mfma_f32_16x16x32_bf16 v[72:75], v[88:91], v[206:209], v[72:75]
	v_mfma_f32_16x16x32_bf16 v[140:143], v[84:87], v[184:187], v[140:143]
	v_mfma_f32_16x16x32_bf16 v[136:139], v[92:95], v[184:187], v[136:139]
	v_mfma_f32_16x16x32_bf16 v[124:127], v[84:87], v[194:197], v[124:127]
	v_mfma_f32_16x16x32_bf16 v[120:123], v[92:95], v[194:197], v[120:123]
	v_mfma_f32_16x16x32_bf16 v[108:111], v[84:87], v[202:205], v[108:111]
	v_mfma_f32_16x16x32_bf16 v[104:107], v[92:95], v[202:205], v[104:107]
	v_mfma_f32_16x16x32_bf16 v[76:79], v[84:87], v[210:213], v[76:79]
	v_mfma_f32_16x16x32_bf16 v[72:75], v[92:95], v[210:213], v[72:75]
	v_mfma_f32_16x16x32_bf16 v[132:135], v[164:167], v[180:183], v[132:135]
	v_mfma_f32_16x16x32_bf16 v[128:131], v[172:175], v[180:183], v[128:131]
	v_mfma_f32_16x16x32_bf16 v[116:119], v[164:167], v[188:191], v[116:119]
	v_mfma_f32_16x16x32_bf16 v[112:115], v[172:175], v[188:191], v[112:115]
	v_mfma_f32_16x16x32_bf16 v[100:103], v[164:167], v[198:201], v[100:103]
	v_mfma_f32_16x16x32_bf16 v[96:99], v[172:175], v[198:201], v[96:99]
	v_mfma_f32_16x16x32_bf16 v[68:71], v[164:167], v[206:209], v[68:71]
	v_mfma_f32_16x16x32_bf16 v[64:67], v[172:175], v[206:209], v[64:67]
	v_mfma_f32_16x16x32_bf16 v[132:135], v[168:171], v[184:187], v[132:135]
	v_mfma_f32_16x16x32_bf16 v[128:131], v[176:179], v[184:187], v[128:131]
	v_mfma_f32_16x16x32_bf16 v[116:119], v[168:171], v[194:197], v[116:119]
	v_mfma_f32_16x16x32_bf16 v[112:115], v[176:179], v[194:197], v[112:115]
	v_mfma_f32_16x16x32_bf16 v[100:103], v[168:171], v[202:205], v[100:103]
	v_mfma_f32_16x16x32_bf16 v[96:99], v[176:179], v[202:205], v[96:99]
	v_mfma_f32_16x16x32_bf16 v[68:71], v[168:171], v[210:213], v[68:71]
	v_mfma_f32_16x16x32_bf16 v[64:67], v[176:179], v[210:213], v[64:67]
	s_setprio 0
	s_barrier
	ds_read_b128 v[180:183], v161 offset:49152
	ds_read_b128 v[184:187], v161 offset:50176
	ds_read_b128 v[188:191], v161 offset:51200
	ds_read_b128 v[194:197], v161 offset:52224
	ds_read_b128 v[198:201], v161 offset:53248
	ds_read_b128 v[202:205], v161 offset:54272
	ds_read_b128 v[206:209], v161 offset:55296
	ds_read_b128 v[210:213], v161 offset:56320
	s_add_u32 s26, s24, 0x80
	s_addc_u32 s27, s25, 0
	s_mov_b32 m0, s48
	s_nop 0
	global_load_lds_dwordx4 v149, s[26:27]
	s_add_u32 s24, s24, 0x80080
	s_mov_b32 m0, s49
	s_nop 0
	global_load_lds_dwordx4 v153, s[26:27]
	s_addc_u32 s25, s25, 0
	s_mov_b32 m0, s52
	s_nop 0
	global_load_lds_dwordx4 v149, s[24:25]
	s_nop 0
	s_mov_b32 m0, s53
	s_nop 0
	global_load_lds_dwordx4 v153, s[24:25]
	s_nop 0
	s_mov_b32 m0, s50
	s_nop 0
	global_load_lds_dwordx4 v147, s[22:23]
	s_nop 0
	s_mov_b32 m0, s51
	s_nop 0
	global_load_lds_dwordx4 v151, s[22:23]
	s_waitcnt vmcnt(8) lgkmcnt(0)
	s_setprio 1
	s_barrier
	v_mfma_f32_16x16x32_bf16 v[60:63], v[80:83], v[180:183], v[60:63]
	v_mfma_f32_16x16x32_bf16 v[56:59], v[88:91], v[180:183], v[56:59]
	v_mfma_f32_16x16x32_bf16 v[44:47], v[80:83], v[188:191], v[44:47]
	v_mfma_f32_16x16x32_bf16 v[40:43], v[88:91], v[188:191], v[40:43]
	v_mfma_f32_16x16x32_bf16 v[28:31], v[80:83], v[198:201], v[28:31]
	v_mfma_f32_16x16x32_bf16 v[24:27], v[88:91], v[198:201], v[24:27]
	v_mfma_f32_16x16x32_bf16 v[12:15], v[80:83], v[206:209], v[12:15]
	v_mfma_f32_16x16x32_bf16 v[8:11], v[88:91], v[206:209], v[8:11]
	v_mfma_f32_16x16x32_bf16 v[60:63], v[84:87], v[184:187], v[60:63]
	v_mfma_f32_16x16x32_bf16 v[56:59], v[92:95], v[184:187], v[56:59]
	v_mfma_f32_16x16x32_bf16 v[44:47], v[84:87], v[194:197], v[44:47]
	v_mfma_f32_16x16x32_bf16 v[40:43], v[92:95], v[194:197], v[40:43]
	v_mfma_f32_16x16x32_bf16 v[28:31], v[84:87], v[202:205], v[28:31]
	v_mfma_f32_16x16x32_bf16 v[24:27], v[92:95], v[202:205], v[24:27]
	v_mfma_f32_16x16x32_bf16 v[12:15], v[84:87], v[210:213], v[12:15]
	v_mfma_f32_16x16x32_bf16 v[8:11], v[92:95], v[210:213], v[8:11]
	v_mfma_f32_16x16x32_bf16 v[52:55], v[164:167], v[180:183], v[52:55]
	v_mfma_f32_16x16x32_bf16 v[48:51], v[172:175], v[180:183], v[48:51]
	v_mfma_f32_16x16x32_bf16 v[36:39], v[164:167], v[188:191], v[36:39]
	v_mfma_f32_16x16x32_bf16 v[32:35], v[172:175], v[188:191], v[32:35]
	v_mfma_f32_16x16x32_bf16 v[20:23], v[164:167], v[198:201], v[20:23]
	v_mfma_f32_16x16x32_bf16 v[16:19], v[172:175], v[198:201], v[16:19]
	v_mfma_f32_16x16x32_bf16 v[4:7], v[164:167], v[206:209], v[4:7]
	v_mfma_f32_16x16x32_bf16 v[0:3], v[172:175], v[206:209], v[0:3]
	v_mfma_f32_16x16x32_bf16 v[52:55], v[168:171], v[184:187], v[52:55]
	v_mfma_f32_16x16x32_bf16 v[48:51], v[176:179], v[184:187], v[48:51]
	v_mfma_f32_16x16x32_bf16 v[36:39], v[168:171], v[194:197], v[36:39]
	v_mfma_f32_16x16x32_bf16 v[32:35], v[176:179], v[194:197], v[32:35]
	v_mfma_f32_16x16x32_bf16 v[20:23], v[168:171], v[202:205], v[20:23]
	v_mfma_f32_16x16x32_bf16 v[16:19], v[176:179], v[202:205], v[16:19]
	v_mfma_f32_16x16x32_bf16 v[4:7], v[168:171], v[210:213], v[4:7]
	v_mfma_f32_16x16x32_bf16 v[0:3], v[176:179], v[210:213], v[0:3]
	s_setprio 0
	s_barrier
	s_add_u32 s79, s79, 0x100
	s_addc_u32 s85, s85, 0
	s_add_u32 s86, s86, 0x100
	s_addc_u32 s87, s87, 0
	s_cmp_ge_i32 s88, s40
	s_mov_b32 s22, s88
	s_cbranch_scc0 .LBB0_1175
	v_readlane_b32 s92, v254, 49
	v_readlane_b32 s93, v254, 50
	s_mov_b32 s79, 0xc00000
	s_and_b64 vcc, exec, s[14:15]
	s_cbranch_vccz .LBB0_1178

; #define PG8_BAR __builtin_amdgcn_s_barrier()
; template <class Epi, class Sched, bool ALIGN_EPI = false, bool SP2 = false>
; __device__ __forceinline__ void gemm_phase(PG8_LAS unsigned char* lds, const Gemm g, const Sched& S, const Epi& E, const int wv) {
;     ...
;     const int tid = tid_of(wv), wid = wid_, lane = tid & 63, wr = wid >> 2, wc = wid & 3, fr = lane & 15, fq = lane >> 4;
;     const int K = g.ld, Kb = g.ldb ? g.ldb : g.ld;
;     unsigned voffA[2], voffB[2];
; #pragma unroll
;     for (int i = 0; i < 2; ++i) { int R, C; stage_rc(tid * 16 + i * 8192, R, C); const int Rb = Epi::PERM ? ((R & ~31) + perm32(R & 31)) : R;
;         voffA[i] = (unsigned)(R * K + C) * 2u; voffB[i] = (unsigned)(Rb * Kb + C) * 2u; }
;     const size_t kstep = (size_t)(BK * 2);
;     const size_t hstepA = (size_t)HALF * K * 2, hstepB = (size_t)HALF * Kb * 2;
;     const size_t tstepA = 2 * hstepA, tstepB = 2 * hstepB;
;     const unsigned ldsw = (unsigned)wid * 1024u;
;     const unsigned ldsb = (unsigned)(size_t)lds + ldsw;
;     const int aoff = lds_byte(wr * 64 + fr, fq * 8), boff = lds_byte(wc * 32 + fr, fq * 8);
;     ...
;         PG8_STAGE(PG8_SB(0, 0), cB, voffB); PG8_STAGE(PG8_SB(0, 1), cB + hstepB, voffB); PG8_STAGE(PG8_SA(0, 0), cA, voffA); PG8_STAGE(PG8_SA(0, 1), cA + hstepA, voffA);
;         if (wr == 1) PG8_BAR;
;         PG8_WAIT_V(2); PG8_BAR;
;         PG8_STAGE(PG8_SB(1, 0), cB + kstep, voffB); PG8_STAGE(PG8_SA(1, 0), cA + kstep, voffA); PG8_STAGE(PG8_SB(1, 1), cB + hstepB + kstep, voffB);
;         PG8_WAIT_V(6); PG8_BAR;
;     __device__ __forceinline__ void operator()(AccT acc, const pg8::Unit& u, int wr, int wc, int fr, int fq) const {
;         const int row0 = u.pm * 256 + wr * 64 + fr, col0 = u.pn * 256 + wc * 32 + 8 * fq, lane = fq * 16 + fr;
;         const int bidx = u.pm < 64 ? (u.pm >> 4) : 4;
;         const float* gp = gate + (size_t)bidx * MODW + col0;
;         f32x4 gv[2][2], gz[2][2];
; #pragma unroll
;         for (int bj = 0; bj < 2; ++bj)
; #pragma unroll
;             for (int n = 0; n < 2; ++n) { gv[bj][n] = *(const f32x4*)(gp + bj * 128 + n * 4) * coef;
;                 if (WZ) gz[bj][n] = *(const f32x4*)(gnext + col0 + bj * 128 + n * 4) * (*(const f32x4*)(scnext + (size_t)bidx * MODW + col0 + bj * 128 + n * 4) + 1.f); }
;         const int st4 = ((lane & 3) * 16 + (lane >> 2)) * 4, ld4 = ((lane & 15) * 4 + (lane >> 4)) * 4;
.LBB0_1231:
	v_readlane_b32 s11, v254, 43
	v_readlane_b32 s2, v254, 33
	s_mul_hi_u32 s10, s11, 0xf669a000
	s_bfe_u32 s65, s2, 0x80010
	s_mul_i32 s2, s11, 0xf669a000
	s_sub_i32 s10, s10, s11
	s_add_u32 s2, s6, s2
	s_addc_u32 s6, s7, s10
	s_add_u32 s10, s14, 0x44f000
	s_addc_u32 s11, s15, 0
	v_bfe_u32 v1, v0, 4, 2
	s_add_u32 s37, s2, 0x30000
	v_and_b32_e32 v186, 15, v0
	v_lshlrev_b32_e32 v2, 4, v1
	v_lshlrev_b32_e32 v3, 2, v0
	s_addc_u32 s42, s6, 0
	s_and_b32 s2, s12, 3
	v_lshl_or_b32 v2, v186, 6, v2
	s_lshl_b32 s6, s13, 13
	v_and_b32_e32 v3, 32, v3
	s_lshl_b32 s43, s13, 6
	v_bitop3_b32 v4, v2, s6, v3 bitop3:0xde
	s_lshl_b32 s16, s2, 5
	s_lshl_b32 s6, s2, 12
	s_add_i32 s44, s28, 0x18000
	v_bitop3_b32 v2, v2, s6, v3 bitop3:0xde
	s_add_u32 s6, s20, 0x80
	s_waitcnt vmcnt(2)
	s_barrier
	s_addc_u32 s7, s21, 0
	s_mov_b32 m0, s44
	s_nop 0
	global_load_lds_dwordx4 v183, s[6:7]
	s_add_i32 s45, s28, 0x1a000
	s_add_i32 s46, s28, 0x8000
	s_mov_b32 m0, s45
	s_nop 0
	global_load_lds_dwordx4 v185, s[6:7]
	s_add_u32 s6, s22, 0x80
	s_addc_u32 s7, s23, 0
	s_mov_b32 m0, s46
	s_nop 0
	global_load_lds_dwordx4 v182, s[6:7]
	s_add_i32 s47, s28, 0xa000
	s_add_i32 s48, s28, 0x1c000
	s_mov_b32 m0, s47
	s_nop 0
	global_load_lds_dwordx4 v184, s[6:7]
	s_add_u32 s6, s20, 0x160080
	s_addc_u32 s7, s21, 0
	s_add_i32 s49, s28, 0x1e000
	s_add_i32 s50, s28, 0xc000
	s_cmp_lt_u32 s12, 4
	s_mov_b32 m0, s48
	s_nop 0
	global_load_lds_dwordx4 v183, s[6:7]
	s_cselect_b64 s[12:13], -1, 0
	s_add_i32 s52, s28, 0xe000
	s_ashr_i32 s53, s70, 31
	s_lshl_b32 s2, s2, 2
	s_mov_b32 m0, s49
	s_nop 0
	global_load_lds_dwordx4 v185, s[6:7]
	v_and_b32_e32 v3, 63, v0
	v_and_b32_e32 v5, 3, v0
	v_bfe_u32 v188, v0, 2, 4
	v_and_b32_e32 v0, 60, v0
	s_add_u32 s2, s14, s2
	s_waitcnt vmcnt(6)
	v_lshl_or_b32 v189, v5, 6, v0
	v_lshlrev_b32_e32 v0, 4, v186
	s_addc_u32 s14, s15, 0
	v_lshl_or_b32 v190, v1, 2, v0
	v_lshlrev_b32_e32 v0, 2, v3
	s_add_u32 s54, s2, 0x21e000
	v_lshl_or_b32 v187, v1, 3, s16
	v_lshl_or_b32 v191, v5, 3, s16
	v_xor_b32_e32 v194, 64, v0
	v_xor_b32_e32 v195, 0x80, v0
	s_mov_b32 s51, 0
	v_cmp_eq_u32_e64 s[6:7], 0, v1
	s_addc_u32 s55, s14, 0
	v_add_u32_e32 v196, 0, v2
	v_add_u32_e32 v253, 0x10000, v196
	v_add_u32_e32 v252, 0x14000, v196
	v_add_u32_e32 v251, 0x18000, v196
	v_add_u32_e32 v250, 0x1c000, v196
	v_add_u32_e32 v197, 0, v4
	s_barrier
	s_branch .LBB0_1234

; #define PG8_STAGE(bufoff, gbase, voff) do { _Pragma("unroll") for (int _i = 0; _i < 2; ++_i) \
;         asm volatile("s_mov_b32 m0, %0\n\ts_nop 0\n\tglobal_load_lds_dwordx4 %1, %2" :: "s"(ldsb + (unsigned)((bufoff) + _i * 8192)), "v"((voff)[_i]), "s"(gbase) : "m0", "memory"); } while (0)
; #define PG8_LDA(dst, b, h) do { _Pragma("unroll") for (int m = 0; m < 4; ++m) _Pragma("unroll") for (int k = 0; k < 2; ++k) dst[m][k] = *(const PG8_LAS bf16x8*)(lds + PG8_SA(b, h) + aoff + m * 2048 + k * 1024); } while (0)
; #define PG8_LDB(dst, b, h) do { _Pragma("unroll") for (int n = 0; n < 2; ++n) _Pragma("unroll") for (int k = 0; k < 2; ++k) dst[n][k] = *(const PG8_LAS bf16x8*)(lds + PG8_SB(b, h) + boff + n * 2048 + k * 1024); } while (0)
; #define PG8_MMA(ai, bj, At, Bt) do { __builtin_amdgcn_s_setprio(1); _Pragma("unroll") for (int m = 0; m < 4; ++m) _Pragma("unroll") for (int n = 0; n < 2; ++n) _Pragma("unroll") for (int k = 0; k < 2; ++k) \
;         acc[ai][bj][m][n] = __builtin_amdgcn_mfma_f32_16x16x32_bf16(Bt[n][k], At[m][k], acc[ai][bj][m][n], 0, 0, 0); __builtin_amdgcn_s_setprio(0); } while (0)
; #define PG8_WAIT_V(n) asm volatile("s_waitcnt vmcnt(" #n ")" ::: "memory")
; #define PG8_WAIT_L(n) asm volatile("s_waitcnt lgkmcnt(" #n ")" ::: "memory")
; template <class Epi, class Sched, bool ALIGN_EPI = false, bool SP2 = false>
; __device__ __forceinline__ void gemm_phase(PG8_LAS unsigned char* lds, const Gemm g, const Sched& S, const Epi& E, const int wv) {
;     ...
;             const bool last = (t == nt - 2);
;             const char* a1 = cA + (size_t)(t + 1) * kstep;
;             const char* a2 = last ? nA : cA + (size_t)(t + 2) * kstep; const char* b2 = last ? nB : cB + (size_t)(t + 2) * kstep;
;             const char* a3 = a2 + kstep; const char* b3 = b2 + kstep;
;             if (last && has_next) S.a_ready(nxt);
;             if constexpr (SP2) {
;             PG8_LDB(B0, 0, 0); PG8_LDB(B1, 0, 1); PG8_SCHED; PG8_LDA(At, 0, 0); PG8_STAGE(PG8_SA(1, 1), a1 + hstepA, voffA);
;             PG8_WAIT_V(8); PG8_WAIT_L(0); PG8_BAR; PG8_MMA(0, 0, At, B0); PG8_MMA(0, 1, At, B1); PG8_BAR; PG8_SCHED;
;             PG8_LDA(At, 0, 1); PG8_STAGE(PG8_SB(0, 0), b2, voffB); PG8_STAGE(PG8_SB(0, 1), b2 + hstepB, voffB); PG8_STAGE(PG8_SA(0, 0), a2, voffA);
;             PG8_WAIT_V(8); PG8_WAIT_L(0); PG8_BAR; PG8_MMA(1, 0, At, B0); PG8_MMA(1, 1, At, B1); PG8_BAR; PG8_SCHED;
.LBB0_1244:
	ds_read_b128 v[128:131], v253
	ds_read_b128 v[132:135], v253 offset:1024
	ds_read_b128 v[136:139], v253 offset:2048
	ds_read_b128 v[140:143], v253 offset:3072
	ds_read_b128 v[144:147], v252
	ds_read_b128 v[148:151], v252 offset:1024
	ds_read_b128 v[152:155], v252 offset:2048
	ds_read_b128 v[156:159], v252 offset:3072
	s_add_i32 s85, s20, 2
	s_cmp_eq_u32 s62, s20
	s_cselect_b32 s24, s14, s77
	s_cselect_b32 s25, s15, s79
	s_cselect_b32 s22, s72, s83
	s_cselect_b32 s23, s71, s84
	s_add_u32 s20, s24, 0x80
	s_addc_u32 s21, s25, 0
	ds_read_b128 v[160:163], v197
	ds_read_b128 v[164:167], v197 offset:1024
	ds_read_b128 v[168:171], v197 offset:2048
	ds_read_b128 v[172:175], v197 offset:3072
	ds_read_b128 v[176:179], v197 offset:4096
	ds_read_b128 v[198:201], v197 offset:5120
	ds_read_b128 v[202:205], v197 offset:6144
	ds_read_b128 v[206:209], v197 offset:7168
	s_add_u32 s86, s77, 0x15ff80
	s_addc_u32 s87, s79, 0
	s_mov_b32 m0, s50
	s_nop 0
	global_load_lds_dwordx4 v182, s[86:87]
	s_nop 0
	s_mov_b32 m0, s52
	s_nop 0
	global_load_lds_dwordx4 v184, s[86:87]
	s_waitcnt vmcnt(8) lgkmcnt(0)
	s_setprio 1
	s_barrier
	v_mfma_f32_16x16x32_bf16 v[124:127], v[128:131], v[160:163], v[124:127]
	v_mfma_f32_16x16x32_bf16 v[120:123], v[136:139], v[160:163], v[120:123]
	v_mfma_f32_16x16x32_bf16 v[108:111], v[128:131], v[168:171], v[108:111]
	v_mfma_f32_16x16x32_bf16 v[104:107], v[136:139], v[168:171], v[104:107]
	v_mfma_f32_16x16x32_bf16 v[92:95], v[128:131], v[176:179], v[92:95]
	v_mfma_f32_16x16x32_bf16 v[88:91], v[136:139], v[176:179], v[88:91]
	v_mfma_f32_16x16x32_bf16 v[76:79], v[128:131], v[202:205], v[76:79]
	v_mfma_f32_16x16x32_bf16 v[72:75], v[136:139], v[202:205], v[72:75]
	v_mfma_f32_16x16x32_bf16 v[124:127], v[132:135], v[164:167], v[124:127]
	v_mfma_f32_16x16x32_bf16 v[120:123], v[140:143], v[164:167], v[120:123]
	v_mfma_f32_16x16x32_bf16 v[108:111], v[132:135], v[172:175], v[108:111]
	v_mfma_f32_16x16x32_bf16 v[104:107], v[140:143], v[172:175], v[104:107]
	v_mfma_f32_16x16x32_bf16 v[92:95], v[132:135], v[198:201], v[92:95]
	v_mfma_f32_16x16x32_bf16 v[88:91], v[140:143], v[198:201], v[88:91]
	v_mfma_f32_16x16x32_bf16 v[76:79], v[132:135], v[206:209], v[76:79]
	v_mfma_f32_16x16x32_bf16 v[72:75], v[140:143], v[206:209], v[72:75]
	v_mfma_f32_16x16x32_bf16 v[116:119], v[144:147], v[160:163], v[116:119]
	v_mfma_f32_16x16x32_bf16 v[112:115], v[152:155], v[160:163], v[112:115]
	v_mfma_f32_16x16x32_bf16 v[100:103], v[144:147], v[168:171], v[100:103]
	v_mfma_f32_16x16x32_bf16 v[96:99], v[152:155], v[168:171], v[96:99]
	v_mfma_f32_16x16x32_bf16 v[84:87], v[144:147], v[176:179], v[84:87]
	v_mfma_f32_16x16x32_bf16 v[80:83], v[152:155], v[176:179], v[80:83]
	v_mfma_f32_16x16x32_bf16 v[68:71], v[144:147], v[202:205], v[68:71]
	v_mfma_f32_16x16x32_bf16 v[64:67], v[152:155], v[202:205], v[64:67]
	v_mfma_f32_16x16x32_bf16 v[116:119], v[148:151], v[164:167], v[116:119]
	v_mfma_f32_16x16x32_bf16 v[112:115], v[156:159], v[164:167], v[112:115]
	v_mfma_f32_16x16x32_bf16 v[100:103], v[148:151], v[172:175], v[100:103]
	v_mfma_f32_16x16x32_bf16 v[96:99], v[156:159], v[172:175], v[96:99]
	v_mfma_f32_16x16x32_bf16 v[84:87], v[148:151], v[198:201], v[84:87]
	v_mfma_f32_16x16x32_bf16 v[80:83], v[156:159], v[198:201], v[80:83]
	v_mfma_f32_16x16x32_bf16 v[68:71], v[148:151], v[206:209], v[68:71]
	v_mfma_f32_16x16x32_bf16 v[64:67], v[156:159], v[206:209], v[64:67]
	s_setprio 0
	s_barrier
	ds_read_b128 v[160:163], v197 offset:16384
	ds_read_b128 v[164:167], v197 offset:17408
	ds_read_b128 v[168:171], v197 offset:18432
	ds_read_b128 v[172:175], v197 offset:19456
	ds_read_b128 v[176:179], v197 offset:20480
	ds_read_b128 v[198:201], v197 offset:21504
	ds_read_b128 v[202:205], v197 offset:22528
	ds_read_b128 v[206:209], v197 offset:23552
	s_mov_b32 m0, s29
	s_nop 0
	global_load_lds_dwordx4 v183, s[22:23]
	s_add_u32 s86, s22, 0x160000
	s_mov_b32 m0, s30
	s_nop 0
	global_load_lds_dwordx4 v185, s[22:23]
	s_addc_u32 s87, s23, 0
	s_mov_b32 m0, s31
	s_nop 0
	global_load_lds_dwordx4 v183, s[86:87]
	s_nop 0
	s_mov_b32 m0, s33
	s_nop 0
	global_load_lds_dwordx4 v185, s[86:87]
	s_nop 0
	s_mov_b32 m0, s28
	s_nop 0
	global_load_lds_dwordx4 v182, s[24:25]
	s_nop 0
	s_mov_b32 m0, s34
	s_nop 0
	global_load_lds_dwordx4 v184, s[24:25]
	s_waitcnt vmcnt(8) lgkmcnt(0)
	s_setprio 1
	s_barrier
	v_mfma_f32_16x16x32_bf16 v[60:63], v[128:131], v[160:163], v[60:63]
	v_mfma_f32_16x16x32_bf16 v[56:59], v[136:139], v[160:163], v[56:59]
	v_mfma_f32_16x16x32_bf16 v[44:47], v[128:131], v[168:171], v[44:47]
	v_mfma_f32_16x16x32_bf16 v[40:43], v[136:139], v[168:171], v[40:43]
	v_mfma_f32_16x16x32_bf16 v[28:31], v[128:131], v[176:179], v[28:31]
	v_mfma_f32_16x16x32_bf16 v[24:27], v[136:139], v[176:179], v[24:27]
	v_mfma_f32_16x16x32_bf16 v[12:15], v[128:131], v[202:205], v[12:15]
	v_mfma_f32_16x16x32_bf16 v[8:11], v[136:139], v[202:205], v[8:11]
	v_mfma_f32_16x16x32_bf16 v[60:63], v[132:135], v[164:167], v[60:63]
	v_mfma_f32_16x16x32_bf16 v[56:59], v[140:143], v[164:167], v[56:59]
	v_mfma_f32_16x16x32_bf16 v[44:47], v[132:135], v[172:175], v[44:47]
	v_mfma_f32_16x16x32_bf16 v[40:43], v[140:143], v[172:175], v[40:43]
	v_mfma_f32_16x16x32_bf16 v[28:31], v[132:135], v[198:201], v[28:31]
	v_mfma_f32_16x16x32_bf16 v[24:27], v[140:143], v[198:201], v[24:27]
	v_mfma_f32_16x16x32_bf16 v[12:15], v[132:135], v[206:209], v[12:15]
	v_mfma_f32_16x16x32_bf16 v[8:11], v[140:143], v[206:209], v[8:11]
	v_mfma_f32_16x16x32_bf16 v[52:55], v[144:147], v[160:163], v[52:55]
	v_mfma_f32_16x16x32_bf16 v[48:51], v[152:155], v[160:163], v[48:51]
	v_mfma_f32_16x16x32_bf16 v[36:39], v[144:147], v[168:171], v[36:39]
	v_mfma_f32_16x16x32_bf16 v[32:35], v[152:155], v[168:171], v[32:35]
	v_mfma_f32_16x16x32_bf16 v[20:23], v[144:147], v[176:179], v[20:23]
	v_mfma_f32_16x16x32_bf16 v[16:19], v[152:155], v[176:179], v[16:19]
	v_mfma_f32_16x16x32_bf16 v[4:7], v[144:147], v[202:205], v[4:7]
	v_mfma_f32_16x16x32_bf16 v[0:3], v[152:155], v[202:205], v[0:3]
	v_mfma_f32_16x16x32_bf16 v[52:55], v[148:151], v[164:167], v[52:55]
	v_mfma_f32_16x16x32_bf16 v[48:51], v[156:159], v[164:167], v[48:51]
	v_mfma_f32_16x16x32_bf16 v[36:39], v[148:151], v[172:175], v[36:39]
	v_mfma_f32_16x16x32_bf16 v[32:35], v[156:159], v[172:175], v[32:35]
	v_mfma_f32_16x16x32_bf16 v[20:23], v[148:151], v[198:201], v[20:23]
	v_mfma_f32_16x16x32_bf16 v[16:19], v[156:159], v[198:201], v[16:19]
	v_mfma_f32_16x16x32_bf16 v[4:7], v[148:151], v[206:209], v[4:7]
	v_mfma_f32_16x16x32_bf16 v[0:3], v[156:159], v[206:209], v[0:3]
	s_setprio 0
	s_barrier
; #define PG8_STAGE(bufoff, gbase, voff) do { _Pragma("unroll") for (int _i = 0; _i < 2; ++_i) \
;         asm volatile("s_mov_b32 m0, %0\n\ts_nop 0\n\tglobal_load_lds_dwordx4 %1, %2" :: "s"(ldsb + (unsigned)((bufoff) + _i * 8192)), "v"((voff)[_i]), "s"(gbase) : "m0", "memory"); } while (0)
; #define PG8_LDA(dst, b, h) do { _Pragma("unroll") for (int m = 0; m < 4; ++m) _Pragma("unroll") for (int k = 0; k < 2; ++k) dst[m][k] = *(const PG8_LAS bf16x8*)(lds + PG8_SA(b, h) + aoff + m * 2048 + k * 1024); } while (0)
; #define PG8_LDB(dst, b, h) do { _Pragma("unroll") for (int n = 0; n < 2; ++n) _Pragma("unroll") for (int k = 0; k < 2; ++k) dst[n][k] = *(const PG8_LAS bf16x8*)(lds + PG8_SB(b, h) + boff + n * 2048 + k * 1024); } while (0)
; #define PG8_MMA(ai, bj, At, Bt) do { __builtin_amdgcn_s_setprio(1); _Pragma("unroll") for (int m = 0; m < 4; ++m) _Pragma("unroll") for (int n = 0; n < 2; ++n) _Pragma("unroll") for (int k = 0; k < 2; ++k) \
;         acc[ai][bj][m][n] = __builtin_amdgcn_mfma_f32_16x16x32_bf16(Bt[n][k], At[m][k], acc[ai][bj][m][n], 0, 0, 0); __builtin_amdgcn_s_setprio(0); } while (0)
; #define PG8_WAIT_V(n) asm volatile("s_waitcnt vmcnt(" #n ")" ::: "memory")
; #define PG8_WAIT_L(n) asm volatile("s_waitcnt lgkmcnt(" #n ")" ::: "memory")
; #define PG8_BAR __builtin_amdgcn_s_barrier()
; #define PG8_SCHED __builtin_amdgcn_sched_barrier(0)
; template <class Epi, class Sched, bool ALIGN_EPI = false, bool SP2 = false>
; __device__ __forceinline__ void gemm_phase(PG8_LAS unsigned char* lds, const Gemm g, const Sched& S, const Epi& E, const int wv) {
;     ...
;             PG8_LDB(B0, 1, 0); PG8_LDB(B1, 1, 1); PG8_SCHED; PG8_LDA(At, 1, 0); PG8_STAGE(PG8_SA(0, 1), a2 + hstepA, voffA);
;             PG8_WAIT_V(8); PG8_WAIT_L(0); PG8_BAR; PG8_MMA(0, 0, At, B0); PG8_MMA(0, 1, At, B1); PG8_BAR; PG8_SCHED;
;             PG8_LDA(At, 1, 1); PG8_STAGE(PG8_SB(1, 0), b3, voffB); PG8_STAGE(PG8_SB(1, 1), b3 + hstepB, voffB); PG8_STAGE(PG8_SA(1, 0), a3, voffA);
;             PG8_WAIT_V(8); PG8_WAIT_L(0); PG8_BAR; PG8_MMA(1, 0, At, B0); PG8_MMA(1, 1, At, B1); PG8_BAR; PG8_SCHED;
	ds_read_b128 v[128:131], v251
	ds_read_b128 v[132:135], v251 offset:1024
	ds_read_b128 v[136:139], v251 offset:2048
	ds_read_b128 v[140:143], v251 offset:3072
	ds_read_b128 v[144:147], v250
	ds_read_b128 v[148:151], v250 offset:1024
	ds_read_b128 v[152:155], v250 offset:2048
	ds_read_b128 v[156:159], v250 offset:3072
	ds_read_b128 v[160:163], v197 offset:32768
	ds_read_b128 v[164:167], v197 offset:33792
	ds_read_b128 v[168:171], v197 offset:34816
	ds_read_b128 v[172:175], v197 offset:35840
	ds_read_b128 v[176:179], v197 offset:36864
	ds_read_b128 v[198:201], v197 offset:37888
	ds_read_b128 v[202:205], v197 offset:38912
	ds_read_b128 v[206:209], v197 offset:39936
	s_add_u32 s24, s24, 0x160000
	s_addc_u32 s25, s25, 0
	s_mov_b32 m0, s35
	s_nop 0
	global_load_lds_dwordx4 v182, s[24:25]
	s_nop 0
	s_mov_b32 m0, s36
	s_nop 0
	global_load_lds_dwordx4 v184, s[24:25]
	s_waitcnt vmcnt(8) lgkmcnt(0)
	s_setprio 1
	s_barrier
	v_mfma_f32_16x16x32_bf16 v[124:127], v[128:131], v[160:163], v[124:127]
	v_mfma_f32_16x16x32_bf16 v[120:123], v[136:139], v[160:163], v[120:123]
	v_mfma_f32_16x16x32_bf16 v[108:111], v[128:131], v[168:171], v[108:111]
	v_mfma_f32_16x16x32_bf16 v[104:107], v[136:139], v[168:171], v[104:107]
	v_mfma_f32_16x16x32_bf16 v[92:95], v[128:131], v[176:179], v[92:95]
	v_mfma_f32_16x16x32_bf16 v[88:91], v[136:139], v[176:179], v[88:91]
	v_mfma_f32_16x16x32_bf16 v[76:79], v[128:131], v[202:205], v[76:79]
	v_mfma_f32_16x16x32_bf16 v[72:75], v[136:139], v[202:205], v[72:75]
	v_mfma_f32_16x16x32_bf16 v[124:127], v[132:135], v[164:167], v[124:127]
	v_mfma_f32_16x16x32_bf16 v[120:123], v[140:143], v[164:167], v[120:123]
	v_mfma_f32_16x16x32_bf16 v[108:111], v[132:135], v[172:175], v[108:111]
	v_mfma_f32_16x16x32_bf16 v[104:107], v[140:143], v[172:175], v[104:107]
	v_mfma_f32_16x16x32_bf16 v[92:95], v[132:135], v[198:201], v[92:95]
	v_mfma_f32_16x16x32_bf16 v[88:91], v[140:143], v[198:201], v[88:91]
	v_mfma_f32_16x16x32_bf16 v[76:79], v[132:135], v[206:209], v[76:79]
	v_mfma_f32_16x16x32_bf16 v[72:75], v[140:143], v[206:209], v[72:75]
	v_mfma_f32_16x16x32_bf16 v[116:119], v[144:147], v[160:163], v[116:119]
	v_mfma_f32_16x16x32_bf16 v[112:115], v[152:155], v[160:163], v[112:115]
	v_mfma_f32_16x16x32_bf16 v[100:103], v[144:147], v[168:171], v[100:103]
	v_mfma_f32_16x16x32_bf16 v[96:99], v[152:155], v[168:171], v[96:99]
	v_mfma_f32_16x16x32_bf16 v[84:87], v[144:147], v[176:179], v[84:87]
	v_mfma_f32_16x16x32_bf16 v[80:83], v[152:155], v[176:179], v[80:83]
	v_mfma_f32_16x16x32_bf16 v[68:71], v[144:147], v[202:205], v[68:71]
	v_mfma_f32_16x16x32_bf16 v[64:67], v[152:155], v[202:205], v[64:67]
	v_mfma_f32_16x16x32_bf16 v[116:119], v[148:151], v[164:167], v[116:119]
	v_mfma_f32_16x16x32_bf16 v[112:115], v[156:159], v[164:167], v[112:115]
	v_mfma_f32_16x16x32_bf16 v[100:103], v[148:151], v[172:175], v[100:103]
	v_mfma_f32_16x16x32_bf16 v[96:99], v[156:159], v[172:175], v[96:99]
	v_mfma_f32_16x16x32_bf16 v[84:87], v[148:151], v[198:201], v[84:87]
	v_mfma_f32_16x16x32_bf16 v[80:83], v[156:159], v[198:201], v[80:83]
	v_mfma_f32_16x16x32_bf16 v[68:71], v[148:151], v[206:209], v[68:71]
	v_mfma_f32_16x16x32_bf16 v[64:67], v[156:159], v[206:209], v[64:67]
	s_setprio 0
	s_barrier
	ds_read_b128 v[160:163], v197 offset:49152
	ds_read_b128 v[164:167], v197 offset:50176
	ds_read_b128 v[168:171], v197 offset:51200
	ds_read_b128 v[172:175], v197 offset:52224
	ds_read_b128 v[176:179], v197 offset:53248
	ds_read_b128 v[198:201], v197 offset:54272
	ds_read_b128 v[202:205], v197 offset:55296
	ds_read_b128 v[206:209], v197 offset:56320
	s_add_u32 s24, s22, 0x80
	s_addc_u32 s25, s23, 0
	s_mov_b32 m0, s44
	s_nop 0
	global_load_lds_dwordx4 v183, s[24:25]
	s_add_u32 s22, s22, 0x160080
	s_mov_b32 m0, s45
	s_nop 0
	global_load_lds_dwordx4 v185, s[24:25]
	s_addc_u32 s23, s23, 0
	s_mov_b32 m0, s48
	s_nop 0
	global_load_lds_dwordx4 v183, s[22:23]
	s_nop 0
	s_mov_b32 m0, s49
	s_nop 0
	global_load_lds_dwordx4 v185, s[22:23]
	s_nop 0
	s_mov_b32 m0, s46
	s_nop 0
	global_load_lds_dwordx4 v182, s[20:21]
	s_nop 0
	s_mov_b32 m0, s47
	s_nop 0
	global_load_lds_dwordx4 v184, s[20:21]
	s_waitcnt vmcnt(8) lgkmcnt(0)
	s_setprio 1
	s_barrier
	v_mfma_f32_16x16x32_bf16 v[60:63], v[128:131], v[160:163], v[60:63]
	v_mfma_f32_16x16x32_bf16 v[56:59], v[136:139], v[160:163], v[56:59]
	v_mfma_f32_16x16x32_bf16 v[44:47], v[128:131], v[168:171], v[44:47]
	v_mfma_f32_16x16x32_bf16 v[40:43], v[136:139], v[168:171], v[40:43]
	v_mfma_f32_16x16x32_bf16 v[28:31], v[128:131], v[176:179], v[28:31]
	v_mfma_f32_16x16x32_bf16 v[24:27], v[136:139], v[176:179], v[24:27]
	v_mfma_f32_16x16x32_bf16 v[12:15], v[128:131], v[202:205], v[12:15]
	v_mfma_f32_16x16x32_bf16 v[8:11], v[136:139], v[202:205], v[8:11]
	v_mfma_f32_16x16x32_bf16 v[60:63], v[132:135], v[164:167], v[60:63]
	v_mfma_f32_16x16x32_bf16 v[56:59], v[140:143], v[164:167], v[56:59]
	v_mfma_f32_16x16x32_bf16 v[44:47], v[132:135], v[172:175], v[44:47]
	v_mfma_f32_16x16x32_bf16 v[40:43], v[140:143], v[172:175], v[40:43]
	v_mfma_f32_16x16x32_bf16 v[28:31], v[132:135], v[198:201], v[28:31]
	v_mfma_f32_16x16x32_bf16 v[24:27], v[140:143], v[198:201], v[24:27]
	v_mfma_f32_16x16x32_bf16 v[12:15], v[132:135], v[206:209], v[12:15]
	v_mfma_f32_16x16x32_bf16 v[8:11], v[140:143], v[206:209], v[8:11]
	v_mfma_f32_16x16x32_bf16 v[52:55], v[144:147], v[160:163], v[52:55]
	v_mfma_f32_16x16x32_bf16 v[48:51], v[152:155], v[160:163], v[48:51]
	v_mfma_f32_16x16x32_bf16 v[36:39], v[144:147], v[168:171], v[36:39]
	v_mfma_f32_16x16x32_bf16 v[32:35], v[152:155], v[168:171], v[32:35]
	v_mfma_f32_16x16x32_bf16 v[20:23], v[144:147], v[176:179], v[20:23]
	v_mfma_f32_16x16x32_bf16 v[16:19], v[152:155], v[176:179], v[16:19]
	v_mfma_f32_16x16x32_bf16 v[4:7], v[144:147], v[202:205], v[4:7]
	v_mfma_f32_16x16x32_bf16 v[0:3], v[152:155], v[202:205], v[0:3]
	v_mfma_f32_16x16x32_bf16 v[52:55], v[148:151], v[164:167], v[52:55]
	v_mfma_f32_16x16x32_bf16 v[48:51], v[156:159], v[164:167], v[48:51]
	v_mfma_f32_16x16x32_bf16 v[36:39], v[148:151], v[172:175], v[36:39]
	v_mfma_f32_16x16x32_bf16 v[32:35], v[156:159], v[172:175], v[32:35]
	v_mfma_f32_16x16x32_bf16 v[20:23], v[148:151], v[198:201], v[20:23]
	v_mfma_f32_16x16x32_bf16 v[16:19], v[156:159], v[198:201], v[16:19]
	v_mfma_f32_16x16x32_bf16 v[4:7], v[148:151], v[206:209], v[4:7]
	v_mfma_f32_16x16x32_bf16 v[0:3], v[156:159], v[206:209], v[0:3]
	s_setprio 0
	s_barrier
	s_add_u32 s77, s77, 0x100
	s_addc_u32 s79, s79, 0
	s_add_u32 s83, s83, 0x100
	s_addc_u32 s84, s84, 0
	s_cmp_ge_i32 s85, s65
	s_mov_b32 s20, s85
	s_cbranch_scc0 .LBB0_1244
	s_mov_b32 s79, 0xc00000
	s_and_b64 vcc, exec, s[12:13]
	s_cbranch_vccz .LBB0_1247

; #define PG8_BAR __builtin_amdgcn_s_barrier()
; template <class Epi, class Sched, bool ALIGN_EPI = false, bool SP2 = false>
; __device__ __forceinline__ void gemm_phase(PG8_LAS unsigned char* lds, const Gemm g, const Sched& S, const Epi& E, const int wv) {
;     ...
;     const int tid = tid_of(wv), wid = wid_, lane = tid & 63, wr = wid >> 2, wc = wid & 3, fr = lane & 15, fq = lane >> 4;
;     const int K = g.ld, Kb = g.ldb ? g.ldb : g.ld;
;     unsigned voffA[2], voffB[2];
; #pragma unroll
;     for (int i = 0; i < 2; ++i) { int R, C; stage_rc(tid * 16 + i * 8192, R, C); const int Rb = Epi::PERM ? ((R & ~31) + perm32(R & 31)) : R;
;         voffA[i] = (unsigned)(R * K + C) * 2u; voffB[i] = (unsigned)(Rb * Kb + C) * 2u; }
;     const size_t kstep = (size_t)(BK * 2);
;     const size_t hstepA = (size_t)HALF * K * 2, hstepB = (size_t)HALF * Kb * 2;
;     const size_t tstepA = 2 * hstepA, tstepB = 2 * hstepB;
;     const unsigned ldsw = (unsigned)wid * 1024u;
;     const unsigned ldsb = (unsigned)(size_t)lds + ldsw;
;     const int aoff = lds_byte(wr * 64 + fr, fq * 8), boff = lds_byte(wc * 32 + fr, fq * 8);
;     ...
;         PG8_STAGE(PG8_SB(0, 0), cB, voffB); PG8_STAGE(PG8_SB(0, 1), cB + hstepB, voffB); PG8_STAGE(PG8_SA(0, 0), cA, voffA); PG8_STAGE(PG8_SA(0, 1), cA + hstepA, voffA);
;         if (wr == 1) PG8_BAR;
;         PG8_WAIT_V(2); PG8_BAR;
;         PG8_STAGE(PG8_SB(1, 0), cB + kstep, voffB); PG8_STAGE(PG8_SA(1, 0), cA + kstep, voffA); PG8_STAGE(PG8_SB(1, 1), cB + hstepB + kstep, voffB);
;         PG8_WAIT_V(6); PG8_BAR;
;     __device__ __forceinline__ void operator()(AccT acc, const pg8::Unit& u, int wr, int wc, int fr, int fq) const {
;         const int row0 = u.pm * 256 + wr * 64 + fr, col0 = u.pn * 256 + wc * 32 + 8 * fq, lane = fq * 16 + fr;
;         const int bidx = u.pm < 64 ? (u.pm >> 4) : 4;
;         const float* gp = gate + (size_t)bidx * MODW + col0;
;         f32x4 gv[2][2], gz[2][2];
; #pragma unroll
;         for (int bj = 0; bj < 2; ++bj)
; #pragma unroll
;             for (int n = 0; n < 2; ++n) { gv[bj][n] = *(const f32x4*)(gp + bj * 128 + n * 4) * coef;
;                 if (WZ) gz[bj][n] = *(const f32x4*)(gnext + col0 + bj * 128 + n * 4) * (*(const f32x4*)(scnext + (size_t)bidx * MODW + col0 + bj * 128 + n * 4) + 1.f); }
;         const int st4 = ((lane & 3) * 16 + (lane >> 2)) * 4, ld4 = ((lane & 15) * 4 + (lane >> 4)) * 4;
.LBB0_1317:
	v_readlane_b32 s10, v254, 56
	v_readlane_b32 s2, v254, 32
	v_readlane_b32 s11, v254, 57
	s_bfe_u32 s40, s2, 0x80010
	s_bfe_u32 s23, s2, 0x40018
	s_lshl_b64 s[12:13], s[10:11], 2
	s_add_u32 s2, s8, s12
	s_addc_u32 s10, s9, s13
	s_add_u32 s12, s8, 0x44f000
	s_addc_u32 s13, s9, 0
	s_add_u32 s54, s2, 0x30000
	s_addc_u32 s55, s10, 0
	s_add_u32 s14, s8, 0x8c4f000
	s_addc_u32 s15, s9, 0
	s_waitcnt lgkmcnt(0)
	s_add_u32 s16, s6, 0x6000
	s_addc_u32 s17, s7, 0
	s_add_u32 s57, s2, 0x7c000
	s_addc_u32 s72, s10, 0
	v_bfe_u32 v1, v0, 4, 2
	s_add_u32 s18, s8, 0x3b98f000
	v_and_b32_e32 v212, 15, v0
	v_lshlrev_b32_e32 v2, 4, v1
	v_lshlrev_b32_e32 v3, 2, v0
	s_addc_u32 s19, s9, 0
	s_and_b32 s2, s22, 3
	v_lshl_or_b32 v2, v212, 6, v2
	s_lshl_b32 s6, s24, 13
	v_and_b32_e32 v3, 32, v3
	s_lshl_b32 s84, s24, 6
	v_bitop3_b32 v4, v2, s6, v3 bitop3:0xde
	s_lshl_b32 s10, s2, 5
	s_lshl_b32 s6, s2, 12
	s_add_i32 s87, s46, 0x18000
	v_bitop3_b32 v3, v2, s6, v3 bitop3:0xde
	s_add_u32 s6, s30, 0x80
	s_waitcnt vmcnt(2)
	s_barrier
	s_addc_u32 s7, s31, 0
	s_mov_b32 m0, s87
	s_nop 0
	global_load_lds_dwordx4 v209, s[6:7]
	s_add_i32 s83, s46, 0x1a000
	s_add_i32 s60, s46, 0x8000
	s_mov_b32 m0, s83
	s_nop 0
	global_load_lds_dwordx4 v211, s[6:7]
	s_add_u32 s6, s34, 0x80
	s_addc_u32 s7, s35, 0
	s_mov_b32 m0, s60
	s_nop 0
	global_load_lds_dwordx4 v208, s[6:7]
	s_add_i32 s89, s46, 0xa000
	s_add_i32 s92, s46, 0x1c000
	s_mov_b32 m0, s89
	s_nop 0
	global_load_lds_dwordx4 v210, s[6:7]
	s_add_u32 s6, s20, 0x80
	s_addc_u32 s7, s21, 0
	s_add_i32 s93, s46, 0x1e000
	s_add_i32 s71, s46, 0xc000
	s_mov_b32 m0, s92
	s_nop 0
	global_load_lds_dwordx4 v209, s[6:7]
	s_cmp_lt_u32 s22, 4
	s_mov_b32 m0, s93
	s_nop 0
	global_load_lds_dwordx4 v211, s[6:7]
	s_cselect_b64 s[20:21], -1, 0
	s_ashr_i32 s6, s84, 31
	s_add_i32 s88, s46, 0xe000
	s_lshl_b32 s2, s2, 2
	s_add_u32 s2, s8, s2
	v_lshrrev_b32_e32 v5, 2, v0
	s_addc_u32 s8, s9, 0
	s_waitcnt vmcnt(6)
	v_and_b32_e32 v2, 3, v0
	v_and_b32_e32 v6, 60, v0
	v_and_or_b32 v156, v5, 15, s84
	v_and_b32_e32 v5, 63, v0
	v_bfe_u32 v215, v0, 2, 4
	v_lshlrev_b32_e32 v0, 4, v212
	s_add_u32 s97, s2, 0x21e000
	s_mov_b32 s2, s26
	v_lshl_or_b32 v214, v2, 6, v6
	v_lshlrev_b32_e32 v2, 3, v2
	v_lshl_or_b32 v216, v1, 2, v0
	v_lshlrev_b32_e32 v0, 2, v5
	v_writelane_b32 v254, s2, 30
	v_lshl_or_b32 v213, v1, 3, s10
	v_mov_b32_e32 v157, s6
	v_or_b32_e32 v217, s10, v2
	v_xor_b32_e32 v218, 64, v0
	v_xor_b32_e32 v219, 0x80, v0
	s_mov_b32 s58, 0
	v_cmp_eq_u32_e64 s[6:7], 0, v1
	s_addc_u32 s90, s8, 0
	s_ashr_i32 s94, s70, 31
	v_add_u32_e32 v220, 0, v3
	v_add_u32_e32 v253, 0x10000, v220
	v_add_u32_e32 v252, 0x14000, v220
	v_add_u32_e32 v251, 0x18000, v220
	v_add_u32_e32 v250, 0x1c000, v220
	v_add_u32_e32 v221, 0, v4
	s_lshl_b32 s22, s10, 1
	v_lshlrev_b32_e32 v158, 1, v2
	v_writelane_b32 v254, s3, 31
	s_mov_b32 s24, s26
	s_barrier
	s_branch .LBB0_1320

; #define PG8_STAGE(bufoff, gbase, voff) do { _Pragma("unroll") for (int _i = 0; _i < 2; ++_i) \
;         asm volatile("s_mov_b32 m0, %0\n\ts_nop 0\n\tglobal_load_lds_dwordx4 %1, %2" :: "s"(ldsb + (unsigned)((bufoff) + _i * 8192)), "v"((voff)[_i]), "s"(gbase) : "m0", "memory"); } while (0)
; #define PG8_LDA(dst, b, h) do { _Pragma("unroll") for (int m = 0; m < 4; ++m) _Pragma("unroll") for (int k = 0; k < 2; ++k) dst[m][k] = *(const PG8_LAS bf16x8*)(lds + PG8_SA(b, h) + aoff + m * 2048 + k * 1024); } while (0)
; #define PG8_LDB(dst, b, h) do { _Pragma("unroll") for (int n = 0; n < 2; ++n) _Pragma("unroll") for (int k = 0; k < 2; ++k) dst[n][k] = *(const PG8_LAS bf16x8*)(lds + PG8_SB(b, h) + boff + n * 2048 + k * 1024); } while (0)
; #define PG8_MMA(ai, bj, At, Bt) do { __builtin_amdgcn_s_setprio(1); _Pragma("unroll") for (int m = 0; m < 4; ++m) _Pragma("unroll") for (int n = 0; n < 2; ++n) _Pragma("unroll") for (int k = 0; k < 2; ++k) \
;         acc[ai][bj][m][n] = __builtin_amdgcn_mfma_f32_16x16x32_bf16(Bt[n][k], At[m][k], acc[ai][bj][m][n], 0, 0, 0); __builtin_amdgcn_s_setprio(0); } while (0)
; #define PG8_WAIT_V(n) asm volatile("s_waitcnt vmcnt(" #n ")" ::: "memory")
; #define PG8_WAIT_L(n) asm volatile("s_waitcnt lgkmcnt(" #n ")" ::: "memory")
; template <class Epi, class Sched, bool ALIGN_EPI = false, bool SP2 = false>
; __device__ __forceinline__ void gemm_phase(PG8_LAS unsigned char* lds, const Gemm g, const Sched& S, const Epi& E, const int wv) {
;     ...
;             const bool last = (t == nt - 2);
;             const char* a1 = cA + (size_t)(t + 1) * kstep;
;             const char* a2 = last ? nA : cA + (size_t)(t + 2) * kstep; const char* b2 = last ? nB : cB + (size_t)(t + 2) * kstep;
;             const char* a3 = a2 + kstep; const char* b3 = b2 + kstep;
;             if (last && has_next) S.a_ready(nxt);
;             if constexpr (SP2) {
;             PG8_LDB(B0, 0, 0); PG8_LDB(B1, 0, 1); PG8_SCHED; PG8_LDA(At, 0, 0); PG8_STAGE(PG8_SA(1, 1), a1 + hstepA, voffA);
;             PG8_WAIT_V(8); PG8_WAIT_L(0); PG8_BAR; PG8_MMA(0, 0, At, B0); PG8_MMA(0, 1, At, B1); PG8_BAR; PG8_SCHED;
;             PG8_LDA(At, 0, 1); PG8_STAGE(PG8_SB(0, 0), b2, voffB); PG8_STAGE(PG8_SB(0, 1), b2 + hstepB, voffB); PG8_STAGE(PG8_SA(0, 0), a2, voffA);
;             PG8_WAIT_V(8); PG8_WAIT_L(0); PG8_BAR; PG8_MMA(1, 0, At, B0); PG8_MMA(1, 1, At, B1); PG8_BAR; PG8_SCHED;
.LBB0_1336:
	ds_read_b128 v[128:131], v253
	ds_read_b128 v[132:135], v253 offset:1024
	ds_read_b128 v[136:139], v253 offset:2048
	ds_read_b128 v[140:143], v253 offset:3072
	ds_read_b128 v[144:147], v252
	ds_read_b128 v[148:151], v252 offset:1024
	ds_read_b128 v[152:155], v252 offset:2048
	ds_read_b128 v[160:163], v252 offset:3072
	s_add_i32 vcc_hi, s34, 2
	s_cmp_eq_u32 s25, s34
	s_cselect_b32 s42, s26, s85
	s_cselect_b32 s43, s27, vcc_lo
	s_cselect_b32 s36, s28, s79
	s_cselect_b32 s37, s29, s62
	s_add_u32 s34, s42, 0x80
	s_addc_u32 s35, s43, 0
	ds_read_b128 v[164:167], v221
	ds_read_b128 v[168:171], v221 offset:1024
	ds_read_b128 v[172:175], v221 offset:2048
	ds_read_b128 v[176:179], v221 offset:3072
	ds_read_b128 v[180:183], v221 offset:4096
	ds_read_b128 v[184:187], v221 offset:5120
	ds_read_b128 v[188:191], v221 offset:6144
	ds_read_b128 v[194:197], v221 offset:7168
	s_mov_b32 m0, s71
	s_nop 0
	global_load_lds_dwordx4 v208, s[30:31]
	s_nop 0
	s_mov_b32 m0, s88
	s_nop 0
	global_load_lds_dwordx4 v210, s[30:31]
	s_waitcnt vmcnt(8) lgkmcnt(0)
	s_setprio 1
	s_barrier
	v_mfma_f32_16x16x32_bf16 v[124:127], v[128:131], v[164:167], v[124:127]
	v_mfma_f32_16x16x32_bf16 v[120:123], v[136:139], v[164:167], v[120:123]
	v_mfma_f32_16x16x32_bf16 v[108:111], v[128:131], v[172:175], v[108:111]
	v_mfma_f32_16x16x32_bf16 v[104:107], v[136:139], v[172:175], v[104:107]
	v_mfma_f32_16x16x32_bf16 v[92:95], v[128:131], v[180:183], v[92:95]
	v_mfma_f32_16x16x32_bf16 v[88:91], v[136:139], v[180:183], v[88:91]
	v_mfma_f32_16x16x32_bf16 v[76:79], v[128:131], v[188:191], v[76:79]
	v_mfma_f32_16x16x32_bf16 v[72:75], v[136:139], v[188:191], v[72:75]
	v_mfma_f32_16x16x32_bf16 v[124:127], v[132:135], v[168:171], v[124:127]
	v_mfma_f32_16x16x32_bf16 v[120:123], v[140:143], v[168:171], v[120:123]
	v_mfma_f32_16x16x32_bf16 v[108:111], v[132:135], v[176:179], v[108:111]
	v_mfma_f32_16x16x32_bf16 v[104:107], v[140:143], v[176:179], v[104:107]
	v_mfma_f32_16x16x32_bf16 v[92:95], v[132:135], v[184:187], v[92:95]
	v_mfma_f32_16x16x32_bf16 v[88:91], v[140:143], v[184:187], v[88:91]
	v_mfma_f32_16x16x32_bf16 v[76:79], v[132:135], v[194:197], v[76:79]
	v_mfma_f32_16x16x32_bf16 v[72:75], v[140:143], v[194:197], v[72:75]
	v_mfma_f32_16x16x32_bf16 v[116:119], v[144:147], v[164:167], v[116:119]
	v_mfma_f32_16x16x32_bf16 v[112:115], v[152:155], v[164:167], v[112:115]
	v_mfma_f32_16x16x32_bf16 v[100:103], v[144:147], v[172:175], v[100:103]
	v_mfma_f32_16x16x32_bf16 v[96:99], v[152:155], v[172:175], v[96:99]
	v_mfma_f32_16x16x32_bf16 v[84:87], v[144:147], v[180:183], v[84:87]
	v_mfma_f32_16x16x32_bf16 v[80:83], v[152:155], v[180:183], v[80:83]
	v_mfma_f32_16x16x32_bf16 v[68:71], v[144:147], v[188:191], v[68:71]
	v_mfma_f32_16x16x32_bf16 v[64:67], v[152:155], v[188:191], v[64:67]
	v_mfma_f32_16x16x32_bf16 v[116:119], v[148:151], v[168:171], v[116:119]
	v_mfma_f32_16x16x32_bf16 v[112:115], v[160:163], v[168:171], v[112:115]
	v_mfma_f32_16x16x32_bf16 v[100:103], v[148:151], v[176:179], v[100:103]
	v_mfma_f32_16x16x32_bf16 v[96:99], v[160:163], v[176:179], v[96:99]
	v_mfma_f32_16x16x32_bf16 v[84:87], v[148:151], v[184:187], v[84:87]
	v_mfma_f32_16x16x32_bf16 v[80:83], v[160:163], v[184:187], v[80:83]
	v_mfma_f32_16x16x32_bf16 v[68:71], v[148:151], v[194:197], v[68:71]
	v_mfma_f32_16x16x32_bf16 v[64:67], v[160:163], v[194:197], v[64:67]
	s_setprio 0
	s_barrier
	ds_read_b128 v[164:167], v221 offset:16384
	ds_read_b128 v[168:171], v221 offset:17408
	ds_read_b128 v[172:175], v221 offset:18432
	ds_read_b128 v[176:179], v221 offset:19456
	ds_read_b128 v[180:183], v221 offset:20480
	ds_read_b128 v[184:187], v221 offset:21504
	ds_read_b128 v[188:191], v221 offset:22528
	ds_read_b128 v[194:197], v221 offset:23552
	s_mov_b32 m0, s47
	s_nop 0
	global_load_lds_dwordx4 v209, s[36:37]
	s_add_u32 s10, s36, 0x160000
	s_mov_b32 m0, s48
	s_nop 0
	global_load_lds_dwordx4 v211, s[36:37]
	s_addc_u32 s11, s37, 0
	s_mov_b32 m0, s49
	s_nop 0
	global_load_lds_dwordx4 v209, s[10:11]
	s_nop 0
	s_mov_b32 m0, s50
	s_nop 0
	global_load_lds_dwordx4 v211, s[10:11]
	s_nop 0
	s_mov_b32 m0, s46
	s_nop 0
	global_load_lds_dwordx4 v208, s[42:43]
	s_nop 0
	s_mov_b32 m0, s51
	s_nop 0
	global_load_lds_dwordx4 v210, s[42:43]
	s_waitcnt vmcnt(8) lgkmcnt(0)
	s_setprio 1
	s_barrier
	v_mfma_f32_16x16x32_bf16 v[60:63], v[128:131], v[164:167], v[60:63]
	v_mfma_f32_16x16x32_bf16 v[56:59], v[136:139], v[164:167], v[56:59]
	v_mfma_f32_16x16x32_bf16 v[44:47], v[128:131], v[172:175], v[44:47]
	v_mfma_f32_16x16x32_bf16 v[40:43], v[136:139], v[172:175], v[40:43]
	v_mfma_f32_16x16x32_bf16 v[28:31], v[128:131], v[180:183], v[28:31]
	v_mfma_f32_16x16x32_bf16 v[24:27], v[136:139], v[180:183], v[24:27]
	v_mfma_f32_16x16x32_bf16 v[12:15], v[128:131], v[188:191], v[12:15]
	v_mfma_f32_16x16x32_bf16 v[8:11], v[136:139], v[188:191], v[8:11]
	v_mfma_f32_16x16x32_bf16 v[60:63], v[132:135], v[168:171], v[60:63]
	v_mfma_f32_16x16x32_bf16 v[56:59], v[140:143], v[168:171], v[56:59]
	v_mfma_f32_16x16x32_bf16 v[44:47], v[132:135], v[176:179], v[44:47]
	v_mfma_f32_16x16x32_bf16 v[40:43], v[140:143], v[176:179], v[40:43]
	v_mfma_f32_16x16x32_bf16 v[28:31], v[132:135], v[184:187], v[28:31]
	v_mfma_f32_16x16x32_bf16 v[24:27], v[140:143], v[184:187], v[24:27]
	v_mfma_f32_16x16x32_bf16 v[12:15], v[132:135], v[194:197], v[12:15]
	v_mfma_f32_16x16x32_bf16 v[8:11], v[140:143], v[194:197], v[8:11]
	v_mfma_f32_16x16x32_bf16 v[52:55], v[144:147], v[164:167], v[52:55]
	v_mfma_f32_16x16x32_bf16 v[48:51], v[152:155], v[164:167], v[48:51]
	v_mfma_f32_16x16x32_bf16 v[36:39], v[144:147], v[172:175], v[36:39]
	v_mfma_f32_16x16x32_bf16 v[32:35], v[152:155], v[172:175], v[32:35]
	v_mfma_f32_16x16x32_bf16 v[20:23], v[144:147], v[180:183], v[20:23]
	v_mfma_f32_16x16x32_bf16 v[16:19], v[152:155], v[180:183], v[16:19]
	v_mfma_f32_16x16x32_bf16 v[4:7], v[144:147], v[188:191], v[4:7]
	v_mfma_f32_16x16x32_bf16 v[0:3], v[152:155], v[188:191], v[0:3]
	v_mfma_f32_16x16x32_bf16 v[52:55], v[148:151], v[168:171], v[52:55]
	v_mfma_f32_16x16x32_bf16 v[48:51], v[160:163], v[168:171], v[48:51]
	v_mfma_f32_16x16x32_bf16 v[36:39], v[148:151], v[176:179], v[36:39]
	v_mfma_f32_16x16x32_bf16 v[32:35], v[160:163], v[176:179], v[32:35]
	v_mfma_f32_16x16x32_bf16 v[20:23], v[148:151], v[184:187], v[20:23]
	v_mfma_f32_16x16x32_bf16 v[16:19], v[160:163], v[184:187], v[16:19]
	v_mfma_f32_16x16x32_bf16 v[4:7], v[148:151], v[194:197], v[4:7]
	v_mfma_f32_16x16x32_bf16 v[0:3], v[160:163], v[194:197], v[0:3]
	s_setprio 0
	s_barrier
; #define PG8_STAGE(bufoff, gbase, voff) do { _Pragma("unroll") for (int _i = 0; _i < 2; ++_i) \
;         asm volatile("s_mov_b32 m0, %0\n\ts_nop 0\n\tglobal_load_lds_dwordx4 %1, %2" :: "s"(ldsb + (unsigned)((bufoff) + _i * 8192)), "v"((voff)[_i]), "s"(gbase) : "m0", "memory"); } while (0)
; #define PG8_LDA(dst, b, h) do { _Pragma("unroll") for (int m = 0; m < 4; ++m) _Pragma("unroll") for (int k = 0; k < 2; ++k) dst[m][k] = *(const PG8_LAS bf16x8*)(lds + PG8_SA(b, h) + aoff + m * 2048 + k * 1024); } while (0)
; #define PG8_LDB(dst, b, h) do { _Pragma("unroll") for (int n = 0; n < 2; ++n) _Pragma("unroll") for (int k = 0; k < 2; ++k) dst[n][k] = *(const PG8_LAS bf16x8*)(lds + PG8_SB(b, h) + boff + n * 2048 + k * 1024); } while (0)
; #define PG8_MMA(ai, bj, At, Bt) do { __builtin_amdgcn_s_setprio(1); _Pragma("unroll") for (int m = 0; m < 4; ++m) _Pragma("unroll") for (int n = 0; n < 2; ++n) _Pragma("unroll") for (int k = 0; k < 2; ++k) \
;         acc[ai][bj][m][n] = __builtin_amdgcn_mfma_f32_16x16x32_bf16(Bt[n][k], At[m][k], acc[ai][bj][m][n], 0, 0, 0); __builtin_amdgcn_s_setprio(0); } while (0)
; #define PG8_WAIT_V(n) asm volatile("s_waitcnt vmcnt(" #n ")" ::: "memory")
; #define PG8_WAIT_L(n) asm volatile("s_waitcnt lgkmcnt(" #n ")" ::: "memory")
; #define PG8_BAR __builtin_amdgcn_s_barrier()
; #define PG8_SCHED __builtin_amdgcn_sched_barrier(0)
; template <class Epi, class Sched, bool ALIGN_EPI = false, bool SP2 = false>
; __device__ __forceinline__ void gemm_phase(PG8_LAS unsigned char* lds, const Gemm g, const Sched& S, const Epi& E, const int wv) {
;     ...
;             PG8_LDB(B0, 1, 0); PG8_LDB(B1, 1, 1); PG8_SCHED; PG8_LDA(At, 1, 0); PG8_STAGE(PG8_SA(0, 1), a2 + hstepA, voffA);
;             PG8_WAIT_V(8); PG8_WAIT_L(0); PG8_BAR; PG8_MMA(0, 0, At, B0); PG8_MMA(0, 1, At, B1); PG8_BAR; PG8_SCHED;
;             PG8_LDA(At, 1, 1); PG8_STAGE(PG8_SB(1, 0), b3, voffB); PG8_STAGE(PG8_SB(1, 1), b3 + hstepB, voffB); PG8_STAGE(PG8_SA(1, 0), a3, voffA);
;             PG8_WAIT_V(8); PG8_WAIT_L(0); PG8_BAR; PG8_MMA(1, 0, At, B0); PG8_MMA(1, 1, At, B1); PG8_BAR; PG8_SCHED;
	ds_read_b128 v[128:131], v251
	ds_read_b128 v[132:135], v251 offset:1024
	ds_read_b128 v[136:139], v251 offset:2048
	ds_read_b128 v[140:143], v251 offset:3072
	ds_read_b128 v[144:147], v250
	ds_read_b128 v[148:151], v250 offset:1024
	ds_read_b128 v[152:155], v250 offset:2048
	ds_read_b128 v[160:163], v250 offset:3072
	ds_read_b128 v[164:167], v221 offset:32768
	ds_read_b128 v[168:171], v221 offset:33792
	ds_read_b128 v[172:175], v221 offset:34816
	ds_read_b128 v[176:179], v221 offset:35840
	ds_read_b128 v[180:183], v221 offset:36864
	ds_read_b128 v[184:187], v221 offset:37888
	ds_read_b128 v[188:191], v221 offset:38912
	ds_read_b128 v[194:197], v221 offset:39936
	s_add_u32 s10, s42, 0x160000
	s_addc_u32 s11, s43, 0
	s_mov_b32 m0, s52
	s_nop 0
	global_load_lds_dwordx4 v208, s[10:11]
	s_nop 0
	s_mov_b32 m0, s53
	s_nop 0
	global_load_lds_dwordx4 v210, s[10:11]
	s_waitcnt vmcnt(8) lgkmcnt(0)
	s_setprio 1
	s_barrier
	v_mfma_f32_16x16x32_bf16 v[124:127], v[128:131], v[164:167], v[124:127]
	v_mfma_f32_16x16x32_bf16 v[120:123], v[136:139], v[164:167], v[120:123]
	v_mfma_f32_16x16x32_bf16 v[108:111], v[128:131], v[172:175], v[108:111]
	v_mfma_f32_16x16x32_bf16 v[104:107], v[136:139], v[172:175], v[104:107]
	v_mfma_f32_16x16x32_bf16 v[92:95], v[128:131], v[180:183], v[92:95]
	v_mfma_f32_16x16x32_bf16 v[88:91], v[136:139], v[180:183], v[88:91]
	v_mfma_f32_16x16x32_bf16 v[76:79], v[128:131], v[188:191], v[76:79]
	v_mfma_f32_16x16x32_bf16 v[72:75], v[136:139], v[188:191], v[72:75]
	v_mfma_f32_16x16x32_bf16 v[124:127], v[132:135], v[168:171], v[124:127]
	v_mfma_f32_16x16x32_bf16 v[120:123], v[140:143], v[168:171], v[120:123]
	v_mfma_f32_16x16x32_bf16 v[108:111], v[132:135], v[176:179], v[108:111]
	v_mfma_f32_16x16x32_bf16 v[104:107], v[140:143], v[176:179], v[104:107]
	v_mfma_f32_16x16x32_bf16 v[92:95], v[132:135], v[184:187], v[92:95]
	v_mfma_f32_16x16x32_bf16 v[88:91], v[140:143], v[184:187], v[88:91]
	v_mfma_f32_16x16x32_bf16 v[76:79], v[132:135], v[194:197], v[76:79]
	v_mfma_f32_16x16x32_bf16 v[72:75], v[140:143], v[194:197], v[72:75]
	v_mfma_f32_16x16x32_bf16 v[116:119], v[144:147], v[164:167], v[116:119]
	v_mfma_f32_16x16x32_bf16 v[112:115], v[152:155], v[164:167], v[112:115]
	v_mfma_f32_16x16x32_bf16 v[100:103], v[144:147], v[172:175], v[100:103]
	v_mfma_f32_16x16x32_bf16 v[96:99], v[152:155], v[172:175], v[96:99]
	v_mfma_f32_16x16x32_bf16 v[84:87], v[144:147], v[180:183], v[84:87]
	v_mfma_f32_16x16x32_bf16 v[80:83], v[152:155], v[180:183], v[80:83]
	v_mfma_f32_16x16x32_bf16 v[68:71], v[144:147], v[188:191], v[68:71]
	v_mfma_f32_16x16x32_bf16 v[64:67], v[152:155], v[188:191], v[64:67]
	v_mfma_f32_16x16x32_bf16 v[116:119], v[148:151], v[168:171], v[116:119]
	v_mfma_f32_16x16x32_bf16 v[112:115], v[160:163], v[168:171], v[112:115]
	v_mfma_f32_16x16x32_bf16 v[100:103], v[148:151], v[176:179], v[100:103]
	v_mfma_f32_16x16x32_bf16 v[96:99], v[160:163], v[176:179], v[96:99]
	v_mfma_f32_16x16x32_bf16 v[84:87], v[148:151], v[184:187], v[84:87]
	v_mfma_f32_16x16x32_bf16 v[80:83], v[160:163], v[184:187], v[80:83]
	v_mfma_f32_16x16x32_bf16 v[68:71], v[148:151], v[194:197], v[68:71]
	v_mfma_f32_16x16x32_bf16 v[64:67], v[160:163], v[194:197], v[64:67]
	s_setprio 0
	s_barrier
	ds_read_b128 v[164:167], v221 offset:49152
	ds_read_b128 v[168:171], v221 offset:50176
	ds_read_b128 v[172:175], v221 offset:51200
	ds_read_b128 v[176:179], v221 offset:52224
	ds_read_b128 v[180:183], v221 offset:53248
	ds_read_b128 v[184:187], v221 offset:54272
	ds_read_b128 v[188:191], v221 offset:55296
	ds_read_b128 v[194:197], v221 offset:56320
	s_add_u32 s10, s36, 0x80
	s_addc_u32 s11, s37, 0
	s_mov_b32 m0, s87
	s_nop 0
	global_load_lds_dwordx4 v209, s[10:11]
	s_nop 0
	s_mov_b32 m0, s83
	s_nop 0
	global_load_lds_dwordx4 v211, s[10:11]
	s_add_u32 s10, s36, 0x160080
	s_addc_u32 s11, s37, 0
	s_mov_b32 m0, s92
	s_nop 0
	global_load_lds_dwordx4 v209, s[10:11]
	s_nop 0
	s_mov_b32 m0, s93
	s_nop 0
	global_load_lds_dwordx4 v211, s[10:11]
	s_nop 0
	s_mov_b32 m0, s60
	s_nop 0
	global_load_lds_dwordx4 v208, s[34:35]
	s_nop 0
	s_mov_b32 m0, s89
	s_nop 0
	global_load_lds_dwordx4 v210, s[34:35]
	s_waitcnt vmcnt(8) lgkmcnt(0)
	s_setprio 1
	s_barrier
	v_mfma_f32_16x16x32_bf16 v[60:63], v[128:131], v[164:167], v[60:63]
	v_mfma_f32_16x16x32_bf16 v[56:59], v[136:139], v[164:167], v[56:59]
	v_mfma_f32_16x16x32_bf16 v[44:47], v[128:131], v[172:175], v[44:47]
	v_mfma_f32_16x16x32_bf16 v[40:43], v[136:139], v[172:175], v[40:43]
	v_mfma_f32_16x16x32_bf16 v[28:31], v[128:131], v[180:183], v[28:31]
	v_mfma_f32_16x16x32_bf16 v[24:27], v[136:139], v[180:183], v[24:27]
	v_mfma_f32_16x16x32_bf16 v[12:15], v[128:131], v[188:191], v[12:15]
	v_mfma_f32_16x16x32_bf16 v[8:11], v[136:139], v[188:191], v[8:11]
	v_mfma_f32_16x16x32_bf16 v[60:63], v[132:135], v[168:171], v[60:63]
	v_mfma_f32_16x16x32_bf16 v[56:59], v[140:143], v[168:171], v[56:59]
	v_mfma_f32_16x16x32_bf16 v[44:47], v[132:135], v[176:179], v[44:47]
	v_mfma_f32_16x16x32_bf16 v[40:43], v[140:143], v[176:179], v[40:43]
	v_mfma_f32_16x16x32_bf16 v[28:31], v[132:135], v[184:187], v[28:31]
	v_mfma_f32_16x16x32_bf16 v[24:27], v[140:143], v[184:187], v[24:27]
	v_mfma_f32_16x16x32_bf16 v[12:15], v[132:135], v[194:197], v[12:15]
	v_mfma_f32_16x16x32_bf16 v[8:11], v[140:143], v[194:197], v[8:11]
	v_mfma_f32_16x16x32_bf16 v[52:55], v[144:147], v[164:167], v[52:55]
	v_mfma_f32_16x16x32_bf16 v[48:51], v[152:155], v[164:167], v[48:51]
	v_mfma_f32_16x16x32_bf16 v[36:39], v[144:147], v[172:175], v[36:39]
	v_mfma_f32_16x16x32_bf16 v[32:35], v[152:155], v[172:175], v[32:35]
	v_mfma_f32_16x16x32_bf16 v[20:23], v[144:147], v[180:183], v[20:23]
	v_mfma_f32_16x16x32_bf16 v[16:19], v[152:155], v[180:183], v[16:19]
	v_mfma_f32_16x16x32_bf16 v[4:7], v[144:147], v[188:191], v[4:7]
	v_mfma_f32_16x16x32_bf16 v[0:3], v[152:155], v[188:191], v[0:3]
	v_mfma_f32_16x16x32_bf16 v[52:55], v[148:151], v[168:171], v[52:55]
	v_mfma_f32_16x16x32_bf16 v[48:51], v[160:163], v[168:171], v[48:51]
	v_mfma_f32_16x16x32_bf16 v[36:39], v[148:151], v[176:179], v[36:39]
	v_mfma_f32_16x16x32_bf16 v[32:35], v[160:163], v[176:179], v[32:35]
	v_mfma_f32_16x16x32_bf16 v[20:23], v[148:151], v[184:187], v[20:23]
	v_mfma_f32_16x16x32_bf16 v[16:19], v[160:163], v[184:187], v[16:19]
	v_mfma_f32_16x16x32_bf16 v[4:7], v[148:151], v[194:197], v[4:7]
	v_mfma_f32_16x16x32_bf16 v[0:3], v[160:163], v[194:197], v[0:3]
	s_setprio 0
	s_barrier
	s_add_u32 s85, s85, 0x100
	s_addc_u32 vcc_lo, vcc_lo, 0
	s_add_u32 s79, s79, 0x100
	s_addc_u32 s62, s62, 0
	s_add_u32 s30, s30, 0x100
	s_addc_u32 s31, s31, 0
	s_cmp_ge_i32 vcc_hi, s40
	s_mov_b32 s34, vcc_hi
	s_cbranch_scc0 .LBB0_1336
	s_mov_b32 s79, 0xc00000
	s_and_b64 vcc, exec, s[20:21]
	s_cbranch_vccz .LBB0_1339
